# v35 + indexer: m0 write moved one instruction up (the preceding VALU/MFMA is the wait state), 88 s_nop 0 dropped
# baseline (speedup 1.0000x reference)
.LBB0_532:
	v_mov_b32_e32 v129, v194
	v_readfirstlane_b32 s83, v194
	v_and_b32_e32 v180, 31, v194
	v_bfe_u32 v131, v194, 5, 1
	v_and_b32_e32 v243, 63, v194
	s_ashr_i32 s84, s83, 6
	s_lshl_b32 s0, s84, 5
	v_or_b32_e32 v130, s0, v180
	v_lshlrev_b32_e32 v243, 2, v243
	s_lshl_b32 s0, s2, 17
	s_lshl_b32 s1, s84, 8
	s_add_u32 s0, s0, s1
	s_add_u32 s8, s28, s0
	s_addc_u32 s9, s29, 0
	s_lshl_b32 s21, s84, 12
	s_cmp_lg_u32 s82, 0
	s_cbranch_scc1 .Lix_reload
	s_mov_b32 s100, 0
	v_bfe_u32 v0, v194, 2, 1
	v_lshrrev_b32_e32 v1, 1, v194
	v_and_b32_e32 v1, 12, v1
	v_and_b32_e32 v228, 3, v194
	v_or_b32_e32 v1, v1, v228
	v_add_u32_e32 v0, s34, v0
	v_lshlrev_b32_e32 v0, 11, v0
	v_lshl_add_u32 v0, v1, 7, v0
	v_lshl_add_u32 v0, v131, 4, v0
	v_add_u32_e32 v1, 0x1000, v0
	global_load_dwordx4 v[70:73], v0, s[36:37]
	global_load_dwordx4 v[74:77], v0, s[36:37] offset:32
	global_load_dwordx4 v[78:81], v0, s[36:37] offset:64
	global_load_dwordx4 v[82:85], v0, s[36:37] offset:96
	global_load_dwordx4 v[86:89], v1, s[36:37]
	global_load_dwordx4 v[90:93], v1, s[36:37] offset:32
	global_load_dwordx4 v[94:97], v1, s[36:37] offset:64
	global_load_dwordx4 v[98:101], v1, s[36:37] offset:96
	v_add_u32_e32 v228, s34, v131
	v_lshlrev_b32_e32 v228, 6, v228
	global_load_dwordx4 v[22:25], v228, s[38:39]
	global_load_dwordx4 v[26:29], v228, s[38:39] offset:16
	global_load_dwordx4 v[30:33], v228, s[38:39] offset:32
	global_load_dwordx4 v[34:37], v228, s[38:39] offset:48
	global_load_dwordx2 v[244:245], v228, s[38:39] offset:128
	global_load_dwordx2 v[246:247], v228, s[38:39] offset:136
	global_load_dwordx2 v[248:249], v228, s[38:39] offset:144
	global_load_dwordx2 v[250:251], v228, s[38:39] offset:152
	global_load_dwordx2 v[252:253], v228, s[38:39] offset:160
	global_load_dwordx2 v[254:255], v228, s[38:39] offset:168
	global_load_dwordx2 v[200:201], v228, s[38:39] offset:176
	global_load_dwordx2 v[202:203], v228, s[38:39] offset:184
	v_lshrrev_b32_e32 v0, 2, v243
	v_lshrrev_b32_e32 v1, 3, v0
	v_lshrrev_b32_e32 v228, 4, v0
	v_and_b32_e32 v229, 7, v0
	v_xor_b32_e32 v228, v229, v228
	v_xor_b32_e32 v229, 4, v228
	s_lshl_b32 s0, s84, 12
	v_lshl_add_u32 v1, v1, 7, s0
	v_lshl_add_u32 v102, v228, 4, v1
	v_lshl_add_u32 v110, v229, 4, v1
	v_add_u32_e32 v110, 0x400, v110
	v_add_u32_e32 v112, 0x800, v102
	v_add_u32_e32 v193, 0x800, v110
	v_lshlrev_b32_e32 v0, 7, v130
	v_bfe_u32 v1, v180, 1, 3
	v_or_b32_e32 v228, 0, v131
	v_xor_b32_e32 v228, v228, v1
	v_lshl_add_u32 v5, v228, 4, v0
	v_or_b32_e32 v228, 2, v131
	v_xor_b32_e32 v228, v228, v1
	v_lshl_add_u32 v52, v228, 4, v0
	v_or_b32_e32 v228, 4, v131
	v_xor_b32_e32 v228, v228, v1
	v_lshl_add_u32 v55, v228, 4, v0
	v_or_b32_e32 v228, 6, v131
	v_xor_b32_e32 v228, v228, v1
	v_lshl_add_u32 v56, v228, 4, v0
	s_mov_b32 s6, s14
	s_mov_b32 s7, s15
	s_add_i32 s10, s0, 10496
	s_sub_i32 s11, s35, s84
	s_add_i32 m0, s10, 0
	s_nop 0
	global_load_lds_dwordx4 v102, s[6:7]
	s_add_i32 m0, s10, 1024
	s_nop 0
	global_load_lds_dwordx4 v110, s[6:7]
	s_add_i32 m0, s10, 2048
	s_nop 0
	global_load_lds_dwordx4 v112, s[6:7]
	s_add_i32 m0, s10, 3072
	s_nop 0
	global_load_lds_dwordx4 v193, s[6:7]
	s_add_u32 s6, s6, 0x8000
	s_addc_u32 s7, s7, 0
	s_add_i32 m0, s10, 32768
	s_nop 0
	global_load_lds_dwordx4 v102, s[6:7]
	s_add_i32 m0, s10, 33792
	s_nop 0
	global_load_lds_dwordx4 v110, s[6:7]
	s_add_i32 m0, s10, 34816
	s_nop 0
	global_load_lds_dwordx4 v112, s[6:7]
	s_add_i32 m0, s10, 35840
	s_nop 0
	global_load_lds_dwordx4 v193, s[6:7]
	s_add_u32 s6, s6, 0x8000
	s_addc_u32 s7, s7, 0
	s_add_i32 m0, s10, 65536
	s_nop 0
	global_load_lds_dwordx4 v102, s[6:7]
	s_add_i32 m0, s10, 66560
	s_nop 0
	global_load_lds_dwordx4 v110, s[6:7]
	s_add_i32 m0, s10, 67584
	s_nop 0
	global_load_lds_dwordx4 v112, s[6:7]
	s_add_i32 m0, s10, 68608
	s_nop 0
	global_load_lds_dwordx4 v193, s[6:7]
	s_add_u32 s6, s6, 0x8000
	s_addc_u32 s7, s7, 0
	s_waitcnt vmcnt(8)
	ds_read_b128 v[38:41], v5 offset:10496
	ds_read_b128 v[42:45], v52 offset:10496
	ds_read_b128 v[46:49], v55 offset:10496
	ds_read_b128 v[196:199], v56 offset:10496
	s_waitcnt lgkmcnt(3)
	s_add_i32 m0, s10, 98304
	v_mfma_f32_32x32x16_bf16 v[212:227], v[70:73], v[38:41], 0
	global_load_lds_dwordx4 v102, s[6:7]
	s_waitcnt lgkmcnt(2)
	s_add_i32 m0, s10, 99328
	v_mfma_f32_32x32x16_bf16 v[212:227], v[74:77], v[42:45], v[212:227]
	global_load_lds_dwordx4 v110, s[6:7]
	s_waitcnt lgkmcnt(1)
	s_add_i32 m0, s10, 100352
	v_mfma_f32_32x32x16_bf16 v[212:227], v[78:81], v[46:49], v[212:227]
	global_load_lds_dwordx4 v112, s[6:7]
	s_waitcnt lgkmcnt(0)
	s_add_i32 m0, s10, 101376
	v_mfma_f32_32x32x16_bf16 v[212:227], v[82:85], v[196:199], v[212:227]
	global_load_lds_dwordx4 v193, s[6:7]
	s_add_u32 s6, s6, 0x8000
	s_addc_u32 s7, s7, 0
	v_mfma_f32_32x32x16_bf16 v[6:21], v[86:89], v[38:41], 0
	s_nop 7
	s_nop 2
	v_max_f32_e32 v108, 0, v212
	v_max_f32_e32 v109, 0, v213
	v_mul_f32_e32 v0, v22, v108
	v_mul_f32_e32 v1, v23, v109
	v_max_f32_e32 v210, 0, v214
	v_max_f32_e32 v211, 0, v215
	v_fmac_f32_e32 v0, v24, v210
	v_fmac_f32_e32 v1, v25, v211
	v_max_f32_e32 v108, 0, v216
	v_max_f32_e32 v109, 0, v217
	v_fmac_f32_e32 v0, v26, v108
	v_fmac_f32_e32 v1, v27, v109
	v_mfma_f32_32x32x16_bf16 v[6:21], v[90:93], v[42:45], v[6:21]
	v_max_f32_e32 v210, 0, v218
	v_max_f32_e32 v211, 0, v219
	v_fmac_f32_e32 v0, v28, v210
	v_fmac_f32_e32 v1, v29, v211
	v_max_f32_e32 v108, 0, v220
	v_max_f32_e32 v109, 0, v221
	v_fmac_f32_e32 v0, v30, v108
	v_fmac_f32_e32 v1, v31, v109
	v_max_f32_e32 v210, 0, v222
	v_max_f32_e32 v211, 0, v223
	v_fmac_f32_e32 v0, v32, v210
	v_fmac_f32_e32 v1, v33, v211
	v_mfma_f32_32x32x16_bf16 v[6:21], v[94:97], v[46:49], v[6:21]
	v_max_f32_e32 v108, 0, v224
	v_max_f32_e32 v109, 0, v225
	v_fmac_f32_e32 v0, v34, v108
	v_fmac_f32_e32 v1, v35, v109
	v_max_f32_e32 v210, 0, v226
	v_max_f32_e32 v211, 0, v227
	v_fmac_f32_e32 v0, v36, v210
	v_fmac_f32_e32 v1, v37, v211
	v_add_f32_e32 v0, v0, v1
	v_ashrrev_i32_e32 v1, 31, v0
	v_mfma_f32_32x32x16_bf16 v[6:21], v[98:101], v[196:199], v[6:21]
	s_waitcnt vmcnt(8)
	ds_read_b128 v[38:41], v5 offset:43264
	ds_read_b128 v[42:45], v52 offset:43264
	ds_read_b128 v[46:49], v55 offset:43264
	ds_read_b128 v[196:199], v56 offset:43264
	v_or_b32_e32 v1, 0x80000000, v1
	s_cmpk_gt_i32 s11, 0
	s_cselect_b64 vcc, -1, 0
	v_xor_b32_e32 v0, v1, v0
	v_cndmask_b32_e32 v133, v123, v0, vcc
	s_nop 3
	s_waitcnt lgkmcnt(3)
	v_mfma_f32_32x32x16_bf16 v[212:227], v[70:73], v[38:41], 0
	v_max_f32_e32 v108, 0, v6
	v_max_f32_e32 v109, 0, v7
	v_mul_f32_e32 v50, v244, v108
	v_mul_f32_e32 v51, v245, v109
	v_max_f32_e32 v210, 0, v8
	v_max_f32_e32 v211, 0, v9
	v_fmac_f32_e32 v50, v246, v210
	v_fmac_f32_e32 v51, v247, v211
	v_max_f32_e32 v108, 0, v10
	v_max_f32_e32 v109, 0, v11
	v_fmac_f32_e32 v50, v248, v108
	v_fmac_f32_e32 v51, v249, v109
	s_waitcnt lgkmcnt(2)
	v_mfma_f32_32x32x16_bf16 v[212:227], v[74:77], v[42:45], v[212:227]
	v_max_f32_e32 v210, 0, v12
	v_max_f32_e32 v211, 0, v13
	v_fmac_f32_e32 v50, v250, v210
	v_fmac_f32_e32 v51, v251, v211
	v_max_f32_e32 v108, 0, v14
	v_max_f32_e32 v109, 0, v15
	v_fmac_f32_e32 v50, v252, v108
	v_fmac_f32_e32 v51, v253, v109
	v_max_f32_e32 v210, 0, v16
	v_max_f32_e32 v211, 0, v17
	v_fmac_f32_e32 v50, v254, v210
	v_fmac_f32_e32 v51, v255, v211
	s_waitcnt lgkmcnt(1)
	v_mfma_f32_32x32x16_bf16 v[212:227], v[78:81], v[46:49], v[212:227]
	v_max_f32_e32 v108, 0, v18
	v_max_f32_e32 v109, 0, v19
	v_fmac_f32_e32 v50, v200, v108
	v_fmac_f32_e32 v51, v201, v109
	v_max_f32_e32 v210, 0, v20
	v_max_f32_e32 v211, 0, v21
	v_fmac_f32_e32 v50, v202, v210
	v_fmac_f32_e32 v51, v203, v211
	v_add_f32_e32 v50, v50, v51
	v_ashrrev_i32_e32 v51, 31, v50
	s_waitcnt lgkmcnt(0)
	v_mfma_f32_32x32x16_bf16 v[212:227], v[82:85], v[196:199], v[212:227]
	v_or_b32_e32 v51, 0x80000000, v51
	s_cmpk_gt_i32 s11, 0
	s_cselect_b64 vcc, -1, 0
	v_xor_b32_e32 v50, v51, v50
	v_cndmask_b32_e32 v50, v123, v50, vcc
	global_store_dword v243, v50, s[8:9]
	s_add_i32 m0, s10, 0
	v_mfma_f32_32x32x16_bf16 v[6:21], v[86:89], v[38:41], 0
	global_load_lds_dwordx4 v102, s[6:7]
	s_add_i32 m0, s10, 1024
	s_nop 0
	global_load_lds_dwordx4 v110, s[6:7]
	s_add_i32 m0, s10, 2048
	s_nop 0
	global_load_lds_dwordx4 v112, s[6:7]
	s_add_i32 m0, s10, 3072
	s_nop 0
	global_load_lds_dwordx4 v193, s[6:7]
	s_add_u32 s6, s6, 0x8000
	s_addc_u32 s7, s7, 0
	v_max_f32_e32 v108, 0, v212
	v_max_f32_e32 v109, 0, v213
	v_mul_f32_e32 v0, v22, v108
	v_mul_f32_e32 v1, v23, v109
	v_max_f32_e32 v210, 0, v214
	v_max_f32_e32 v211, 0, v215
	v_fmac_f32_e32 v0, v24, v210
	v_fmac_f32_e32 v1, v25, v211
	v_max_f32_e32 v108, 0, v216
	v_max_f32_e32 v109, 0, v217
	v_fmac_f32_e32 v0, v26, v108
	v_fmac_f32_e32 v1, v27, v109
	v_mfma_f32_32x32x16_bf16 v[6:21], v[90:93], v[42:45], v[6:21]
	v_max_f32_e32 v210, 0, v218
	v_max_f32_e32 v211, 0, v219
	v_fmac_f32_e32 v0, v28, v210
	v_fmac_f32_e32 v1, v29, v211
	v_max_f32_e32 v108, 0, v220
	v_max_f32_e32 v109, 0, v221
	v_fmac_f32_e32 v0, v30, v108
	v_fmac_f32_e32 v1, v31, v109
	v_max_f32_e32 v210, 0, v222
	v_max_f32_e32 v211, 0, v223
	v_fmac_f32_e32 v0, v32, v210
	v_fmac_f32_e32 v1, v33, v211
	v_mfma_f32_32x32x16_bf16 v[6:21], v[94:97], v[46:49], v[6:21]
	v_max_f32_e32 v108, 0, v224
	v_max_f32_e32 v109, 0, v225
	v_fmac_f32_e32 v0, v34, v108
	v_fmac_f32_e32 v1, v35, v109
	v_max_f32_e32 v210, 0, v226
	v_max_f32_e32 v211, 0, v227
	v_fmac_f32_e32 v0, v36, v210
	v_fmac_f32_e32 v1, v37, v211
	v_add_f32_e32 v0, v0, v1
	v_ashrrev_i32_e32 v1, 31, v0
	v_mfma_f32_32x32x16_bf16 v[6:21], v[98:101], v[196:199], v[6:21]
	s_waitcnt vmcnt(9)
	v_add_u32_e32 v228, 0x10000, v5
	ds_read_b128 v[38:41], v228 offset:10496
	v_add_u32_e32 v228, 0x10000, v52
	ds_read_b128 v[42:45], v228 offset:10496
	v_add_u32_e32 v228, 0x10000, v55
	ds_read_b128 v[46:49], v228 offset:10496
	v_add_u32_e32 v228, 0x10000, v56
	ds_read_b128 v[196:199], v228 offset:10496
	v_or_b32_e32 v1, 0x80000000, v1
	s_cmpk_gt_i32 s11, 8
	s_cselect_b64 vcc, -1, 0
	v_xor_b32_e32 v0, v1, v0
	v_cndmask_b32_e32 v132, v123, v0, vcc
	s_nop 3
	s_waitcnt lgkmcnt(3)
	v_mfma_f32_32x32x16_bf16 v[212:227], v[70:73], v[38:41], 0
	v_max_f32_e32 v108, 0, v6
	v_max_f32_e32 v109, 0, v7
	v_mul_f32_e32 v50, v244, v108
	v_mul_f32_e32 v51, v245, v109
	v_max_f32_e32 v210, 0, v8
	v_max_f32_e32 v211, 0, v9
	v_fmac_f32_e32 v50, v246, v210
	v_fmac_f32_e32 v51, v247, v211
	v_max_f32_e32 v108, 0, v10
	v_max_f32_e32 v109, 0, v11
	v_fmac_f32_e32 v50, v248, v108
	v_fmac_f32_e32 v51, v249, v109
	s_waitcnt lgkmcnt(2)
	v_mfma_f32_32x32x16_bf16 v[212:227], v[74:77], v[42:45], v[212:227]
	v_max_f32_e32 v210, 0, v12
	v_max_f32_e32 v211, 0, v13
	v_fmac_f32_e32 v50, v250, v210
	v_fmac_f32_e32 v51, v251, v211
	v_max_f32_e32 v108, 0, v14
	v_max_f32_e32 v109, 0, v15
	v_fmac_f32_e32 v50, v252, v108
	v_fmac_f32_e32 v51, v253, v109
	v_max_f32_e32 v210, 0, v16
	v_max_f32_e32 v211, 0, v17
	v_fmac_f32_e32 v50, v254, v210
	v_fmac_f32_e32 v51, v255, v211
	s_waitcnt lgkmcnt(1)
	v_mfma_f32_32x32x16_bf16 v[212:227], v[78:81], v[46:49], v[212:227]
	v_max_f32_e32 v108, 0, v18
	v_max_f32_e32 v109, 0, v19
	v_fmac_f32_e32 v50, v200, v108
	v_fmac_f32_e32 v51, v201, v109
	v_max_f32_e32 v210, 0, v20
	v_max_f32_e32 v211, 0, v21
	v_fmac_f32_e32 v50, v202, v210
	v_fmac_f32_e32 v51, v203, v211
	v_add_f32_e32 v50, v50, v51
	v_ashrrev_i32_e32 v51, 31, v50
	s_waitcnt lgkmcnt(0)
	v_mfma_f32_32x32x16_bf16 v[212:227], v[82:85], v[196:199], v[212:227]
	v_or_b32_e32 v51, 0x80000000, v51
	s_cmpk_gt_i32 s11, 8
	s_cselect_b64 vcc, -1, 0
	v_xor_b32_e32 v50, v51, v50
	v_cndmask_b32_e32 v50, v123, v50, vcc
	global_store_dword v243, v50, s[8:9] offset:2048
	s_add_u32 s8, s8, 0x1000
	s_addc_u32 s9, s9, 0
	s_add_i32 m0, s10, 32768
	v_mfma_f32_32x32x16_bf16 v[6:21], v[86:89], v[38:41], 0
	global_load_lds_dwordx4 v102, s[6:7]
	s_add_i32 m0, s10, 33792
	s_nop 0
	global_load_lds_dwordx4 v110, s[6:7]
	s_add_i32 m0, s10, 34816
	s_nop 0
	global_load_lds_dwordx4 v112, s[6:7]
	s_add_i32 m0, s10, 35840
	s_nop 0
	global_load_lds_dwordx4 v193, s[6:7]
	s_add_u32 s6, s6, 0x8000
	s_addc_u32 s7, s7, 0
	v_max_f32_e32 v108, 0, v212
	v_max_f32_e32 v109, 0, v213
	v_mul_f32_e32 v0, v22, v108
	v_mul_f32_e32 v1, v23, v109
	v_max_f32_e32 v210, 0, v214
	v_max_f32_e32 v211, 0, v215
	v_fmac_f32_e32 v0, v24, v210
	v_fmac_f32_e32 v1, v25, v211
	v_max_f32_e32 v108, 0, v216
	v_max_f32_e32 v109, 0, v217
	v_fmac_f32_e32 v0, v26, v108
	v_fmac_f32_e32 v1, v27, v109
	v_mfma_f32_32x32x16_bf16 v[6:21], v[90:93], v[42:45], v[6:21]
	v_max_f32_e32 v210, 0, v218
	v_max_f32_e32 v211, 0, v219
	v_fmac_f32_e32 v0, v28, v210
	v_fmac_f32_e32 v1, v29, v211
	v_max_f32_e32 v108, 0, v220
	v_max_f32_e32 v109, 0, v221
	v_fmac_f32_e32 v0, v30, v108
	v_fmac_f32_e32 v1, v31, v109
	v_max_f32_e32 v210, 0, v222
	v_max_f32_e32 v211, 0, v223
	v_fmac_f32_e32 v0, v32, v210
	v_fmac_f32_e32 v1, v33, v211
	v_mfma_f32_32x32x16_bf16 v[6:21], v[94:97], v[46:49], v[6:21]
	v_max_f32_e32 v108, 0, v224
	v_max_f32_e32 v109, 0, v225
	v_fmac_f32_e32 v0, v34, v108
	v_fmac_f32_e32 v1, v35, v109
	v_max_f32_e32 v210, 0, v226
	v_max_f32_e32 v211, 0, v227
	v_fmac_f32_e32 v0, v36, v210
	v_fmac_f32_e32 v1, v37, v211
	v_add_f32_e32 v0, v0, v1
	v_ashrrev_i32_e32 v1, 31, v0
	v_mfma_f32_32x32x16_bf16 v[6:21], v[98:101], v[196:199], v[6:21]
	s_waitcnt vmcnt(10)
	v_add_u32_e32 v228, 0x10000, v5
	ds_read_b128 v[38:41], v228 offset:43264
	v_add_u32_e32 v228, 0x10000, v52
	ds_read_b128 v[42:45], v228 offset:43264
	v_add_u32_e32 v228, 0x10000, v55
	ds_read_b128 v[46:49], v228 offset:43264
	v_add_u32_e32 v228, 0x10000, v56
	ds_read_b128 v[196:199], v228 offset:43264
	v_or_b32_e32 v1, 0x80000000, v1
	s_cmpk_gt_i32 s11, 16
	s_cselect_b64 vcc, -1, 0
	v_xor_b32_e32 v0, v1, v0
	v_cndmask_b32_e32 v135, v123, v0, vcc
	s_nop 3
	s_waitcnt lgkmcnt(3)
	v_mfma_f32_32x32x16_bf16 v[212:227], v[70:73], v[38:41], 0
	v_max_f32_e32 v108, 0, v6
	v_max_f32_e32 v109, 0, v7
	v_mul_f32_e32 v50, v244, v108
	v_mul_f32_e32 v51, v245, v109
	v_max_f32_e32 v210, 0, v8
	v_max_f32_e32 v211, 0, v9
	v_fmac_f32_e32 v50, v246, v210
	v_fmac_f32_e32 v51, v247, v211
	v_max_f32_e32 v108, 0, v10
	v_max_f32_e32 v109, 0, v11
	v_fmac_f32_e32 v50, v248, v108
	v_fmac_f32_e32 v51, v249, v109
	s_waitcnt lgkmcnt(2)
	v_mfma_f32_32x32x16_bf16 v[212:227], v[74:77], v[42:45], v[212:227]
	v_max_f32_e32 v210, 0, v12
	v_max_f32_e32 v211, 0, v13
	v_fmac_f32_e32 v50, v250, v210
	v_fmac_f32_e32 v51, v251, v211
	v_max_f32_e32 v108, 0, v14
	v_max_f32_e32 v109, 0, v15
	v_fmac_f32_e32 v50, v252, v108
	v_fmac_f32_e32 v51, v253, v109
	v_max_f32_e32 v210, 0, v16
	v_max_f32_e32 v211, 0, v17
	v_fmac_f32_e32 v50, v254, v210
	v_fmac_f32_e32 v51, v255, v211
	s_waitcnt lgkmcnt(1)
	v_mfma_f32_32x32x16_bf16 v[212:227], v[78:81], v[46:49], v[212:227]
	v_max_f32_e32 v108, 0, v18
	v_max_f32_e32 v109, 0, v19
	v_fmac_f32_e32 v50, v200, v108
	v_fmac_f32_e32 v51, v201, v109
	v_max_f32_e32 v210, 0, v20
	v_max_f32_e32 v211, 0, v21
	v_fmac_f32_e32 v50, v202, v210
	v_fmac_f32_e32 v51, v203, v211
	v_add_f32_e32 v50, v50, v51
	v_ashrrev_i32_e32 v51, 31, v50
	s_waitcnt lgkmcnt(0)
	v_mfma_f32_32x32x16_bf16 v[212:227], v[82:85], v[196:199], v[212:227]
	v_or_b32_e32 v51, 0x80000000, v51
	s_cmpk_gt_i32 s11, 16
	s_cselect_b64 vcc, -1, 0
	v_xor_b32_e32 v50, v51, v50
	v_cndmask_b32_e32 v50, v123, v50, vcc
	global_store_dword v243, v50, s[8:9]
	s_add_i32 m0, s10, 65536
	v_mfma_f32_32x32x16_bf16 v[6:21], v[86:89], v[38:41], 0
	global_load_lds_dwordx4 v102, s[6:7]
	s_add_i32 m0, s10, 66560
	s_nop 0
	global_load_lds_dwordx4 v110, s[6:7]
	s_add_i32 m0, s10, 67584
	s_nop 0
	global_load_lds_dwordx4 v112, s[6:7]
	s_add_i32 m0, s10, 68608
	s_nop 0
	global_load_lds_dwordx4 v193, s[6:7]
	s_add_u32 s6, s6, 0x8000
	s_addc_u32 s7, s7, 0
	v_max_f32_e32 v108, 0, v212
	v_max_f32_e32 v109, 0, v213
	v_mul_f32_e32 v0, v22, v108
	v_mul_f32_e32 v1, v23, v109
	v_max_f32_e32 v210, 0, v214
	v_max_f32_e32 v211, 0, v215
	v_fmac_f32_e32 v0, v24, v210
	v_fmac_f32_e32 v1, v25, v211
	v_max_f32_e32 v108, 0, v216
	v_max_f32_e32 v109, 0, v217
	v_fmac_f32_e32 v0, v26, v108
	v_fmac_f32_e32 v1, v27, v109
	v_mfma_f32_32x32x16_bf16 v[6:21], v[90:93], v[42:45], v[6:21]
	v_max_f32_e32 v210, 0, v218
	v_max_f32_e32 v211, 0, v219
	v_fmac_f32_e32 v0, v28, v210
	v_fmac_f32_e32 v1, v29, v211
	v_max_f32_e32 v108, 0, v220
	v_max_f32_e32 v109, 0, v221
	v_fmac_f32_e32 v0, v30, v108
	v_fmac_f32_e32 v1, v31, v109
	v_max_f32_e32 v210, 0, v222
	v_max_f32_e32 v211, 0, v223
	v_fmac_f32_e32 v0, v32, v210
	v_fmac_f32_e32 v1, v33, v211
	v_mfma_f32_32x32x16_bf16 v[6:21], v[94:97], v[46:49], v[6:21]
	v_max_f32_e32 v108, 0, v224
	v_max_f32_e32 v109, 0, v225
	v_fmac_f32_e32 v0, v34, v108
	v_fmac_f32_e32 v1, v35, v109
	v_max_f32_e32 v210, 0, v226
	v_max_f32_e32 v211, 0, v227
	v_fmac_f32_e32 v0, v36, v210
	v_fmac_f32_e32 v1, v37, v211
	v_add_f32_e32 v0, v0, v1
	v_ashrrev_i32_e32 v1, 31, v0
	v_mfma_f32_32x32x16_bf16 v[6:21], v[98:101], v[196:199], v[6:21]
	s_waitcnt vmcnt(10)
	ds_read_b128 v[38:41], v5 offset:10496
	ds_read_b128 v[42:45], v52 offset:10496
	ds_read_b128 v[46:49], v55 offset:10496
	ds_read_b128 v[196:199], v56 offset:10496
	v_or_b32_e32 v1, 0x80000000, v1
	s_cmpk_gt_i32 s11, 24
	s_cselect_b64 vcc, -1, 0
	v_xor_b32_e32 v0, v1, v0
	v_cndmask_b32_e32 v134, v123, v0, vcc
	s_nop 3
	s_waitcnt lgkmcnt(3)
	v_mfma_f32_32x32x16_bf16 v[212:227], v[70:73], v[38:41], 0
	v_max_f32_e32 v108, 0, v6
	v_max_f32_e32 v109, 0, v7
	v_mul_f32_e32 v50, v244, v108
	v_mul_f32_e32 v51, v245, v109
	v_max_f32_e32 v210, 0, v8
	v_max_f32_e32 v211, 0, v9
	v_fmac_f32_e32 v50, v246, v210
	v_fmac_f32_e32 v51, v247, v211
	v_max_f32_e32 v108, 0, v10
	v_max_f32_e32 v109, 0, v11
	v_fmac_f32_e32 v50, v248, v108
	v_fmac_f32_e32 v51, v249, v109
	s_waitcnt lgkmcnt(2)
	v_mfma_f32_32x32x16_bf16 v[212:227], v[74:77], v[42:45], v[212:227]
	v_max_f32_e32 v210, 0, v12
	v_max_f32_e32 v211, 0, v13
	v_fmac_f32_e32 v50, v250, v210
	v_fmac_f32_e32 v51, v251, v211
	v_max_f32_e32 v108, 0, v14
	v_max_f32_e32 v109, 0, v15
	v_fmac_f32_e32 v50, v252, v108
	v_fmac_f32_e32 v51, v253, v109
	v_max_f32_e32 v210, 0, v16
	v_max_f32_e32 v211, 0, v17
	v_fmac_f32_e32 v50, v254, v210
	v_fmac_f32_e32 v51, v255, v211
	s_waitcnt lgkmcnt(1)
	v_mfma_f32_32x32x16_bf16 v[212:227], v[78:81], v[46:49], v[212:227]
	v_max_f32_e32 v108, 0, v18
	v_max_f32_e32 v109, 0, v19
	v_fmac_f32_e32 v50, v200, v108
	v_fmac_f32_e32 v51, v201, v109
	v_max_f32_e32 v210, 0, v20
	v_max_f32_e32 v211, 0, v21
	v_fmac_f32_e32 v50, v202, v210
	v_fmac_f32_e32 v51, v203, v211
	v_add_f32_e32 v50, v50, v51
	v_ashrrev_i32_e32 v51, 31, v50
	s_waitcnt lgkmcnt(0)
	v_mfma_f32_32x32x16_bf16 v[212:227], v[82:85], v[196:199], v[212:227]
	v_or_b32_e32 v51, 0x80000000, v51
	s_cmpk_gt_i32 s11, 24
	s_cselect_b64 vcc, -1, 0
	v_xor_b32_e32 v50, v51, v50
	v_cndmask_b32_e32 v50, v123, v50, vcc
	global_store_dword v243, v50, s[8:9] offset:2048
	s_add_u32 s8, s8, 0x1000
	s_addc_u32 s9, s9, 0
	s_add_i32 m0, s10, 98304
	v_mfma_f32_32x32x16_bf16 v[6:21], v[86:89], v[38:41], 0
	global_load_lds_dwordx4 v102, s[6:7]
	s_add_i32 m0, s10, 99328
	s_nop 0
	global_load_lds_dwordx4 v110, s[6:7]
	s_add_i32 m0, s10, 100352
	s_nop 0
	global_load_lds_dwordx4 v112, s[6:7]
	s_add_i32 m0, s10, 101376
	s_nop 0
	global_load_lds_dwordx4 v193, s[6:7]
	s_add_u32 s6, s6, 0x8000
	s_addc_u32 s7, s7, 0
	v_max_f32_e32 v108, 0, v212
	v_max_f32_e32 v109, 0, v213
	v_mul_f32_e32 v0, v22, v108
	v_mul_f32_e32 v1, v23, v109
	v_max_f32_e32 v210, 0, v214
	v_max_f32_e32 v211, 0, v215
	v_fmac_f32_e32 v0, v24, v210
	v_fmac_f32_e32 v1, v25, v211
	v_max_f32_e32 v108, 0, v216
	v_max_f32_e32 v109, 0, v217
	v_fmac_f32_e32 v0, v26, v108
	v_fmac_f32_e32 v1, v27, v109
	v_mfma_f32_32x32x16_bf16 v[6:21], v[90:93], v[42:45], v[6:21]
	v_max_f32_e32 v210, 0, v218
	v_max_f32_e32 v211, 0, v219
	v_fmac_f32_e32 v0, v28, v210
	v_fmac_f32_e32 v1, v29, v211
	v_max_f32_e32 v108, 0, v220
	v_max_f32_e32 v109, 0, v221
	v_fmac_f32_e32 v0, v30, v108
	v_fmac_f32_e32 v1, v31, v109
	v_max_f32_e32 v210, 0, v222
	v_max_f32_e32 v211, 0, v223
	v_fmac_f32_e32 v0, v32, v210
	v_fmac_f32_e32 v1, v33, v211
	v_mfma_f32_32x32x16_bf16 v[6:21], v[94:97], v[46:49], v[6:21]
	v_max_f32_e32 v108, 0, v224
	v_max_f32_e32 v109, 0, v225
	v_fmac_f32_e32 v0, v34, v108
	v_fmac_f32_e32 v1, v35, v109
	v_max_f32_e32 v210, 0, v226
	v_max_f32_e32 v211, 0, v227
	v_fmac_f32_e32 v0, v36, v210
	v_fmac_f32_e32 v1, v37, v211
	v_add_f32_e32 v0, v0, v1
	v_ashrrev_i32_e32 v1, 31, v0
	v_mfma_f32_32x32x16_bf16 v[6:21], v[98:101], v[196:199], v[6:21]
	s_waitcnt vmcnt(10)
	ds_read_b128 v[38:41], v5 offset:43264
	ds_read_b128 v[42:45], v52 offset:43264
	ds_read_b128 v[46:49], v55 offset:43264
	ds_read_b128 v[196:199], v56 offset:43264
	v_or_b32_e32 v1, 0x80000000, v1
	s_cmpk_gt_i32 s11, 32
	s_cselect_b64 vcc, -1, 0
	v_xor_b32_e32 v0, v1, v0
	v_cndmask_b32_e32 v138, v123, v0, vcc
	s_nop 3
	s_waitcnt lgkmcnt(3)
	v_mfma_f32_32x32x16_bf16 v[212:227], v[70:73], v[38:41], 0
	v_max_f32_e32 v108, 0, v6
	v_max_f32_e32 v109, 0, v7
	v_mul_f32_e32 v50, v244, v108
	v_mul_f32_e32 v51, v245, v109
	v_max_f32_e32 v210, 0, v8
	v_max_f32_e32 v211, 0, v9
	v_fmac_f32_e32 v50, v246, v210
	v_fmac_f32_e32 v51, v247, v211
	v_max_f32_e32 v108, 0, v10
	v_max_f32_e32 v109, 0, v11
	v_fmac_f32_e32 v50, v248, v108
	v_fmac_f32_e32 v51, v249, v109
	s_waitcnt lgkmcnt(2)
	v_mfma_f32_32x32x16_bf16 v[212:227], v[74:77], v[42:45], v[212:227]
	v_max_f32_e32 v210, 0, v12
	v_max_f32_e32 v211, 0, v13
	v_fmac_f32_e32 v50, v250, v210
	v_fmac_f32_e32 v51, v251, v211
	v_max_f32_e32 v108, 0, v14
	v_max_f32_e32 v109, 0, v15
	v_fmac_f32_e32 v50, v252, v108
	v_fmac_f32_e32 v51, v253, v109
	v_max_f32_e32 v210, 0, v16
	v_max_f32_e32 v211, 0, v17
	v_fmac_f32_e32 v50, v254, v210
	v_fmac_f32_e32 v51, v255, v211
	s_waitcnt lgkmcnt(1)
	v_mfma_f32_32x32x16_bf16 v[212:227], v[78:81], v[46:49], v[212:227]
	v_max_f32_e32 v108, 0, v18
	v_max_f32_e32 v109, 0, v19
	v_fmac_f32_e32 v50, v200, v108
	v_fmac_f32_e32 v51, v201, v109
	v_max_f32_e32 v210, 0, v20
	v_max_f32_e32 v211, 0, v21
	v_fmac_f32_e32 v50, v202, v210
	v_fmac_f32_e32 v51, v203, v211
	v_add_f32_e32 v50, v50, v51
	v_ashrrev_i32_e32 v51, 31, v50
	s_waitcnt lgkmcnt(0)
	v_mfma_f32_32x32x16_bf16 v[212:227], v[82:85], v[196:199], v[212:227]
	v_or_b32_e32 v51, 0x80000000, v51
	s_cmpk_gt_i32 s11, 32
	s_cselect_b64 vcc, -1, 0
	v_xor_b32_e32 v50, v51, v50
	v_cndmask_b32_e32 v50, v123, v50, vcc
	global_store_dword v243, v50, s[8:9]
	s_add_i32 m0, s10, 0
	v_mfma_f32_32x32x16_bf16 v[6:21], v[86:89], v[38:41], 0
	global_load_lds_dwordx4 v102, s[6:7]
	s_add_i32 m0, s10, 1024
	s_nop 0
	global_load_lds_dwordx4 v110, s[6:7]
	s_add_i32 m0, s10, 2048
	s_nop 0
	global_load_lds_dwordx4 v112, s[6:7]
	s_add_i32 m0, s10, 3072
	s_nop 0
	global_load_lds_dwordx4 v193, s[6:7]
	s_add_u32 s6, s6, 0x8000
	s_addc_u32 s7, s7, 0
	v_max_f32_e32 v108, 0, v212
	v_max_f32_e32 v109, 0, v213
	v_mul_f32_e32 v0, v22, v108
	v_mul_f32_e32 v1, v23, v109
	v_max_f32_e32 v210, 0, v214
	v_max_f32_e32 v211, 0, v215
	v_fmac_f32_e32 v0, v24, v210
	v_fmac_f32_e32 v1, v25, v211
	v_max_f32_e32 v108, 0, v216
	v_max_f32_e32 v109, 0, v217
	v_fmac_f32_e32 v0, v26, v108
	v_fmac_f32_e32 v1, v27, v109
	v_mfma_f32_32x32x16_bf16 v[6:21], v[90:93], v[42:45], v[6:21]
	v_max_f32_e32 v210, 0, v218
	v_max_f32_e32 v211, 0, v219
	v_fmac_f32_e32 v0, v28, v210
	v_fmac_f32_e32 v1, v29, v211
	v_max_f32_e32 v108, 0, v220
	v_max_f32_e32 v109, 0, v221
	v_fmac_f32_e32 v0, v30, v108
	v_fmac_f32_e32 v1, v31, v109
	v_max_f32_e32 v210, 0, v222
	v_max_f32_e32 v211, 0, v223
	v_fmac_f32_e32 v0, v32, v210
	v_fmac_f32_e32 v1, v33, v211
	v_mfma_f32_32x32x16_bf16 v[6:21], v[94:97], v[46:49], v[6:21]
	v_max_f32_e32 v108, 0, v224
	v_max_f32_e32 v109, 0, v225
	v_fmac_f32_e32 v0, v34, v108
	v_fmac_f32_e32 v1, v35, v109
	v_max_f32_e32 v210, 0, v226
	v_max_f32_e32 v211, 0, v227
	v_fmac_f32_e32 v0, v36, v210
	v_fmac_f32_e32 v1, v37, v211
	v_add_f32_e32 v0, v0, v1
	v_ashrrev_i32_e32 v1, 31, v0
	v_mfma_f32_32x32x16_bf16 v[6:21], v[98:101], v[196:199], v[6:21]
	s_waitcnt vmcnt(10)
	v_add_u32_e32 v228, 0x10000, v5
	ds_read_b128 v[38:41], v228 offset:10496
	v_add_u32_e32 v228, 0x10000, v52
	ds_read_b128 v[42:45], v228 offset:10496
	v_add_u32_e32 v228, 0x10000, v55
	ds_read_b128 v[46:49], v228 offset:10496
	v_add_u32_e32 v228, 0x10000, v56
	ds_read_b128 v[196:199], v228 offset:10496
	v_or_b32_e32 v1, 0x80000000, v1
	s_cmpk_gt_i32 s11, 40
	s_cselect_b64 vcc, -1, 0
	v_xor_b32_e32 v0, v1, v0
	v_cndmask_b32_e32 v137, v123, v0, vcc
	s_nop 3
	s_waitcnt lgkmcnt(3)
	v_mfma_f32_32x32x16_bf16 v[212:227], v[70:73], v[38:41], 0
	v_max_f32_e32 v108, 0, v6
	v_max_f32_e32 v109, 0, v7
	v_mul_f32_e32 v50, v244, v108
	v_mul_f32_e32 v51, v245, v109
	v_max_f32_e32 v210, 0, v8
	v_max_f32_e32 v211, 0, v9
	v_fmac_f32_e32 v50, v246, v210
	v_fmac_f32_e32 v51, v247, v211
	v_max_f32_e32 v108, 0, v10
	v_max_f32_e32 v109, 0, v11
	v_fmac_f32_e32 v50, v248, v108
	v_fmac_f32_e32 v51, v249, v109
	s_waitcnt lgkmcnt(2)
	v_mfma_f32_32x32x16_bf16 v[212:227], v[74:77], v[42:45], v[212:227]
	v_max_f32_e32 v210, 0, v12
	v_max_f32_e32 v211, 0, v13
	v_fmac_f32_e32 v50, v250, v210
	v_fmac_f32_e32 v51, v251, v211
	v_max_f32_e32 v108, 0, v14
	v_max_f32_e32 v109, 0, v15
	v_fmac_f32_e32 v50, v252, v108
	v_fmac_f32_e32 v51, v253, v109
	v_max_f32_e32 v210, 0, v16
	v_max_f32_e32 v211, 0, v17
	v_fmac_f32_e32 v50, v254, v210
	v_fmac_f32_e32 v51, v255, v211
	s_waitcnt lgkmcnt(1)
	v_mfma_f32_32x32x16_bf16 v[212:227], v[78:81], v[46:49], v[212:227]
	v_max_f32_e32 v108, 0, v18
	v_max_f32_e32 v109, 0, v19
	v_fmac_f32_e32 v50, v200, v108
	v_fmac_f32_e32 v51, v201, v109
	v_max_f32_e32 v210, 0, v20
	v_max_f32_e32 v211, 0, v21
	v_fmac_f32_e32 v50, v202, v210
	v_fmac_f32_e32 v51, v203, v211
	v_add_f32_e32 v50, v50, v51
	v_ashrrev_i32_e32 v51, 31, v50
	s_waitcnt lgkmcnt(0)
	v_mfma_f32_32x32x16_bf16 v[212:227], v[82:85], v[196:199], v[212:227]
	v_or_b32_e32 v51, 0x80000000, v51
	s_cmpk_gt_i32 s11, 40
	s_cselect_b64 vcc, -1, 0
	v_xor_b32_e32 v50, v51, v50
	v_cndmask_b32_e32 v50, v123, v50, vcc
	global_store_dword v243, v50, s[8:9] offset:2048
	s_add_u32 s8, s8, 0x1000
	s_addc_u32 s9, s9, 0
	s_add_i32 m0, s10, 32768
	v_mfma_f32_32x32x16_bf16 v[6:21], v[86:89], v[38:41], 0
	global_load_lds_dwordx4 v102, s[6:7]
	s_add_i32 m0, s10, 33792
	s_nop 0
	global_load_lds_dwordx4 v110, s[6:7]
	s_add_i32 m0, s10, 34816
	s_nop 0
	global_load_lds_dwordx4 v112, s[6:7]
	s_add_i32 m0, s10, 35840
	s_nop 0
	global_load_lds_dwordx4 v193, s[6:7]
	s_add_u32 s6, s6, 0x8000
	s_addc_u32 s7, s7, 0
	v_max_f32_e32 v108, 0, v212
	v_max_f32_e32 v109, 0, v213
	v_mul_f32_e32 v0, v22, v108
	v_mul_f32_e32 v1, v23, v109
	v_max_f32_e32 v210, 0, v214
	v_max_f32_e32 v211, 0, v215
	v_fmac_f32_e32 v0, v24, v210
	v_fmac_f32_e32 v1, v25, v211
	v_max_f32_e32 v108, 0, v216
	v_max_f32_e32 v109, 0, v217
	v_fmac_f32_e32 v0, v26, v108
	v_fmac_f32_e32 v1, v27, v109
	v_mfma_f32_32x32x16_bf16 v[6:21], v[90:93], v[42:45], v[6:21]
	v_max_f32_e32 v210, 0, v218
	v_max_f32_e32 v211, 0, v219
	v_fmac_f32_e32 v0, v28, v210
	v_fmac_f32_e32 v1, v29, v211
	v_max_f32_e32 v108, 0, v220
	v_max_f32_e32 v109, 0, v221
	v_fmac_f32_e32 v0, v30, v108
	v_fmac_f32_e32 v1, v31, v109
	v_max_f32_e32 v210, 0, v222
	v_max_f32_e32 v211, 0, v223
	v_fmac_f32_e32 v0, v32, v210
	v_fmac_f32_e32 v1, v33, v211
	v_mfma_f32_32x32x16_bf16 v[6:21], v[94:97], v[46:49], v[6:21]
	v_max_f32_e32 v108, 0, v224
	v_max_f32_e32 v109, 0, v225
	v_fmac_f32_e32 v0, v34, v108
	v_fmac_f32_e32 v1, v35, v109
	v_max_f32_e32 v210, 0, v226
	v_max_f32_e32 v211, 0, v227
	v_fmac_f32_e32 v0, v36, v210
	v_fmac_f32_e32 v1, v37, v211
	v_add_f32_e32 v0, v0, v1
	v_ashrrev_i32_e32 v1, 31, v0
	v_mfma_f32_32x32x16_bf16 v[6:21], v[98:101], v[196:199], v[6:21]
	s_waitcnt vmcnt(10)
	v_add_u32_e32 v228, 0x10000, v5
	ds_read_b128 v[38:41], v228 offset:43264
	v_add_u32_e32 v228, 0x10000, v52
	ds_read_b128 v[42:45], v228 offset:43264
	v_add_u32_e32 v228, 0x10000, v55
	ds_read_b128 v[46:49], v228 offset:43264
	v_add_u32_e32 v228, 0x10000, v56
	ds_read_b128 v[196:199], v228 offset:43264
	v_or_b32_e32 v1, 0x80000000, v1
	s_cmpk_gt_i32 s11, 48
	s_cselect_b64 vcc, -1, 0
	v_xor_b32_e32 v0, v1, v0
	v_cndmask_b32_e32 v140, v123, v0, vcc
	s_nop 3
	s_waitcnt lgkmcnt(3)
	v_mfma_f32_32x32x16_bf16 v[212:227], v[70:73], v[38:41], 0
	v_max_f32_e32 v108, 0, v6
	v_max_f32_e32 v109, 0, v7
	v_mul_f32_e32 v50, v244, v108
	v_mul_f32_e32 v51, v245, v109
	v_max_f32_e32 v210, 0, v8
	v_max_f32_e32 v211, 0, v9
	v_fmac_f32_e32 v50, v246, v210
	v_fmac_f32_e32 v51, v247, v211
	v_max_f32_e32 v108, 0, v10
	v_max_f32_e32 v109, 0, v11
	v_fmac_f32_e32 v50, v248, v108
	v_fmac_f32_e32 v51, v249, v109
	s_waitcnt lgkmcnt(2)
	v_mfma_f32_32x32x16_bf16 v[212:227], v[74:77], v[42:45], v[212:227]
	v_max_f32_e32 v210, 0, v12
	v_max_f32_e32 v211, 0, v13
	v_fmac_f32_e32 v50, v250, v210
	v_fmac_f32_e32 v51, v251, v211
	v_max_f32_e32 v108, 0, v14
	v_max_f32_e32 v109, 0, v15
	v_fmac_f32_e32 v50, v252, v108
	v_fmac_f32_e32 v51, v253, v109
	v_max_f32_e32 v210, 0, v16
	v_max_f32_e32 v211, 0, v17
	v_fmac_f32_e32 v50, v254, v210
	v_fmac_f32_e32 v51, v255, v211
	s_waitcnt lgkmcnt(1)
	v_mfma_f32_32x32x16_bf16 v[212:227], v[78:81], v[46:49], v[212:227]
	v_max_f32_e32 v108, 0, v18
	v_max_f32_e32 v109, 0, v19
	v_fmac_f32_e32 v50, v200, v108
	v_fmac_f32_e32 v51, v201, v109
	v_max_f32_e32 v210, 0, v20
	v_max_f32_e32 v211, 0, v21
	v_fmac_f32_e32 v50, v202, v210
	v_fmac_f32_e32 v51, v203, v211
	v_add_f32_e32 v50, v50, v51
	v_ashrrev_i32_e32 v51, 31, v50
	s_waitcnt lgkmcnt(0)
	v_mfma_f32_32x32x16_bf16 v[212:227], v[82:85], v[196:199], v[212:227]
	v_or_b32_e32 v51, 0x80000000, v51
	s_cmpk_gt_i32 s11, 48
	s_cselect_b64 vcc, -1, 0
	v_xor_b32_e32 v50, v51, v50
	v_cndmask_b32_e32 v50, v123, v50, vcc
	global_store_dword v243, v50, s[8:9]
	s_add_i32 m0, s10, 65536
	v_mfma_f32_32x32x16_bf16 v[6:21], v[86:89], v[38:41], 0
	global_load_lds_dwordx4 v102, s[6:7]
	s_add_i32 m0, s10, 66560
	s_nop 0
	global_load_lds_dwordx4 v110, s[6:7]
	s_add_i32 m0, s10, 67584
	s_nop 0
	global_load_lds_dwordx4 v112, s[6:7]
	s_add_i32 m0, s10, 68608
	s_nop 0
	global_load_lds_dwordx4 v193, s[6:7]
	s_add_u32 s6, s6, 0x8000
	s_addc_u32 s7, s7, 0
	v_max_f32_e32 v108, 0, v212
	v_max_f32_e32 v109, 0, v213
	v_mul_f32_e32 v0, v22, v108
	v_mul_f32_e32 v1, v23, v109
	v_max_f32_e32 v210, 0, v214
	v_max_f32_e32 v211, 0, v215
	v_fmac_f32_e32 v0, v24, v210
	v_fmac_f32_e32 v1, v25, v211
	v_max_f32_e32 v108, 0, v216
	v_max_f32_e32 v109, 0, v217
	v_fmac_f32_e32 v0, v26, v108
	v_fmac_f32_e32 v1, v27, v109
	v_mfma_f32_32x32x16_bf16 v[6:21], v[90:93], v[42:45], v[6:21]
	v_max_f32_e32 v210, 0, v218
	v_max_f32_e32 v211, 0, v219
	v_fmac_f32_e32 v0, v28, v210
	v_fmac_f32_e32 v1, v29, v211
	v_max_f32_e32 v108, 0, v220
	v_max_f32_e32 v109, 0, v221
	v_fmac_f32_e32 v0, v30, v108
	v_fmac_f32_e32 v1, v31, v109
	v_max_f32_e32 v210, 0, v222
	v_max_f32_e32 v211, 0, v223
	v_fmac_f32_e32 v0, v32, v210
	v_fmac_f32_e32 v1, v33, v211
	v_mfma_f32_32x32x16_bf16 v[6:21], v[94:97], v[46:49], v[6:21]
	v_max_f32_e32 v108, 0, v224
	v_max_f32_e32 v109, 0, v225
	v_fmac_f32_e32 v0, v34, v108
	v_fmac_f32_e32 v1, v35, v109
	v_max_f32_e32 v210, 0, v226
	v_max_f32_e32 v211, 0, v227
	v_fmac_f32_e32 v0, v36, v210
	v_fmac_f32_e32 v1, v37, v211
	v_add_f32_e32 v0, v0, v1
	v_ashrrev_i32_e32 v1, 31, v0
	v_mfma_f32_32x32x16_bf16 v[6:21], v[98:101], v[196:199], v[6:21]
	s_waitcnt vmcnt(10)
	ds_read_b128 v[38:41], v5 offset:10496
	ds_read_b128 v[42:45], v52 offset:10496
	ds_read_b128 v[46:49], v55 offset:10496
	ds_read_b128 v[196:199], v56 offset:10496
	v_or_b32_e32 v1, 0x80000000, v1
	s_cmpk_gt_i32 s11, 56
	s_cselect_b64 vcc, -1, 0
	v_xor_b32_e32 v0, v1, v0
	v_cndmask_b32_e32 v139, v123, v0, vcc
	s_nop 3
	v_max_f32_e32 v108, 0, v6
	v_max_f32_e32 v109, 0, v7
	v_mul_f32_e32 v50, v244, v108
	v_mul_f32_e32 v51, v245, v109
	v_max_f32_e32 v210, 0, v8
	v_max_f32_e32 v211, 0, v9
	v_fmac_f32_e32 v50, v246, v210
	v_fmac_f32_e32 v51, v247, v211
	v_max_f32_e32 v108, 0, v10
	v_max_f32_e32 v109, 0, v11
	v_fmac_f32_e32 v50, v248, v108
	v_fmac_f32_e32 v51, v249, v109
	v_max_f32_e32 v210, 0, v12
	v_max_f32_e32 v211, 0, v13
	v_fmac_f32_e32 v50, v250, v210
	v_fmac_f32_e32 v51, v251, v211
	v_max_f32_e32 v108, 0, v14
	v_max_f32_e32 v109, 0, v15
	v_fmac_f32_e32 v50, v252, v108
	v_fmac_f32_e32 v51, v253, v109
	v_max_f32_e32 v210, 0, v16
	v_max_f32_e32 v211, 0, v17
	v_fmac_f32_e32 v50, v254, v210
	v_fmac_f32_e32 v51, v255, v211
	v_max_f32_e32 v108, 0, v18
	v_max_f32_e32 v109, 0, v19
	v_fmac_f32_e32 v50, v200, v108
	v_fmac_f32_e32 v51, v201, v109
	v_max_f32_e32 v210, 0, v20
	v_max_f32_e32 v211, 0, v21
	v_fmac_f32_e32 v50, v202, v210
	v_fmac_f32_e32 v51, v203, v211
	v_add_f32_e32 v50, v50, v51
	v_ashrrev_i32_e32 v51, 31, v50
	v_or_b32_e32 v51, 0x80000000, v51
	s_cmpk_gt_i32 s11, 56
	s_cselect_b64 vcc, -1, 0
	v_xor_b32_e32 v50, v51, v50
	v_cndmask_b32_e32 v50, v123, v50, vcc
	global_store_dword v243, v50, s[8:9] offset:2048
	s_add_u32 s8, s8, 0x1000
	s_addc_u32 s9, s9, 0
	s_cmpk_gt_i32 s81, 8
	s_cbranch_scc0 .Lix_fill_1
	s_waitcnt lgkmcnt(3)
	s_add_i32 m0, s10, 98304
	v_mfma_f32_32x32x16_bf16 v[212:227], v[70:73], v[38:41], 0
	global_load_lds_dwordx4 v102, s[6:7]
	s_waitcnt lgkmcnt(2)
	s_add_i32 m0, s10, 99328
	v_mfma_f32_32x32x16_bf16 v[212:227], v[74:77], v[42:45], v[212:227]
	global_load_lds_dwordx4 v110, s[6:7]
	s_waitcnt lgkmcnt(1)
	s_add_i32 m0, s10, 100352
	v_mfma_f32_32x32x16_bf16 v[212:227], v[78:81], v[46:49], v[212:227]
	global_load_lds_dwordx4 v112, s[6:7]
	s_waitcnt lgkmcnt(0)
	s_add_i32 m0, s10, 101376
	v_mfma_f32_32x32x16_bf16 v[212:227], v[82:85], v[196:199], v[212:227]
	global_load_lds_dwordx4 v193, s[6:7]
	s_add_u32 s6, s6, 0x8000
	s_addc_u32 s7, s7, 0
	v_mfma_f32_32x32x16_bf16 v[6:21], v[86:89], v[38:41], 0
	s_nop 7
	s_nop 2
	v_max_f32_e32 v108, 0, v212
	v_max_f32_e32 v109, 0, v213
	v_mul_f32_e32 v0, v22, v108
	v_mul_f32_e32 v1, v23, v109
	v_max_f32_e32 v210, 0, v214
	v_max_f32_e32 v211, 0, v215
	v_fmac_f32_e32 v0, v24, v210
	v_fmac_f32_e32 v1, v25, v211
	v_max_f32_e32 v108, 0, v216
	v_max_f32_e32 v109, 0, v217
	v_fmac_f32_e32 v0, v26, v108
	v_fmac_f32_e32 v1, v27, v109
	v_mfma_f32_32x32x16_bf16 v[6:21], v[90:93], v[42:45], v[6:21]
	v_max_f32_e32 v210, 0, v218
	v_max_f32_e32 v211, 0, v219
	v_fmac_f32_e32 v0, v28, v210
	v_fmac_f32_e32 v1, v29, v211
	v_max_f32_e32 v108, 0, v220
	v_max_f32_e32 v109, 0, v221
	v_fmac_f32_e32 v0, v30, v108
	v_fmac_f32_e32 v1, v31, v109
	v_max_f32_e32 v210, 0, v222
	v_max_f32_e32 v211, 0, v223
	v_fmac_f32_e32 v0, v32, v210
	v_fmac_f32_e32 v1, v33, v211
	v_mfma_f32_32x32x16_bf16 v[6:21], v[94:97], v[46:49], v[6:21]
	v_max_f32_e32 v108, 0, v224
	v_max_f32_e32 v109, 0, v225
	v_fmac_f32_e32 v0, v34, v108
	v_fmac_f32_e32 v1, v35, v109
	v_max_f32_e32 v210, 0, v226
	v_max_f32_e32 v211, 0, v227
	v_fmac_f32_e32 v0, v36, v210
	v_fmac_f32_e32 v1, v37, v211
	v_add_f32_e32 v0, v0, v1
	v_ashrrev_i32_e32 v1, 31, v0
	v_mfma_f32_32x32x16_bf16 v[6:21], v[98:101], v[196:199], v[6:21]
	s_waitcnt vmcnt(10)
	ds_read_b128 v[38:41], v5 offset:43264
	ds_read_b128 v[42:45], v52 offset:43264
	ds_read_b128 v[46:49], v55 offset:43264
	ds_read_b128 v[196:199], v56 offset:43264
	v_or_b32_e32 v1, 0x80000000, v1
	s_cmpk_gt_i32 s11, 64
	s_cselect_b64 vcc, -1, 0
	v_xor_b32_e32 v0, v1, v0
	v_cndmask_b32_e32 v142, v123, v0, vcc
	s_nop 3
	s_waitcnt lgkmcnt(3)
	v_mfma_f32_32x32x16_bf16 v[212:227], v[70:73], v[38:41], 0
	v_max_f32_e32 v108, 0, v6
	v_max_f32_e32 v109, 0, v7
	v_mul_f32_e32 v50, v244, v108
	v_mul_f32_e32 v51, v245, v109
	v_max_f32_e32 v210, 0, v8
	v_max_f32_e32 v211, 0, v9
	v_fmac_f32_e32 v50, v246, v210
	v_fmac_f32_e32 v51, v247, v211
	v_max_f32_e32 v108, 0, v10
	v_max_f32_e32 v109, 0, v11
	v_fmac_f32_e32 v50, v248, v108
	v_fmac_f32_e32 v51, v249, v109
	s_waitcnt lgkmcnt(2)
	v_mfma_f32_32x32x16_bf16 v[212:227], v[74:77], v[42:45], v[212:227]
	v_max_f32_e32 v210, 0, v12
	v_max_f32_e32 v211, 0, v13
	v_fmac_f32_e32 v50, v250, v210
	v_fmac_f32_e32 v51, v251, v211
	v_max_f32_e32 v108, 0, v14
	v_max_f32_e32 v109, 0, v15
	v_fmac_f32_e32 v50, v252, v108
	v_fmac_f32_e32 v51, v253, v109
	v_max_f32_e32 v210, 0, v16
	v_max_f32_e32 v211, 0, v17
	v_fmac_f32_e32 v50, v254, v210
	v_fmac_f32_e32 v51, v255, v211
	s_waitcnt lgkmcnt(1)
	v_mfma_f32_32x32x16_bf16 v[212:227], v[78:81], v[46:49], v[212:227]
	v_max_f32_e32 v108, 0, v18
	v_max_f32_e32 v109, 0, v19
	v_fmac_f32_e32 v50, v200, v108
	v_fmac_f32_e32 v51, v201, v109
	v_max_f32_e32 v210, 0, v20
	v_max_f32_e32 v211, 0, v21
	v_fmac_f32_e32 v50, v202, v210
	v_fmac_f32_e32 v51, v203, v211
	v_add_f32_e32 v50, v50, v51
	v_ashrrev_i32_e32 v51, 31, v50
	s_waitcnt lgkmcnt(0)
	v_mfma_f32_32x32x16_bf16 v[212:227], v[82:85], v[196:199], v[212:227]
	v_or_b32_e32 v51, 0x80000000, v51
	s_cmpk_gt_i32 s11, 64
	s_cselect_b64 vcc, -1, 0
	v_xor_b32_e32 v50, v51, v50
	v_cndmask_b32_e32 v50, v123, v50, vcc
	global_store_dword v243, v50, s[8:9]
	s_add_i32 m0, s10, 0
	v_mfma_f32_32x32x16_bf16 v[6:21], v[86:89], v[38:41], 0
	global_load_lds_dwordx4 v102, s[6:7]
	s_add_i32 m0, s10, 1024
	s_nop 0
	global_load_lds_dwordx4 v110, s[6:7]
	s_add_i32 m0, s10, 2048
	s_nop 0
	global_load_lds_dwordx4 v112, s[6:7]
	s_add_i32 m0, s10, 3072
	s_nop 0
	global_load_lds_dwordx4 v193, s[6:7]
	s_add_u32 s6, s6, 0x8000
	s_addc_u32 s7, s7, 0
	v_max_f32_e32 v108, 0, v212
	v_max_f32_e32 v109, 0, v213
	v_mul_f32_e32 v0, v22, v108
	v_mul_f32_e32 v1, v23, v109
	v_max_f32_e32 v210, 0, v214
	v_max_f32_e32 v211, 0, v215
	v_fmac_f32_e32 v0, v24, v210
	v_fmac_f32_e32 v1, v25, v211
	v_max_f32_e32 v108, 0, v216
	v_max_f32_e32 v109, 0, v217
	v_fmac_f32_e32 v0, v26, v108
	v_fmac_f32_e32 v1, v27, v109
	v_mfma_f32_32x32x16_bf16 v[6:21], v[90:93], v[42:45], v[6:21]
	v_max_f32_e32 v210, 0, v218
	v_max_f32_e32 v211, 0, v219
	v_fmac_f32_e32 v0, v28, v210
	v_fmac_f32_e32 v1, v29, v211
	v_max_f32_e32 v108, 0, v220
	v_max_f32_e32 v109, 0, v221
	v_fmac_f32_e32 v0, v30, v108
	v_fmac_f32_e32 v1, v31, v109
	v_max_f32_e32 v210, 0, v222
	v_max_f32_e32 v211, 0, v223
	v_fmac_f32_e32 v0, v32, v210
	v_fmac_f32_e32 v1, v33, v211
	v_mfma_f32_32x32x16_bf16 v[6:21], v[94:97], v[46:49], v[6:21]
	v_max_f32_e32 v108, 0, v224
	v_max_f32_e32 v109, 0, v225
	v_fmac_f32_e32 v0, v34, v108
	v_fmac_f32_e32 v1, v35, v109
	v_max_f32_e32 v210, 0, v226
	v_max_f32_e32 v211, 0, v227
	v_fmac_f32_e32 v0, v36, v210
	v_fmac_f32_e32 v1, v37, v211
	v_add_f32_e32 v0, v0, v1
	v_ashrrev_i32_e32 v1, 31, v0
	v_mfma_f32_32x32x16_bf16 v[6:21], v[98:101], v[196:199], v[6:21]
	s_waitcnt vmcnt(10)
	v_add_u32_e32 v228, 0x10000, v5
	ds_read_b128 v[38:41], v228 offset:10496
	v_add_u32_e32 v228, 0x10000, v52
	ds_read_b128 v[42:45], v228 offset:10496
	v_add_u32_e32 v228, 0x10000, v55
	ds_read_b128 v[46:49], v228 offset:10496
	v_add_u32_e32 v228, 0x10000, v56
	ds_read_b128 v[196:199], v228 offset:10496
	v_or_b32_e32 v1, 0x80000000, v1
	s_cmpk_gt_i32 s11, 72
	s_cselect_b64 vcc, -1, 0
	v_xor_b32_e32 v0, v1, v0
	v_cndmask_b32_e32 v141, v123, v0, vcc
	s_nop 3
	s_waitcnt lgkmcnt(3)
	v_mfma_f32_32x32x16_bf16 v[212:227], v[70:73], v[38:41], 0
	v_max_f32_e32 v108, 0, v6
	v_max_f32_e32 v109, 0, v7
	v_mul_f32_e32 v50, v244, v108
	v_mul_f32_e32 v51, v245, v109
	v_max_f32_e32 v210, 0, v8
	v_max_f32_e32 v211, 0, v9
	v_fmac_f32_e32 v50, v246, v210
	v_fmac_f32_e32 v51, v247, v211
	v_max_f32_e32 v108, 0, v10
	v_max_f32_e32 v109, 0, v11
	v_fmac_f32_e32 v50, v248, v108
	v_fmac_f32_e32 v51, v249, v109
	s_waitcnt lgkmcnt(2)
	v_mfma_f32_32x32x16_bf16 v[212:227], v[74:77], v[42:45], v[212:227]
	v_max_f32_e32 v210, 0, v12
	v_max_f32_e32 v211, 0, v13
	v_fmac_f32_e32 v50, v250, v210
	v_fmac_f32_e32 v51, v251, v211
	v_max_f32_e32 v108, 0, v14
	v_max_f32_e32 v109, 0, v15
	v_fmac_f32_e32 v50, v252, v108
	v_fmac_f32_e32 v51, v253, v109
	v_max_f32_e32 v210, 0, v16
	v_max_f32_e32 v211, 0, v17
	v_fmac_f32_e32 v50, v254, v210
	v_fmac_f32_e32 v51, v255, v211
	s_waitcnt lgkmcnt(1)
	v_mfma_f32_32x32x16_bf16 v[212:227], v[78:81], v[46:49], v[212:227]
	v_max_f32_e32 v108, 0, v18
	v_max_f32_e32 v109, 0, v19
	v_fmac_f32_e32 v50, v200, v108
	v_fmac_f32_e32 v51, v201, v109
	v_max_f32_e32 v210, 0, v20
	v_max_f32_e32 v211, 0, v21
	v_fmac_f32_e32 v50, v202, v210
	v_fmac_f32_e32 v51, v203, v211
	v_add_f32_e32 v50, v50, v51
	v_ashrrev_i32_e32 v51, 31, v50
	s_waitcnt lgkmcnt(0)
	v_mfma_f32_32x32x16_bf16 v[212:227], v[82:85], v[196:199], v[212:227]
	v_or_b32_e32 v51, 0x80000000, v51
	s_cmpk_gt_i32 s11, 72
	s_cselect_b64 vcc, -1, 0
	v_xor_b32_e32 v50, v51, v50
	v_cndmask_b32_e32 v50, v123, v50, vcc
	global_store_dword v243, v50, s[8:9] offset:2048
	s_add_u32 s8, s8, 0x1000
	s_addc_u32 s9, s9, 0
	s_add_i32 m0, s10, 32768
	v_mfma_f32_32x32x16_bf16 v[6:21], v[86:89], v[38:41], 0
	global_load_lds_dwordx4 v102, s[6:7]
	s_add_i32 m0, s10, 33792
	s_nop 0
	global_load_lds_dwordx4 v110, s[6:7]
	s_add_i32 m0, s10, 34816
	s_nop 0
	global_load_lds_dwordx4 v112, s[6:7]
	s_add_i32 m0, s10, 35840
	s_nop 0
	global_load_lds_dwordx4 v193, s[6:7]
	s_add_u32 s6, s6, 0x8000
	s_addc_u32 s7, s7, 0
	v_max_f32_e32 v108, 0, v212
	v_max_f32_e32 v109, 0, v213
	v_mul_f32_e32 v0, v22, v108
	v_mul_f32_e32 v1, v23, v109
	v_max_f32_e32 v210, 0, v214
	v_max_f32_e32 v211, 0, v215
	v_fmac_f32_e32 v0, v24, v210
	v_fmac_f32_e32 v1, v25, v211
	v_max_f32_e32 v108, 0, v216
	v_max_f32_e32 v109, 0, v217
	v_fmac_f32_e32 v0, v26, v108
	v_fmac_f32_e32 v1, v27, v109
	v_mfma_f32_32x32x16_bf16 v[6:21], v[90:93], v[42:45], v[6:21]
	v_max_f32_e32 v210, 0, v218
	v_max_f32_e32 v211, 0, v219
	v_fmac_f32_e32 v0, v28, v210
	v_fmac_f32_e32 v1, v29, v211
	v_max_f32_e32 v108, 0, v220
	v_max_f32_e32 v109, 0, v221
	v_fmac_f32_e32 v0, v30, v108
	v_fmac_f32_e32 v1, v31, v109
	v_max_f32_e32 v210, 0, v222
	v_max_f32_e32 v211, 0, v223
	v_fmac_f32_e32 v0, v32, v210
	v_fmac_f32_e32 v1, v33, v211
	v_mfma_f32_32x32x16_bf16 v[6:21], v[94:97], v[46:49], v[6:21]
	v_max_f32_e32 v108, 0, v224
	v_max_f32_e32 v109, 0, v225
	v_fmac_f32_e32 v0, v34, v108
	v_fmac_f32_e32 v1, v35, v109
	v_max_f32_e32 v210, 0, v226
	v_max_f32_e32 v211, 0, v227
	v_fmac_f32_e32 v0, v36, v210
	v_fmac_f32_e32 v1, v37, v211
	v_add_f32_e32 v0, v0, v1
	v_ashrrev_i32_e32 v1, 31, v0
	v_mfma_f32_32x32x16_bf16 v[6:21], v[98:101], v[196:199], v[6:21]
	s_waitcnt vmcnt(10)
	v_add_u32_e32 v228, 0x10000, v5
	ds_read_b128 v[38:41], v228 offset:43264
	v_add_u32_e32 v228, 0x10000, v52
	ds_read_b128 v[42:45], v228 offset:43264
	v_add_u32_e32 v228, 0x10000, v55
	ds_read_b128 v[46:49], v228 offset:43264
	v_add_u32_e32 v228, 0x10000, v56
	ds_read_b128 v[196:199], v228 offset:43264
	v_or_b32_e32 v1, 0x80000000, v1
	s_cmpk_gt_i32 s11, 80
	s_cselect_b64 vcc, -1, 0
	v_xor_b32_e32 v0, v1, v0
	v_cndmask_b32_e32 v144, v123, v0, vcc
	s_nop 3
	s_waitcnt lgkmcnt(3)
	v_mfma_f32_32x32x16_bf16 v[212:227], v[70:73], v[38:41], 0
	v_max_f32_e32 v108, 0, v6
	v_max_f32_e32 v109, 0, v7
	v_mul_f32_e32 v50, v244, v108
	v_mul_f32_e32 v51, v245, v109
	v_max_f32_e32 v210, 0, v8
	v_max_f32_e32 v211, 0, v9
	v_fmac_f32_e32 v50, v246, v210
	v_fmac_f32_e32 v51, v247, v211
	v_max_f32_e32 v108, 0, v10
	v_max_f32_e32 v109, 0, v11
	v_fmac_f32_e32 v50, v248, v108
	v_fmac_f32_e32 v51, v249, v109
	s_waitcnt lgkmcnt(2)
	v_mfma_f32_32x32x16_bf16 v[212:227], v[74:77], v[42:45], v[212:227]
	v_max_f32_e32 v210, 0, v12
	v_max_f32_e32 v211, 0, v13
	v_fmac_f32_e32 v50, v250, v210
	v_fmac_f32_e32 v51, v251, v211
	v_max_f32_e32 v108, 0, v14
	v_max_f32_e32 v109, 0, v15
	v_fmac_f32_e32 v50, v252, v108
	v_fmac_f32_e32 v51, v253, v109
	v_max_f32_e32 v210, 0, v16
	v_max_f32_e32 v211, 0, v17
	v_fmac_f32_e32 v50, v254, v210
	v_fmac_f32_e32 v51, v255, v211
	s_waitcnt lgkmcnt(1)
	v_mfma_f32_32x32x16_bf16 v[212:227], v[78:81], v[46:49], v[212:227]
	v_max_f32_e32 v108, 0, v18
	v_max_f32_e32 v109, 0, v19
	v_fmac_f32_e32 v50, v200, v108
	v_fmac_f32_e32 v51, v201, v109
	v_max_f32_e32 v210, 0, v20
	v_max_f32_e32 v211, 0, v21
	v_fmac_f32_e32 v50, v202, v210
	v_fmac_f32_e32 v51, v203, v211
	v_add_f32_e32 v50, v50, v51
	v_ashrrev_i32_e32 v51, 31, v50
	s_waitcnt lgkmcnt(0)
	v_mfma_f32_32x32x16_bf16 v[212:227], v[82:85], v[196:199], v[212:227]
	v_or_b32_e32 v51, 0x80000000, v51
	s_cmpk_gt_i32 s11, 80
	s_cselect_b64 vcc, -1, 0
	v_xor_b32_e32 v50, v51, v50
	v_cndmask_b32_e32 v50, v123, v50, vcc
	global_store_dword v243, v50, s[8:9]
	s_add_i32 m0, s10, 65536
	v_mfma_f32_32x32x16_bf16 v[6:21], v[86:89], v[38:41], 0
	global_load_lds_dwordx4 v102, s[6:7]
	s_add_i32 m0, s10, 66560
	s_nop 0
	global_load_lds_dwordx4 v110, s[6:7]
	s_add_i32 m0, s10, 67584
	s_nop 0
	global_load_lds_dwordx4 v112, s[6:7]
	s_add_i32 m0, s10, 68608
	s_nop 0
	global_load_lds_dwordx4 v193, s[6:7]
	s_add_u32 s6, s6, 0x8000
	s_addc_u32 s7, s7, 0
	v_max_f32_e32 v108, 0, v212
	v_max_f32_e32 v109, 0, v213
	v_mul_f32_e32 v0, v22, v108
	v_mul_f32_e32 v1, v23, v109
	v_max_f32_e32 v210, 0, v214
	v_max_f32_e32 v211, 0, v215
	v_fmac_f32_e32 v0, v24, v210
	v_fmac_f32_e32 v1, v25, v211
	v_max_f32_e32 v108, 0, v216
	v_max_f32_e32 v109, 0, v217
	v_fmac_f32_e32 v0, v26, v108
	v_fmac_f32_e32 v1, v27, v109
	v_mfma_f32_32x32x16_bf16 v[6:21], v[90:93], v[42:45], v[6:21]
	v_max_f32_e32 v210, 0, v218
	v_max_f32_e32 v211, 0, v219
	v_fmac_f32_e32 v0, v28, v210
	v_fmac_f32_e32 v1, v29, v211
	v_max_f32_e32 v108, 0, v220
	v_max_f32_e32 v109, 0, v221
	v_fmac_f32_e32 v0, v30, v108
	v_fmac_f32_e32 v1, v31, v109
	v_max_f32_e32 v210, 0, v222
	v_max_f32_e32 v211, 0, v223
	v_fmac_f32_e32 v0, v32, v210
	v_fmac_f32_e32 v1, v33, v211
	v_mfma_f32_32x32x16_bf16 v[6:21], v[94:97], v[46:49], v[6:21]
	v_max_f32_e32 v108, 0, v224
	v_max_f32_e32 v109, 0, v225
	v_fmac_f32_e32 v0, v34, v108
	v_fmac_f32_e32 v1, v35, v109
	v_max_f32_e32 v210, 0, v226
	v_max_f32_e32 v211, 0, v227
	v_fmac_f32_e32 v0, v36, v210
	v_fmac_f32_e32 v1, v37, v211
	v_add_f32_e32 v0, v0, v1
	v_ashrrev_i32_e32 v1, 31, v0
	v_mfma_f32_32x32x16_bf16 v[6:21], v[98:101], v[196:199], v[6:21]
	s_waitcnt vmcnt(10)
	ds_read_b128 v[38:41], v5 offset:10496
	ds_read_b128 v[42:45], v52 offset:10496
	ds_read_b128 v[46:49], v55 offset:10496
	ds_read_b128 v[196:199], v56 offset:10496
	v_or_b32_e32 v1, 0x80000000, v1
	s_cmpk_gt_i32 s11, 88
	s_cselect_b64 vcc, -1, 0
	v_xor_b32_e32 v0, v1, v0
	v_cndmask_b32_e32 v143, v123, v0, vcc
	s_nop 3
	s_waitcnt lgkmcnt(3)
	v_mfma_f32_32x32x16_bf16 v[212:227], v[70:73], v[38:41], 0
	v_max_f32_e32 v108, 0, v6
	v_max_f32_e32 v109, 0, v7
	v_mul_f32_e32 v50, v244, v108
	v_mul_f32_e32 v51, v245, v109
	v_max_f32_e32 v210, 0, v8
	v_max_f32_e32 v211, 0, v9
	v_fmac_f32_e32 v50, v246, v210
	v_fmac_f32_e32 v51, v247, v211
	v_max_f32_e32 v108, 0, v10
	v_max_f32_e32 v109, 0, v11
	v_fmac_f32_e32 v50, v248, v108
	v_fmac_f32_e32 v51, v249, v109
	s_waitcnt lgkmcnt(2)
	v_mfma_f32_32x32x16_bf16 v[212:227], v[74:77], v[42:45], v[212:227]
	v_max_f32_e32 v210, 0, v12
	v_max_f32_e32 v211, 0, v13
	v_fmac_f32_e32 v50, v250, v210
	v_fmac_f32_e32 v51, v251, v211
	v_max_f32_e32 v108, 0, v14
	v_max_f32_e32 v109, 0, v15
	v_fmac_f32_e32 v50, v252, v108
	v_fmac_f32_e32 v51, v253, v109
	v_max_f32_e32 v210, 0, v16
	v_max_f32_e32 v211, 0, v17
	v_fmac_f32_e32 v50, v254, v210
	v_fmac_f32_e32 v51, v255, v211
	s_waitcnt lgkmcnt(1)
	v_mfma_f32_32x32x16_bf16 v[212:227], v[78:81], v[46:49], v[212:227]
	v_max_f32_e32 v108, 0, v18
	v_max_f32_e32 v109, 0, v19
	v_fmac_f32_e32 v50, v200, v108
	v_fmac_f32_e32 v51, v201, v109
	v_max_f32_e32 v210, 0, v20
	v_max_f32_e32 v211, 0, v21
	v_fmac_f32_e32 v50, v202, v210
	v_fmac_f32_e32 v51, v203, v211
	v_add_f32_e32 v50, v50, v51
	v_ashrrev_i32_e32 v51, 31, v50
	s_waitcnt lgkmcnt(0)
	v_mfma_f32_32x32x16_bf16 v[212:227], v[82:85], v[196:199], v[212:227]
	v_or_b32_e32 v51, 0x80000000, v51
	s_cmpk_gt_i32 s11, 88
	s_cselect_b64 vcc, -1, 0
	v_xor_b32_e32 v50, v51, v50
	v_cndmask_b32_e32 v50, v123, v50, vcc
	global_store_dword v243, v50, s[8:9] offset:2048
	s_add_u32 s8, s8, 0x1000
	s_addc_u32 s9, s9, 0
	s_add_i32 m0, s10, 98304
	v_mfma_f32_32x32x16_bf16 v[6:21], v[86:89], v[38:41], 0
	global_load_lds_dwordx4 v102, s[6:7]
	s_add_i32 m0, s10, 99328
	s_nop 0
	global_load_lds_dwordx4 v110, s[6:7]
	s_add_i32 m0, s10, 100352
	s_nop 0
	global_load_lds_dwordx4 v112, s[6:7]
	s_add_i32 m0, s10, 101376
	s_nop 0
	global_load_lds_dwordx4 v193, s[6:7]
	s_add_u32 s6, s6, 0x8000
	s_addc_u32 s7, s7, 0
	v_max_f32_e32 v108, 0, v212
	v_max_f32_e32 v109, 0, v213
	v_mul_f32_e32 v0, v22, v108
	v_mul_f32_e32 v1, v23, v109
	v_max_f32_e32 v210, 0, v214
	v_max_f32_e32 v211, 0, v215
	v_fmac_f32_e32 v0, v24, v210
	v_fmac_f32_e32 v1, v25, v211
	v_max_f32_e32 v108, 0, v216
	v_max_f32_e32 v109, 0, v217
	v_fmac_f32_e32 v0, v26, v108
	v_fmac_f32_e32 v1, v27, v109
	v_mfma_f32_32x32x16_bf16 v[6:21], v[90:93], v[42:45], v[6:21]
	v_max_f32_e32 v210, 0, v218
	v_max_f32_e32 v211, 0, v219
	v_fmac_f32_e32 v0, v28, v210
	v_fmac_f32_e32 v1, v29, v211
	v_max_f32_e32 v108, 0, v220
	v_max_f32_e32 v109, 0, v221
	v_fmac_f32_e32 v0, v30, v108
	v_fmac_f32_e32 v1, v31, v109
	v_max_f32_e32 v210, 0, v222
	v_max_f32_e32 v211, 0, v223
	v_fmac_f32_e32 v0, v32, v210
	v_fmac_f32_e32 v1, v33, v211
	v_mfma_f32_32x32x16_bf16 v[6:21], v[94:97], v[46:49], v[6:21]
	v_max_f32_e32 v108, 0, v224
	v_max_f32_e32 v109, 0, v225
	v_fmac_f32_e32 v0, v34, v108
	v_fmac_f32_e32 v1, v35, v109
	v_max_f32_e32 v210, 0, v226
	v_max_f32_e32 v211, 0, v227
	v_fmac_f32_e32 v0, v36, v210
	v_fmac_f32_e32 v1, v37, v211
	v_add_f32_e32 v0, v0, v1
	v_ashrrev_i32_e32 v1, 31, v0
	v_mfma_f32_32x32x16_bf16 v[6:21], v[98:101], v[196:199], v[6:21]
	s_waitcnt vmcnt(10)
	ds_read_b128 v[38:41], v5 offset:43264
	ds_read_b128 v[42:45], v52 offset:43264
	ds_read_b128 v[46:49], v55 offset:43264
	ds_read_b128 v[196:199], v56 offset:43264
	v_or_b32_e32 v1, 0x80000000, v1
	s_cmpk_gt_i32 s11, 96
	s_cselect_b64 vcc, -1, 0
	v_xor_b32_e32 v0, v1, v0
	v_cndmask_b32_e32 v146, v123, v0, vcc
	s_nop 3
	s_waitcnt lgkmcnt(3)
	v_mfma_f32_32x32x16_bf16 v[212:227], v[70:73], v[38:41], 0
	v_max_f32_e32 v108, 0, v6
	v_max_f32_e32 v109, 0, v7
	v_mul_f32_e32 v50, v244, v108
	v_mul_f32_e32 v51, v245, v109
	v_max_f32_e32 v210, 0, v8
	v_max_f32_e32 v211, 0, v9
	v_fmac_f32_e32 v50, v246, v210
	v_fmac_f32_e32 v51, v247, v211
	v_max_f32_e32 v108, 0, v10
	v_max_f32_e32 v109, 0, v11
	v_fmac_f32_e32 v50, v248, v108
	v_fmac_f32_e32 v51, v249, v109
	s_waitcnt lgkmcnt(2)
	v_mfma_f32_32x32x16_bf16 v[212:227], v[74:77], v[42:45], v[212:227]
	v_max_f32_e32 v210, 0, v12
	v_max_f32_e32 v211, 0, v13
	v_fmac_f32_e32 v50, v250, v210
	v_fmac_f32_e32 v51, v251, v211
	v_max_f32_e32 v108, 0, v14
	v_max_f32_e32 v109, 0, v15
	v_fmac_f32_e32 v50, v252, v108
	v_fmac_f32_e32 v51, v253, v109
	v_max_f32_e32 v210, 0, v16
	v_max_f32_e32 v211, 0, v17
	v_fmac_f32_e32 v50, v254, v210
	v_fmac_f32_e32 v51, v255, v211
	s_waitcnt lgkmcnt(1)
	v_mfma_f32_32x32x16_bf16 v[212:227], v[78:81], v[46:49], v[212:227]
	v_max_f32_e32 v108, 0, v18
	v_max_f32_e32 v109, 0, v19
	v_fmac_f32_e32 v50, v200, v108
	v_fmac_f32_e32 v51, v201, v109
	v_max_f32_e32 v210, 0, v20
	v_max_f32_e32 v211, 0, v21
	v_fmac_f32_e32 v50, v202, v210
	v_fmac_f32_e32 v51, v203, v211
	v_add_f32_e32 v50, v50, v51
	v_ashrrev_i32_e32 v51, 31, v50
	s_waitcnt lgkmcnt(0)
	v_mfma_f32_32x32x16_bf16 v[212:227], v[82:85], v[196:199], v[212:227]
	v_or_b32_e32 v51, 0x80000000, v51
	s_cmpk_gt_i32 s11, 96
	s_cselect_b64 vcc, -1, 0
	v_xor_b32_e32 v50, v51, v50
	v_cndmask_b32_e32 v50, v123, v50, vcc
	global_store_dword v243, v50, s[8:9]
	s_add_i32 m0, s10, 0
	v_mfma_f32_32x32x16_bf16 v[6:21], v[86:89], v[38:41], 0
	global_load_lds_dwordx4 v102, s[6:7]
	s_add_i32 m0, s10, 1024
	s_nop 0
	global_load_lds_dwordx4 v110, s[6:7]
	s_add_i32 m0, s10, 2048
	s_nop 0
	global_load_lds_dwordx4 v112, s[6:7]
	s_add_i32 m0, s10, 3072
	s_nop 0
	global_load_lds_dwordx4 v193, s[6:7]
	s_add_u32 s6, s6, 0x8000
	s_addc_u32 s7, s7, 0
	v_max_f32_e32 v108, 0, v212
	v_max_f32_e32 v109, 0, v213
	v_mul_f32_e32 v0, v22, v108
	v_mul_f32_e32 v1, v23, v109
	v_max_f32_e32 v210, 0, v214
	v_max_f32_e32 v211, 0, v215
	v_fmac_f32_e32 v0, v24, v210
	v_fmac_f32_e32 v1, v25, v211
	v_max_f32_e32 v108, 0, v216
	v_max_f32_e32 v109, 0, v217
	v_fmac_f32_e32 v0, v26, v108
	v_fmac_f32_e32 v1, v27, v109
	v_mfma_f32_32x32x16_bf16 v[6:21], v[90:93], v[42:45], v[6:21]
	v_max_f32_e32 v210, 0, v218
	v_max_f32_e32 v211, 0, v219
	v_fmac_f32_e32 v0, v28, v210
	v_fmac_f32_e32 v1, v29, v211
	v_max_f32_e32 v108, 0, v220
	v_max_f32_e32 v109, 0, v221
	v_fmac_f32_e32 v0, v30, v108
	v_fmac_f32_e32 v1, v31, v109
	v_max_f32_e32 v210, 0, v222
	v_max_f32_e32 v211, 0, v223
	v_fmac_f32_e32 v0, v32, v210
	v_fmac_f32_e32 v1, v33, v211
	v_mfma_f32_32x32x16_bf16 v[6:21], v[94:97], v[46:49], v[6:21]
	v_max_f32_e32 v108, 0, v224
	v_max_f32_e32 v109, 0, v225
	v_fmac_f32_e32 v0, v34, v108
	v_fmac_f32_e32 v1, v35, v109
	v_max_f32_e32 v210, 0, v226
	v_max_f32_e32 v211, 0, v227
	v_fmac_f32_e32 v0, v36, v210
	v_fmac_f32_e32 v1, v37, v211
	v_add_f32_e32 v0, v0, v1
	v_ashrrev_i32_e32 v1, 31, v0
	v_mfma_f32_32x32x16_bf16 v[6:21], v[98:101], v[196:199], v[6:21]
	s_waitcnt vmcnt(10)
	v_add_u32_e32 v228, 0x10000, v5
	ds_read_b128 v[38:41], v228 offset:10496
	v_add_u32_e32 v228, 0x10000, v52
	ds_read_b128 v[42:45], v228 offset:10496
	v_add_u32_e32 v228, 0x10000, v55
	ds_read_b128 v[46:49], v228 offset:10496
	v_add_u32_e32 v228, 0x10000, v56
	ds_read_b128 v[196:199], v228 offset:10496
	v_or_b32_e32 v1, 0x80000000, v1
	s_cmpk_gt_i32 s11, 104
	s_cselect_b64 vcc, -1, 0
	v_xor_b32_e32 v0, v1, v0
	v_cndmask_b32_e32 v145, v123, v0, vcc
	s_nop 3
	s_waitcnt lgkmcnt(3)
	v_mfma_f32_32x32x16_bf16 v[212:227], v[70:73], v[38:41], 0
	v_max_f32_e32 v108, 0, v6
	v_max_f32_e32 v109, 0, v7
	v_mul_f32_e32 v50, v244, v108
	v_mul_f32_e32 v51, v245, v109
	v_max_f32_e32 v210, 0, v8
	v_max_f32_e32 v211, 0, v9
	v_fmac_f32_e32 v50, v246, v210
	v_fmac_f32_e32 v51, v247, v211
	v_max_f32_e32 v108, 0, v10
	v_max_f32_e32 v109, 0, v11
	v_fmac_f32_e32 v50, v248, v108
	v_fmac_f32_e32 v51, v249, v109
	s_waitcnt lgkmcnt(2)
	v_mfma_f32_32x32x16_bf16 v[212:227], v[74:77], v[42:45], v[212:227]
	v_max_f32_e32 v210, 0, v12
	v_max_f32_e32 v211, 0, v13
	v_fmac_f32_e32 v50, v250, v210
	v_fmac_f32_e32 v51, v251, v211
	v_max_f32_e32 v108, 0, v14
	v_max_f32_e32 v109, 0, v15
	v_fmac_f32_e32 v50, v252, v108
	v_fmac_f32_e32 v51, v253, v109
	v_max_f32_e32 v210, 0, v16
	v_max_f32_e32 v211, 0, v17
	v_fmac_f32_e32 v50, v254, v210
	v_fmac_f32_e32 v51, v255, v211
	s_waitcnt lgkmcnt(1)
	v_mfma_f32_32x32x16_bf16 v[212:227], v[78:81], v[46:49], v[212:227]
	v_max_f32_e32 v108, 0, v18
	v_max_f32_e32 v109, 0, v19
	v_fmac_f32_e32 v50, v200, v108
	v_fmac_f32_e32 v51, v201, v109
	v_max_f32_e32 v210, 0, v20
	v_max_f32_e32 v211, 0, v21
	v_fmac_f32_e32 v50, v202, v210
	v_fmac_f32_e32 v51, v203, v211
	v_add_f32_e32 v50, v50, v51
	v_ashrrev_i32_e32 v51, 31, v50
	s_waitcnt lgkmcnt(0)
	v_mfma_f32_32x32x16_bf16 v[212:227], v[82:85], v[196:199], v[212:227]
	v_or_b32_e32 v51, 0x80000000, v51
	s_cmpk_gt_i32 s11, 104
	s_cselect_b64 vcc, -1, 0
	v_xor_b32_e32 v50, v51, v50
	v_cndmask_b32_e32 v50, v123, v50, vcc
	global_store_dword v243, v50, s[8:9] offset:2048
	s_add_u32 s8, s8, 0x1000
	s_addc_u32 s9, s9, 0
	s_add_i32 m0, s10, 32768
	v_mfma_f32_32x32x16_bf16 v[6:21], v[86:89], v[38:41], 0
	global_load_lds_dwordx4 v102, s[6:7]
	s_add_i32 m0, s10, 33792
	s_nop 0
	global_load_lds_dwordx4 v110, s[6:7]
	s_add_i32 m0, s10, 34816
	s_nop 0
	global_load_lds_dwordx4 v112, s[6:7]
	s_add_i32 m0, s10, 35840
	s_nop 0
	global_load_lds_dwordx4 v193, s[6:7]
	s_add_u32 s6, s6, 0x8000
	s_addc_u32 s7, s7, 0
	v_max_f32_e32 v108, 0, v212
	v_max_f32_e32 v109, 0, v213
	v_mul_f32_e32 v0, v22, v108
	v_mul_f32_e32 v1, v23, v109
	v_max_f32_e32 v210, 0, v214
	v_max_f32_e32 v211, 0, v215
	v_fmac_f32_e32 v0, v24, v210
	v_fmac_f32_e32 v1, v25, v211
	v_max_f32_e32 v108, 0, v216
	v_max_f32_e32 v109, 0, v217
	v_fmac_f32_e32 v0, v26, v108
	v_fmac_f32_e32 v1, v27, v109
	v_mfma_f32_32x32x16_bf16 v[6:21], v[90:93], v[42:45], v[6:21]
	v_max_f32_e32 v210, 0, v218
	v_max_f32_e32 v211, 0, v219
	v_fmac_f32_e32 v0, v28, v210
	v_fmac_f32_e32 v1, v29, v211
	v_max_f32_e32 v108, 0, v220
	v_max_f32_e32 v109, 0, v221
	v_fmac_f32_e32 v0, v30, v108
	v_fmac_f32_e32 v1, v31, v109
	v_max_f32_e32 v210, 0, v222
	v_max_f32_e32 v211, 0, v223
	v_fmac_f32_e32 v0, v32, v210
	v_fmac_f32_e32 v1, v33, v211
	v_mfma_f32_32x32x16_bf16 v[6:21], v[94:97], v[46:49], v[6:21]
	v_max_f32_e32 v108, 0, v224
	v_max_f32_e32 v109, 0, v225
	v_fmac_f32_e32 v0, v34, v108
	v_fmac_f32_e32 v1, v35, v109
	v_max_f32_e32 v210, 0, v226
	v_max_f32_e32 v211, 0, v227
	v_fmac_f32_e32 v0, v36, v210
	v_fmac_f32_e32 v1, v37, v211
	v_add_f32_e32 v0, v0, v1
	v_ashrrev_i32_e32 v1, 31, v0
	v_mfma_f32_32x32x16_bf16 v[6:21], v[98:101], v[196:199], v[6:21]
	s_waitcnt vmcnt(10)
	v_add_u32_e32 v228, 0x10000, v5
	ds_read_b128 v[38:41], v228 offset:43264
	v_add_u32_e32 v228, 0x10000, v52
	ds_read_b128 v[42:45], v228 offset:43264
	v_add_u32_e32 v228, 0x10000, v55
	ds_read_b128 v[46:49], v228 offset:43264
	v_add_u32_e32 v228, 0x10000, v56
	ds_read_b128 v[196:199], v228 offset:43264
	v_or_b32_e32 v1, 0x80000000, v1
	s_cmpk_gt_i32 s11, 112
	s_cselect_b64 vcc, -1, 0
	v_xor_b32_e32 v0, v1, v0
	v_cndmask_b32_e32 v147, v123, v0, vcc
	s_nop 3
	s_waitcnt lgkmcnt(3)
	v_mfma_f32_32x32x16_bf16 v[212:227], v[70:73], v[38:41], 0
	v_max_f32_e32 v108, 0, v6
	v_max_f32_e32 v109, 0, v7
	v_mul_f32_e32 v50, v244, v108
	v_mul_f32_e32 v51, v245, v109
	v_max_f32_e32 v210, 0, v8
	v_max_f32_e32 v211, 0, v9
	v_fmac_f32_e32 v50, v246, v210
	v_fmac_f32_e32 v51, v247, v211
	v_max_f32_e32 v108, 0, v10
	v_max_f32_e32 v109, 0, v11
	v_fmac_f32_e32 v50, v248, v108
	v_fmac_f32_e32 v51, v249, v109
	s_waitcnt lgkmcnt(2)
	v_mfma_f32_32x32x16_bf16 v[212:227], v[74:77], v[42:45], v[212:227]
	v_max_f32_e32 v210, 0, v12
	v_max_f32_e32 v211, 0, v13
	v_fmac_f32_e32 v50, v250, v210
	v_fmac_f32_e32 v51, v251, v211
	v_max_f32_e32 v108, 0, v14
	v_max_f32_e32 v109, 0, v15
	v_fmac_f32_e32 v50, v252, v108
	v_fmac_f32_e32 v51, v253, v109
	v_max_f32_e32 v210, 0, v16
	v_max_f32_e32 v211, 0, v17
	v_fmac_f32_e32 v50, v254, v210
	v_fmac_f32_e32 v51, v255, v211
	s_waitcnt lgkmcnt(1)
	v_mfma_f32_32x32x16_bf16 v[212:227], v[78:81], v[46:49], v[212:227]
	v_max_f32_e32 v108, 0, v18
	v_max_f32_e32 v109, 0, v19
	v_fmac_f32_e32 v50, v200, v108
	v_fmac_f32_e32 v51, v201, v109
	v_max_f32_e32 v210, 0, v20
	v_max_f32_e32 v211, 0, v21
	v_fmac_f32_e32 v50, v202, v210
	v_fmac_f32_e32 v51, v203, v211
	v_add_f32_e32 v50, v50, v51
	v_ashrrev_i32_e32 v51, 31, v50
	s_waitcnt lgkmcnt(0)
	v_mfma_f32_32x32x16_bf16 v[212:227], v[82:85], v[196:199], v[212:227]
	v_or_b32_e32 v51, 0x80000000, v51
	s_cmpk_gt_i32 s11, 112
	s_cselect_b64 vcc, -1, 0
	v_xor_b32_e32 v50, v51, v50
	v_cndmask_b32_e32 v50, v123, v50, vcc
	global_store_dword v243, v50, s[8:9]
	s_add_i32 m0, s10, 65536
	v_mfma_f32_32x32x16_bf16 v[6:21], v[86:89], v[38:41], 0
	global_load_lds_dwordx4 v102, s[6:7]
	s_add_i32 m0, s10, 66560
	s_nop 0
	global_load_lds_dwordx4 v110, s[6:7]
	s_add_i32 m0, s10, 67584
	s_nop 0
	global_load_lds_dwordx4 v112, s[6:7]
	s_add_i32 m0, s10, 68608
	s_nop 0
	global_load_lds_dwordx4 v193, s[6:7]
	s_add_u32 s6, s6, 0x8000
	s_addc_u32 s7, s7, 0
	v_max_f32_e32 v108, 0, v212
	v_max_f32_e32 v109, 0, v213
	v_mul_f32_e32 v0, v22, v108
	v_mul_f32_e32 v1, v23, v109
	v_max_f32_e32 v210, 0, v214
	v_max_f32_e32 v211, 0, v215
	v_fmac_f32_e32 v0, v24, v210
	v_fmac_f32_e32 v1, v25, v211
	v_max_f32_e32 v108, 0, v216
	v_max_f32_e32 v109, 0, v217
	v_fmac_f32_e32 v0, v26, v108
	v_fmac_f32_e32 v1, v27, v109
	v_mfma_f32_32x32x16_bf16 v[6:21], v[90:93], v[42:45], v[6:21]
	v_max_f32_e32 v210, 0, v218
	v_max_f32_e32 v211, 0, v219
	v_fmac_f32_e32 v0, v28, v210
	v_fmac_f32_e32 v1, v29, v211
	v_max_f32_e32 v108, 0, v220
	v_max_f32_e32 v109, 0, v221
	v_fmac_f32_e32 v0, v30, v108
	v_fmac_f32_e32 v1, v31, v109
	v_max_f32_e32 v210, 0, v222
	v_max_f32_e32 v211, 0, v223
	v_fmac_f32_e32 v0, v32, v210
	v_fmac_f32_e32 v1, v33, v211
	v_mfma_f32_32x32x16_bf16 v[6:21], v[94:97], v[46:49], v[6:21]
	v_max_f32_e32 v108, 0, v224
	v_max_f32_e32 v109, 0, v225
	v_fmac_f32_e32 v0, v34, v108
	v_fmac_f32_e32 v1, v35, v109
	v_max_f32_e32 v210, 0, v226
	v_max_f32_e32 v211, 0, v227
	v_fmac_f32_e32 v0, v36, v210
	v_fmac_f32_e32 v1, v37, v211
	v_add_f32_e32 v0, v0, v1
	v_ashrrev_i32_e32 v1, 31, v0
	v_mfma_f32_32x32x16_bf16 v[6:21], v[98:101], v[196:199], v[6:21]
	s_waitcnt vmcnt(10)
	ds_read_b128 v[38:41], v5 offset:10496
	ds_read_b128 v[42:45], v52 offset:10496
	ds_read_b128 v[46:49], v55 offset:10496
	ds_read_b128 v[196:199], v56 offset:10496
	v_or_b32_e32 v1, 0x80000000, v1
	s_cmpk_gt_i32 s11, 120
	s_cselect_b64 vcc, -1, 0
	v_xor_b32_e32 v0, v1, v0
	v_cndmask_b32_e32 v136, v123, v0, vcc
	s_nop 3
	v_max_f32_e32 v108, 0, v6
	v_max_f32_e32 v109, 0, v7
	v_mul_f32_e32 v50, v244, v108
	v_mul_f32_e32 v51, v245, v109
	v_max_f32_e32 v210, 0, v8
	v_max_f32_e32 v211, 0, v9
	v_fmac_f32_e32 v50, v246, v210
	v_fmac_f32_e32 v51, v247, v211
	v_max_f32_e32 v108, 0, v10
	v_max_f32_e32 v109, 0, v11
	v_fmac_f32_e32 v50, v248, v108
	v_fmac_f32_e32 v51, v249, v109
	v_max_f32_e32 v210, 0, v12
	v_max_f32_e32 v211, 0, v13
	v_fmac_f32_e32 v50, v250, v210
	v_fmac_f32_e32 v51, v251, v211
	v_max_f32_e32 v108, 0, v14
	v_max_f32_e32 v109, 0, v15
	v_fmac_f32_e32 v50, v252, v108
	v_fmac_f32_e32 v51, v253, v109
	v_max_f32_e32 v210, 0, v16
	v_max_f32_e32 v211, 0, v17
	v_fmac_f32_e32 v50, v254, v210
	v_fmac_f32_e32 v51, v255, v211
	v_max_f32_e32 v108, 0, v18
	v_max_f32_e32 v109, 0, v19
	v_fmac_f32_e32 v50, v200, v108
	v_fmac_f32_e32 v51, v201, v109
	v_max_f32_e32 v210, 0, v20
	v_max_f32_e32 v211, 0, v21
	v_fmac_f32_e32 v50, v202, v210
	v_fmac_f32_e32 v51, v203, v211
	v_add_f32_e32 v50, v50, v51
	v_ashrrev_i32_e32 v51, 31, v50
	v_or_b32_e32 v51, 0x80000000, v51
	s_cmpk_gt_i32 s11, 120
	s_cselect_b64 vcc, -1, 0
	v_xor_b32_e32 v50, v51, v50
	v_cndmask_b32_e32 v50, v123, v50, vcc
	global_store_dword v243, v50, s[8:9] offset:2048
	s_add_u32 s8, s8, 0x1000
	s_addc_u32 s9, s9, 0
	s_cmpk_gt_i32 s81, 16
	s_cbranch_scc0 .Lix_fill_2
	s_waitcnt lgkmcnt(3)
	s_add_i32 m0, s10, 98304
	v_mfma_f32_32x32x16_bf16 v[212:227], v[70:73], v[38:41], 0
	global_load_lds_dwordx4 v102, s[6:7]
	s_waitcnt lgkmcnt(2)
	s_add_i32 m0, s10, 99328
	v_mfma_f32_32x32x16_bf16 v[212:227], v[74:77], v[42:45], v[212:227]
	global_load_lds_dwordx4 v110, s[6:7]
	s_waitcnt lgkmcnt(1)
	s_add_i32 m0, s10, 100352
	v_mfma_f32_32x32x16_bf16 v[212:227], v[78:81], v[46:49], v[212:227]
	global_load_lds_dwordx4 v112, s[6:7]
	s_waitcnt lgkmcnt(0)
	s_add_i32 m0, s10, 101376
	v_mfma_f32_32x32x16_bf16 v[212:227], v[82:85], v[196:199], v[212:227]
	global_load_lds_dwordx4 v193, s[6:7]
	s_add_u32 s6, s6, 0x8000
	s_addc_u32 s7, s7, 0
	v_mfma_f32_32x32x16_bf16 v[6:21], v[86:89], v[38:41], 0
	s_nop 7
	s_nop 2
	v_max_f32_e32 v108, 0, v212
	v_max_f32_e32 v109, 0, v213
	v_mul_f32_e32 v0, v22, v108
	v_mul_f32_e32 v1, v23, v109
	v_max_f32_e32 v210, 0, v214
	v_max_f32_e32 v211, 0, v215
	v_fmac_f32_e32 v0, v24, v210
	v_fmac_f32_e32 v1, v25, v211
	v_max_f32_e32 v108, 0, v216
	v_max_f32_e32 v109, 0, v217
	v_fmac_f32_e32 v0, v26, v108
	v_fmac_f32_e32 v1, v27, v109
	v_mfma_f32_32x32x16_bf16 v[6:21], v[90:93], v[42:45], v[6:21]
	v_max_f32_e32 v210, 0, v218
	v_max_f32_e32 v211, 0, v219
	v_fmac_f32_e32 v0, v28, v210
	v_fmac_f32_e32 v1, v29, v211
	v_max_f32_e32 v108, 0, v220
	v_max_f32_e32 v109, 0, v221
	v_fmac_f32_e32 v0, v30, v108
	v_fmac_f32_e32 v1, v31, v109
	v_max_f32_e32 v210, 0, v222
	v_max_f32_e32 v211, 0, v223
	v_fmac_f32_e32 v0, v32, v210
	v_fmac_f32_e32 v1, v33, v211
	v_mfma_f32_32x32x16_bf16 v[6:21], v[94:97], v[46:49], v[6:21]
	v_max_f32_e32 v108, 0, v224
	v_max_f32_e32 v109, 0, v225
	v_fmac_f32_e32 v0, v34, v108
	v_fmac_f32_e32 v1, v35, v109
	v_max_f32_e32 v210, 0, v226
	v_max_f32_e32 v211, 0, v227
	v_fmac_f32_e32 v0, v36, v210
	v_fmac_f32_e32 v1, v37, v211
	v_add_f32_e32 v0, v0, v1
	v_ashrrev_i32_e32 v1, 31, v0
	v_mfma_f32_32x32x16_bf16 v[6:21], v[98:101], v[196:199], v[6:21]
	s_waitcnt vmcnt(10)
	ds_read_b128 v[38:41], v5 offset:43264
	ds_read_b128 v[42:45], v52 offset:43264
	ds_read_b128 v[46:49], v55 offset:43264
	ds_read_b128 v[196:199], v56 offset:43264
	v_or_b32_e32 v1, 0x80000000, v1
	s_cmpk_gt_i32 s11, 128
	s_cselect_b64 vcc, -1, 0
	v_xor_b32_e32 v0, v1, v0
	v_cndmask_b32_e32 v149, v123, v0, vcc
	s_nop 3
	s_waitcnt lgkmcnt(3)
	v_mfma_f32_32x32x16_bf16 v[212:227], v[70:73], v[38:41], 0
	v_max_f32_e32 v108, 0, v6
	v_max_f32_e32 v109, 0, v7
	v_mul_f32_e32 v50, v244, v108
	v_mul_f32_e32 v51, v245, v109
	v_max_f32_e32 v210, 0, v8
	v_max_f32_e32 v211, 0, v9
	v_fmac_f32_e32 v50, v246, v210
	v_fmac_f32_e32 v51, v247, v211
	v_max_f32_e32 v108, 0, v10
	v_max_f32_e32 v109, 0, v11
	v_fmac_f32_e32 v50, v248, v108
	v_fmac_f32_e32 v51, v249, v109
	s_waitcnt lgkmcnt(2)
	v_mfma_f32_32x32x16_bf16 v[212:227], v[74:77], v[42:45], v[212:227]
	v_max_f32_e32 v210, 0, v12
	v_max_f32_e32 v211, 0, v13
	v_fmac_f32_e32 v50, v250, v210
	v_fmac_f32_e32 v51, v251, v211
	v_max_f32_e32 v108, 0, v14
	v_max_f32_e32 v109, 0, v15
	v_fmac_f32_e32 v50, v252, v108
	v_fmac_f32_e32 v51, v253, v109
	v_max_f32_e32 v210, 0, v16
	v_max_f32_e32 v211, 0, v17
	v_fmac_f32_e32 v50, v254, v210
	v_fmac_f32_e32 v51, v255, v211
	s_waitcnt lgkmcnt(1)
	v_mfma_f32_32x32x16_bf16 v[212:227], v[78:81], v[46:49], v[212:227]
	v_max_f32_e32 v108, 0, v18
	v_max_f32_e32 v109, 0, v19
	v_fmac_f32_e32 v50, v200, v108
	v_fmac_f32_e32 v51, v201, v109
	v_max_f32_e32 v210, 0, v20
	v_max_f32_e32 v211, 0, v21
	v_fmac_f32_e32 v50, v202, v210
	v_fmac_f32_e32 v51, v203, v211
	v_add_f32_e32 v50, v50, v51
	v_ashrrev_i32_e32 v51, 31, v50
	s_waitcnt lgkmcnt(0)
	v_mfma_f32_32x32x16_bf16 v[212:227], v[82:85], v[196:199], v[212:227]
	v_or_b32_e32 v51, 0x80000000, v51
	s_cmpk_gt_i32 s11, 128
	s_cselect_b64 vcc, -1, 0
	v_xor_b32_e32 v50, v51, v50
	v_cndmask_b32_e32 v50, v123, v50, vcc
	global_store_dword v243, v50, s[8:9]
	s_add_i32 m0, s10, 0
	v_mfma_f32_32x32x16_bf16 v[6:21], v[86:89], v[38:41], 0
	global_load_lds_dwordx4 v102, s[6:7]
	s_add_i32 m0, s10, 1024
	s_nop 0
	global_load_lds_dwordx4 v110, s[6:7]
	s_add_i32 m0, s10, 2048
	s_nop 0
	global_load_lds_dwordx4 v112, s[6:7]
	s_add_i32 m0, s10, 3072
	s_nop 0
	global_load_lds_dwordx4 v193, s[6:7]
	s_add_u32 s6, s6, 0x8000
	s_addc_u32 s7, s7, 0
	v_max_f32_e32 v108, 0, v212
	v_max_f32_e32 v109, 0, v213
	v_mul_f32_e32 v0, v22, v108
	v_mul_f32_e32 v1, v23, v109
	v_max_f32_e32 v210, 0, v214
	v_max_f32_e32 v211, 0, v215
	v_fmac_f32_e32 v0, v24, v210
	v_fmac_f32_e32 v1, v25, v211
	v_max_f32_e32 v108, 0, v216
	v_max_f32_e32 v109, 0, v217
	v_fmac_f32_e32 v0, v26, v108
	v_fmac_f32_e32 v1, v27, v109
	v_mfma_f32_32x32x16_bf16 v[6:21], v[90:93], v[42:45], v[6:21]
	v_max_f32_e32 v210, 0, v218
	v_max_f32_e32 v211, 0, v219
	v_fmac_f32_e32 v0, v28, v210
	v_fmac_f32_e32 v1, v29, v211
	v_max_f32_e32 v108, 0, v220
	v_max_f32_e32 v109, 0, v221
	v_fmac_f32_e32 v0, v30, v108
	v_fmac_f32_e32 v1, v31, v109
	v_max_f32_e32 v210, 0, v222
	v_max_f32_e32 v211, 0, v223
	v_fmac_f32_e32 v0, v32, v210
	v_fmac_f32_e32 v1, v33, v211
	v_mfma_f32_32x32x16_bf16 v[6:21], v[94:97], v[46:49], v[6:21]
	v_max_f32_e32 v108, 0, v224
	v_max_f32_e32 v109, 0, v225
	v_fmac_f32_e32 v0, v34, v108
	v_fmac_f32_e32 v1, v35, v109
	v_max_f32_e32 v210, 0, v226
	v_max_f32_e32 v211, 0, v227
	v_fmac_f32_e32 v0, v36, v210
	v_fmac_f32_e32 v1, v37, v211
	v_add_f32_e32 v0, v0, v1
	v_ashrrev_i32_e32 v1, 31, v0
	v_mfma_f32_32x32x16_bf16 v[6:21], v[98:101], v[196:199], v[6:21]
	s_waitcnt vmcnt(10)
	v_add_u32_e32 v228, 0x10000, v5
	ds_read_b128 v[38:41], v228 offset:10496
	v_add_u32_e32 v228, 0x10000, v52
	ds_read_b128 v[42:45], v228 offset:10496
	v_add_u32_e32 v228, 0x10000, v55
	ds_read_b128 v[46:49], v228 offset:10496
	v_add_u32_e32 v228, 0x10000, v56
	ds_read_b128 v[196:199], v228 offset:10496
	v_or_b32_e32 v1, 0x80000000, v1
	s_cmpk_gt_i32 s11, 136
	s_cselect_b64 vcc, -1, 0
	v_xor_b32_e32 v0, v1, v0
	v_cndmask_b32_e32 v148, v123, v0, vcc
	s_nop 3
	s_waitcnt lgkmcnt(3)
	v_mfma_f32_32x32x16_bf16 v[212:227], v[70:73], v[38:41], 0
	v_max_f32_e32 v108, 0, v6
	v_max_f32_e32 v109, 0, v7
	v_mul_f32_e32 v50, v244, v108
	v_mul_f32_e32 v51, v245, v109
	v_max_f32_e32 v210, 0, v8
	v_max_f32_e32 v211, 0, v9
	v_fmac_f32_e32 v50, v246, v210
	v_fmac_f32_e32 v51, v247, v211
	v_max_f32_e32 v108, 0, v10
	v_max_f32_e32 v109, 0, v11
	v_fmac_f32_e32 v50, v248, v108
	v_fmac_f32_e32 v51, v249, v109
	s_waitcnt lgkmcnt(2)
	v_mfma_f32_32x32x16_bf16 v[212:227], v[74:77], v[42:45], v[212:227]
	v_max_f32_e32 v210, 0, v12
	v_max_f32_e32 v211, 0, v13
	v_fmac_f32_e32 v50, v250, v210
	v_fmac_f32_e32 v51, v251, v211
	v_max_f32_e32 v108, 0, v14
	v_max_f32_e32 v109, 0, v15
	v_fmac_f32_e32 v50, v252, v108
	v_fmac_f32_e32 v51, v253, v109
	v_max_f32_e32 v210, 0, v16
	v_max_f32_e32 v211, 0, v17
	v_fmac_f32_e32 v50, v254, v210
	v_fmac_f32_e32 v51, v255, v211
	s_waitcnt lgkmcnt(1)
	v_mfma_f32_32x32x16_bf16 v[212:227], v[78:81], v[46:49], v[212:227]
	v_max_f32_e32 v108, 0, v18
	v_max_f32_e32 v109, 0, v19
	v_fmac_f32_e32 v50, v200, v108
	v_fmac_f32_e32 v51, v201, v109
	v_max_f32_e32 v210, 0, v20
	v_max_f32_e32 v211, 0, v21
	v_fmac_f32_e32 v50, v202, v210
	v_fmac_f32_e32 v51, v203, v211
	v_add_f32_e32 v50, v50, v51
	v_ashrrev_i32_e32 v51, 31, v50
	s_waitcnt lgkmcnt(0)
	v_mfma_f32_32x32x16_bf16 v[212:227], v[82:85], v[196:199], v[212:227]
	v_or_b32_e32 v51, 0x80000000, v51
	s_cmpk_gt_i32 s11, 136
	s_cselect_b64 vcc, -1, 0
	v_xor_b32_e32 v50, v51, v50
	v_cndmask_b32_e32 v50, v123, v50, vcc
	global_store_dword v243, v50, s[8:9] offset:2048
	s_add_u32 s8, s8, 0x1000
	s_addc_u32 s9, s9, 0
	s_add_i32 m0, s10, 32768
	v_mfma_f32_32x32x16_bf16 v[6:21], v[86:89], v[38:41], 0
	global_load_lds_dwordx4 v102, s[6:7]
	s_add_i32 m0, s10, 33792
	s_nop 0
	global_load_lds_dwordx4 v110, s[6:7]
	s_add_i32 m0, s10, 34816
	s_nop 0
	global_load_lds_dwordx4 v112, s[6:7]
	s_add_i32 m0, s10, 35840
	s_nop 0
	global_load_lds_dwordx4 v193, s[6:7]
	s_add_u32 s6, s6, 0x8000
	s_addc_u32 s7, s7, 0
	v_max_f32_e32 v108, 0, v212
	v_max_f32_e32 v109, 0, v213
	v_mul_f32_e32 v0, v22, v108
	v_mul_f32_e32 v1, v23, v109
	v_max_f32_e32 v210, 0, v214
	v_max_f32_e32 v211, 0, v215
	v_fmac_f32_e32 v0, v24, v210
	v_fmac_f32_e32 v1, v25, v211
	v_max_f32_e32 v108, 0, v216
	v_max_f32_e32 v109, 0, v217
	v_fmac_f32_e32 v0, v26, v108
	v_fmac_f32_e32 v1, v27, v109
	v_mfma_f32_32x32x16_bf16 v[6:21], v[90:93], v[42:45], v[6:21]
	v_max_f32_e32 v210, 0, v218
	v_max_f32_e32 v211, 0, v219
	v_fmac_f32_e32 v0, v28, v210
	v_fmac_f32_e32 v1, v29, v211
	v_max_f32_e32 v108, 0, v220
	v_max_f32_e32 v109, 0, v221
	v_fmac_f32_e32 v0, v30, v108
	v_fmac_f32_e32 v1, v31, v109
	v_max_f32_e32 v210, 0, v222
	v_max_f32_e32 v211, 0, v223
	v_fmac_f32_e32 v0, v32, v210
	v_fmac_f32_e32 v1, v33, v211
	v_mfma_f32_32x32x16_bf16 v[6:21], v[94:97], v[46:49], v[6:21]
	v_max_f32_e32 v108, 0, v224
	v_max_f32_e32 v109, 0, v225
	v_fmac_f32_e32 v0, v34, v108
	v_fmac_f32_e32 v1, v35, v109
	v_max_f32_e32 v210, 0, v226
	v_max_f32_e32 v211, 0, v227
	v_fmac_f32_e32 v0, v36, v210
	v_fmac_f32_e32 v1, v37, v211
	v_add_f32_e32 v0, v0, v1
	v_ashrrev_i32_e32 v1, 31, v0
	v_mfma_f32_32x32x16_bf16 v[6:21], v[98:101], v[196:199], v[6:21]
	s_waitcnt vmcnt(10)
	v_add_u32_e32 v228, 0x10000, v5
	ds_read_b128 v[38:41], v228 offset:43264
	v_add_u32_e32 v228, 0x10000, v52
	ds_read_b128 v[42:45], v228 offset:43264
	v_add_u32_e32 v228, 0x10000, v55
	ds_read_b128 v[46:49], v228 offset:43264
	v_add_u32_e32 v228, 0x10000, v56
	ds_read_b128 v[196:199], v228 offset:43264
	v_or_b32_e32 v1, 0x80000000, v1
	s_cmpk_gt_i32 s11, 144
	s_cselect_b64 vcc, -1, 0
	v_xor_b32_e32 v0, v1, v0
	v_cndmask_b32_e32 v151, v123, v0, vcc
	s_nop 3
	s_waitcnt lgkmcnt(3)
	v_mfma_f32_32x32x16_bf16 v[212:227], v[70:73], v[38:41], 0
	v_max_f32_e32 v108, 0, v6
	v_max_f32_e32 v109, 0, v7
	v_mul_f32_e32 v50, v244, v108
	v_mul_f32_e32 v51, v245, v109
	v_max_f32_e32 v210, 0, v8
	v_max_f32_e32 v211, 0, v9
	v_fmac_f32_e32 v50, v246, v210
	v_fmac_f32_e32 v51, v247, v211
	v_max_f32_e32 v108, 0, v10
	v_max_f32_e32 v109, 0, v11
	v_fmac_f32_e32 v50, v248, v108
	v_fmac_f32_e32 v51, v249, v109
	s_waitcnt lgkmcnt(2)
	v_mfma_f32_32x32x16_bf16 v[212:227], v[74:77], v[42:45], v[212:227]
	v_max_f32_e32 v210, 0, v12
	v_max_f32_e32 v211, 0, v13
	v_fmac_f32_e32 v50, v250, v210
	v_fmac_f32_e32 v51, v251, v211
	v_max_f32_e32 v108, 0, v14
	v_max_f32_e32 v109, 0, v15
	v_fmac_f32_e32 v50, v252, v108
	v_fmac_f32_e32 v51, v253, v109
	v_max_f32_e32 v210, 0, v16
	v_max_f32_e32 v211, 0, v17
	v_fmac_f32_e32 v50, v254, v210
	v_fmac_f32_e32 v51, v255, v211
	s_waitcnt lgkmcnt(1)
	v_mfma_f32_32x32x16_bf16 v[212:227], v[78:81], v[46:49], v[212:227]
	v_max_f32_e32 v108, 0, v18
	v_max_f32_e32 v109, 0, v19
	v_fmac_f32_e32 v50, v200, v108
	v_fmac_f32_e32 v51, v201, v109
	v_max_f32_e32 v210, 0, v20
	v_max_f32_e32 v211, 0, v21
	v_fmac_f32_e32 v50, v202, v210
	v_fmac_f32_e32 v51, v203, v211
	v_add_f32_e32 v50, v50, v51
	v_ashrrev_i32_e32 v51, 31, v50
	s_waitcnt lgkmcnt(0)
	v_mfma_f32_32x32x16_bf16 v[212:227], v[82:85], v[196:199], v[212:227]
	v_or_b32_e32 v51, 0x80000000, v51
	s_cmpk_gt_i32 s11, 144
	s_cselect_b64 vcc, -1, 0
	v_xor_b32_e32 v50, v51, v50
	v_cndmask_b32_e32 v50, v123, v50, vcc
	global_store_dword v243, v50, s[8:9]
	s_add_i32 m0, s10, 65536
	v_mfma_f32_32x32x16_bf16 v[6:21], v[86:89], v[38:41], 0
	global_load_lds_dwordx4 v102, s[6:7]
	s_add_i32 m0, s10, 66560
	s_nop 0
	global_load_lds_dwordx4 v110, s[6:7]
	s_add_i32 m0, s10, 67584
	s_nop 0
	global_load_lds_dwordx4 v112, s[6:7]
	s_add_i32 m0, s10, 68608
	s_nop 0
	global_load_lds_dwordx4 v193, s[6:7]
	s_add_u32 s6, s6, 0x8000
	s_addc_u32 s7, s7, 0
	v_max_f32_e32 v108, 0, v212
	v_max_f32_e32 v109, 0, v213
	v_mul_f32_e32 v0, v22, v108
	v_mul_f32_e32 v1, v23, v109
	v_max_f32_e32 v210, 0, v214
	v_max_f32_e32 v211, 0, v215
	v_fmac_f32_e32 v0, v24, v210
	v_fmac_f32_e32 v1, v25, v211
	v_max_f32_e32 v108, 0, v216
	v_max_f32_e32 v109, 0, v217
	v_fmac_f32_e32 v0, v26, v108
	v_fmac_f32_e32 v1, v27, v109
	v_mfma_f32_32x32x16_bf16 v[6:21], v[90:93], v[42:45], v[6:21]
	v_max_f32_e32 v210, 0, v218
	v_max_f32_e32 v211, 0, v219
	v_fmac_f32_e32 v0, v28, v210
	v_fmac_f32_e32 v1, v29, v211
	v_max_f32_e32 v108, 0, v220
	v_max_f32_e32 v109, 0, v221
	v_fmac_f32_e32 v0, v30, v108
	v_fmac_f32_e32 v1, v31, v109
	v_max_f32_e32 v210, 0, v222
	v_max_f32_e32 v211, 0, v223
	v_fmac_f32_e32 v0, v32, v210
	v_fmac_f32_e32 v1, v33, v211
	v_mfma_f32_32x32x16_bf16 v[6:21], v[94:97], v[46:49], v[6:21]
	v_max_f32_e32 v108, 0, v224
	v_max_f32_e32 v109, 0, v225
	v_fmac_f32_e32 v0, v34, v108
	v_fmac_f32_e32 v1, v35, v109
	v_max_f32_e32 v210, 0, v226
	v_max_f32_e32 v211, 0, v227
	v_fmac_f32_e32 v0, v36, v210
	v_fmac_f32_e32 v1, v37, v211
	v_add_f32_e32 v0, v0, v1
	v_ashrrev_i32_e32 v1, 31, v0
	v_mfma_f32_32x32x16_bf16 v[6:21], v[98:101], v[196:199], v[6:21]
	s_waitcnt vmcnt(10)
	ds_read_b128 v[38:41], v5 offset:10496
	ds_read_b128 v[42:45], v52 offset:10496
	ds_read_b128 v[46:49], v55 offset:10496
	ds_read_b128 v[196:199], v56 offset:10496
	v_or_b32_e32 v1, 0x80000000, v1
	s_cmpk_gt_i32 s11, 152
	s_cselect_b64 vcc, -1, 0
	v_xor_b32_e32 v0, v1, v0
	v_cndmask_b32_e32 v150, v123, v0, vcc
	s_nop 3
	s_waitcnt lgkmcnt(3)
	v_mfma_f32_32x32x16_bf16 v[212:227], v[70:73], v[38:41], 0
	v_max_f32_e32 v108, 0, v6
	v_max_f32_e32 v109, 0, v7
	v_mul_f32_e32 v50, v244, v108
	v_mul_f32_e32 v51, v245, v109
	v_max_f32_e32 v210, 0, v8
	v_max_f32_e32 v211, 0, v9
	v_fmac_f32_e32 v50, v246, v210
	v_fmac_f32_e32 v51, v247, v211
	v_max_f32_e32 v108, 0, v10
	v_max_f32_e32 v109, 0, v11
	v_fmac_f32_e32 v50, v248, v108
	v_fmac_f32_e32 v51, v249, v109
	s_waitcnt lgkmcnt(2)
	v_mfma_f32_32x32x16_bf16 v[212:227], v[74:77], v[42:45], v[212:227]
	v_max_f32_e32 v210, 0, v12
	v_max_f32_e32 v211, 0, v13
	v_fmac_f32_e32 v50, v250, v210
	v_fmac_f32_e32 v51, v251, v211
	v_max_f32_e32 v108, 0, v14
	v_max_f32_e32 v109, 0, v15
	v_fmac_f32_e32 v50, v252, v108
	v_fmac_f32_e32 v51, v253, v109
	v_max_f32_e32 v210, 0, v16
	v_max_f32_e32 v211, 0, v17
	v_fmac_f32_e32 v50, v254, v210
	v_fmac_f32_e32 v51, v255, v211
	s_waitcnt lgkmcnt(1)
	v_mfma_f32_32x32x16_bf16 v[212:227], v[78:81], v[46:49], v[212:227]
	v_max_f32_e32 v108, 0, v18
	v_max_f32_e32 v109, 0, v19
	v_fmac_f32_e32 v50, v200, v108
	v_fmac_f32_e32 v51, v201, v109
	v_max_f32_e32 v210, 0, v20
	v_max_f32_e32 v211, 0, v21
	v_fmac_f32_e32 v50, v202, v210
	v_fmac_f32_e32 v51, v203, v211
	v_add_f32_e32 v50, v50, v51
	v_ashrrev_i32_e32 v51, 31, v50
	s_waitcnt lgkmcnt(0)
	v_mfma_f32_32x32x16_bf16 v[212:227], v[82:85], v[196:199], v[212:227]
	v_or_b32_e32 v51, 0x80000000, v51
	s_cmpk_gt_i32 s11, 152
	s_cselect_b64 vcc, -1, 0
	v_xor_b32_e32 v50, v51, v50
	v_cndmask_b32_e32 v50, v123, v50, vcc
	global_store_dword v243, v50, s[8:9] offset:2048
	s_add_u32 s8, s8, 0x1000
	s_addc_u32 s9, s9, 0
	s_add_i32 m0, s10, 98304
	v_mfma_f32_32x32x16_bf16 v[6:21], v[86:89], v[38:41], 0
	global_load_lds_dwordx4 v102, s[6:7]
	s_add_i32 m0, s10, 99328
	s_nop 0
	global_load_lds_dwordx4 v110, s[6:7]
	s_add_i32 m0, s10, 100352
	s_nop 0
	global_load_lds_dwordx4 v112, s[6:7]
	s_add_i32 m0, s10, 101376
	s_nop 0
	global_load_lds_dwordx4 v193, s[6:7]
	s_add_u32 s6, s6, 0x8000
	s_addc_u32 s7, s7, 0
	v_max_f32_e32 v108, 0, v212
	v_max_f32_e32 v109, 0, v213
	v_mul_f32_e32 v0, v22, v108
	v_mul_f32_e32 v1, v23, v109
	v_max_f32_e32 v210, 0, v214
	v_max_f32_e32 v211, 0, v215
	v_fmac_f32_e32 v0, v24, v210
	v_fmac_f32_e32 v1, v25, v211
	v_max_f32_e32 v108, 0, v216
	v_max_f32_e32 v109, 0, v217
	v_fmac_f32_e32 v0, v26, v108
	v_fmac_f32_e32 v1, v27, v109
	v_mfma_f32_32x32x16_bf16 v[6:21], v[90:93], v[42:45], v[6:21]
	v_max_f32_e32 v210, 0, v218
	v_max_f32_e32 v211, 0, v219
	v_fmac_f32_e32 v0, v28, v210
	v_fmac_f32_e32 v1, v29, v211
	v_max_f32_e32 v108, 0, v220
	v_max_f32_e32 v109, 0, v221
	v_fmac_f32_e32 v0, v30, v108
	v_fmac_f32_e32 v1, v31, v109
	v_max_f32_e32 v210, 0, v222
	v_max_f32_e32 v211, 0, v223
	v_fmac_f32_e32 v0, v32, v210
	v_fmac_f32_e32 v1, v33, v211
	v_mfma_f32_32x32x16_bf16 v[6:21], v[94:97], v[46:49], v[6:21]
	v_max_f32_e32 v108, 0, v224
	v_max_f32_e32 v109, 0, v225
	v_fmac_f32_e32 v0, v34, v108
	v_fmac_f32_e32 v1, v35, v109
	v_max_f32_e32 v210, 0, v226
	v_max_f32_e32 v211, 0, v227
	v_fmac_f32_e32 v0, v36, v210
	v_fmac_f32_e32 v1, v37, v211
	v_add_f32_e32 v0, v0, v1
	v_ashrrev_i32_e32 v1, 31, v0
	v_mfma_f32_32x32x16_bf16 v[6:21], v[98:101], v[196:199], v[6:21]
	s_waitcnt vmcnt(10)
	ds_read_b128 v[38:41], v5 offset:43264
	ds_read_b128 v[42:45], v52 offset:43264
	ds_read_b128 v[46:49], v55 offset:43264
	ds_read_b128 v[196:199], v56 offset:43264
	v_or_b32_e32 v1, 0x80000000, v1
	s_cmpk_gt_i32 s11, 160
	s_cselect_b64 vcc, -1, 0
	v_xor_b32_e32 v0, v1, v0
	v_cndmask_b32_e32 v154, v123, v0, vcc
	s_nop 3
	s_waitcnt lgkmcnt(3)
	v_mfma_f32_32x32x16_bf16 v[212:227], v[70:73], v[38:41], 0
	v_max_f32_e32 v108, 0, v6
	v_max_f32_e32 v109, 0, v7
	v_mul_f32_e32 v50, v244, v108
	v_mul_f32_e32 v51, v245, v109
	v_max_f32_e32 v210, 0, v8
	v_max_f32_e32 v211, 0, v9
	v_fmac_f32_e32 v50, v246, v210
	v_fmac_f32_e32 v51, v247, v211
	v_max_f32_e32 v108, 0, v10
	v_max_f32_e32 v109, 0, v11
	v_fmac_f32_e32 v50, v248, v108
	v_fmac_f32_e32 v51, v249, v109
	s_waitcnt lgkmcnt(2)
	v_mfma_f32_32x32x16_bf16 v[212:227], v[74:77], v[42:45], v[212:227]
	v_max_f32_e32 v210, 0, v12
	v_max_f32_e32 v211, 0, v13
	v_fmac_f32_e32 v50, v250, v210
	v_fmac_f32_e32 v51, v251, v211
	v_max_f32_e32 v108, 0, v14
	v_max_f32_e32 v109, 0, v15
	v_fmac_f32_e32 v50, v252, v108
	v_fmac_f32_e32 v51, v253, v109
	v_max_f32_e32 v210, 0, v16
	v_max_f32_e32 v211, 0, v17
	v_fmac_f32_e32 v50, v254, v210
	v_fmac_f32_e32 v51, v255, v211
	s_waitcnt lgkmcnt(1)
	v_mfma_f32_32x32x16_bf16 v[212:227], v[78:81], v[46:49], v[212:227]
	v_max_f32_e32 v108, 0, v18
	v_max_f32_e32 v109, 0, v19
	v_fmac_f32_e32 v50, v200, v108
	v_fmac_f32_e32 v51, v201, v109
	v_max_f32_e32 v210, 0, v20
	v_max_f32_e32 v211, 0, v21
	v_fmac_f32_e32 v50, v202, v210
	v_fmac_f32_e32 v51, v203, v211
	v_add_f32_e32 v50, v50, v51
	v_ashrrev_i32_e32 v51, 31, v50
	s_waitcnt lgkmcnt(0)
	v_mfma_f32_32x32x16_bf16 v[212:227], v[82:85], v[196:199], v[212:227]
	v_or_b32_e32 v51, 0x80000000, v51
	s_cmpk_gt_i32 s11, 160
	s_cselect_b64 vcc, -1, 0
	v_xor_b32_e32 v50, v51, v50
	v_cndmask_b32_e32 v50, v123, v50, vcc
	global_store_dword v243, v50, s[8:9]
	s_add_i32 m0, s10, 0
	v_mfma_f32_32x32x16_bf16 v[6:21], v[86:89], v[38:41], 0
	global_load_lds_dwordx4 v102, s[6:7]
	s_add_i32 m0, s10, 1024
	s_nop 0
	global_load_lds_dwordx4 v110, s[6:7]
	s_add_i32 m0, s10, 2048
	s_nop 0
	global_load_lds_dwordx4 v112, s[6:7]
	s_add_i32 m0, s10, 3072
	s_nop 0
	global_load_lds_dwordx4 v193, s[6:7]
	s_add_u32 s6, s6, 0x8000
	s_addc_u32 s7, s7, 0
	v_max_f32_e32 v108, 0, v212
	v_max_f32_e32 v109, 0, v213
	v_mul_f32_e32 v0, v22, v108
	v_mul_f32_e32 v1, v23, v109
	v_max_f32_e32 v210, 0, v214
	v_max_f32_e32 v211, 0, v215
	v_fmac_f32_e32 v0, v24, v210
	v_fmac_f32_e32 v1, v25, v211
	v_max_f32_e32 v108, 0, v216
	v_max_f32_e32 v109, 0, v217
	v_fmac_f32_e32 v0, v26, v108
	v_fmac_f32_e32 v1, v27, v109
	v_mfma_f32_32x32x16_bf16 v[6:21], v[90:93], v[42:45], v[6:21]
	v_max_f32_e32 v210, 0, v218
	v_max_f32_e32 v211, 0, v219
	v_fmac_f32_e32 v0, v28, v210
	v_fmac_f32_e32 v1, v29, v211
	v_max_f32_e32 v108, 0, v220
	v_max_f32_e32 v109, 0, v221
	v_fmac_f32_e32 v0, v30, v108
	v_fmac_f32_e32 v1, v31, v109
	v_max_f32_e32 v210, 0, v222
	v_max_f32_e32 v211, 0, v223
	v_fmac_f32_e32 v0, v32, v210
	v_fmac_f32_e32 v1, v33, v211
	v_mfma_f32_32x32x16_bf16 v[6:21], v[94:97], v[46:49], v[6:21]
	v_max_f32_e32 v108, 0, v224
	v_max_f32_e32 v109, 0, v225
	v_fmac_f32_e32 v0, v34, v108
	v_fmac_f32_e32 v1, v35, v109
	v_max_f32_e32 v210, 0, v226
	v_max_f32_e32 v211, 0, v227
	v_fmac_f32_e32 v0, v36, v210
	v_fmac_f32_e32 v1, v37, v211
	v_add_f32_e32 v0, v0, v1
	v_ashrrev_i32_e32 v1, 31, v0
	v_mfma_f32_32x32x16_bf16 v[6:21], v[98:101], v[196:199], v[6:21]
	s_waitcnt vmcnt(10)
	v_add_u32_e32 v228, 0x10000, v5
	ds_read_b128 v[38:41], v228 offset:10496
	v_add_u32_e32 v228, 0x10000, v52
	ds_read_b128 v[42:45], v228 offset:10496
	v_add_u32_e32 v228, 0x10000, v55
	ds_read_b128 v[46:49], v228 offset:10496
	v_add_u32_e32 v228, 0x10000, v56
	ds_read_b128 v[196:199], v228 offset:10496
	v_or_b32_e32 v1, 0x80000000, v1
	s_cmpk_gt_i32 s11, 168
	s_cselect_b64 vcc, -1, 0
	v_xor_b32_e32 v0, v1, v0
	v_cndmask_b32_e32 v153, v123, v0, vcc
	s_nop 3
	s_waitcnt lgkmcnt(3)
	v_mfma_f32_32x32x16_bf16 v[212:227], v[70:73], v[38:41], 0
	v_max_f32_e32 v108, 0, v6
	v_max_f32_e32 v109, 0, v7
	v_mul_f32_e32 v50, v244, v108
	v_mul_f32_e32 v51, v245, v109
	v_max_f32_e32 v210, 0, v8
	v_max_f32_e32 v211, 0, v9
	v_fmac_f32_e32 v50, v246, v210
	v_fmac_f32_e32 v51, v247, v211
	v_max_f32_e32 v108, 0, v10
	v_max_f32_e32 v109, 0, v11
	v_fmac_f32_e32 v50, v248, v108
	v_fmac_f32_e32 v51, v249, v109
	s_waitcnt lgkmcnt(2)
	v_mfma_f32_32x32x16_bf16 v[212:227], v[74:77], v[42:45], v[212:227]
	v_max_f32_e32 v210, 0, v12
	v_max_f32_e32 v211, 0, v13
	v_fmac_f32_e32 v50, v250, v210
	v_fmac_f32_e32 v51, v251, v211
	v_max_f32_e32 v108, 0, v14
	v_max_f32_e32 v109, 0, v15
	v_fmac_f32_e32 v50, v252, v108
	v_fmac_f32_e32 v51, v253, v109
	v_max_f32_e32 v210, 0, v16
	v_max_f32_e32 v211, 0, v17
	v_fmac_f32_e32 v50, v254, v210
	v_fmac_f32_e32 v51, v255, v211
	s_waitcnt lgkmcnt(1)
	v_mfma_f32_32x32x16_bf16 v[212:227], v[78:81], v[46:49], v[212:227]
	v_max_f32_e32 v108, 0, v18
	v_max_f32_e32 v109, 0, v19
	v_fmac_f32_e32 v50, v200, v108
	v_fmac_f32_e32 v51, v201, v109
	v_max_f32_e32 v210, 0, v20
	v_max_f32_e32 v211, 0, v21
	v_fmac_f32_e32 v50, v202, v210
	v_fmac_f32_e32 v51, v203, v211
	v_add_f32_e32 v50, v50, v51
	v_ashrrev_i32_e32 v51, 31, v50
	s_waitcnt lgkmcnt(0)
	v_mfma_f32_32x32x16_bf16 v[212:227], v[82:85], v[196:199], v[212:227]
	v_or_b32_e32 v51, 0x80000000, v51
	s_cmpk_gt_i32 s11, 168
	s_cselect_b64 vcc, -1, 0
	v_xor_b32_e32 v50, v51, v50
	v_cndmask_b32_e32 v50, v123, v50, vcc
	global_store_dword v243, v50, s[8:9] offset:2048
	s_add_u32 s8, s8, 0x1000
	s_addc_u32 s9, s9, 0
	s_add_i32 m0, s10, 32768
	v_mfma_f32_32x32x16_bf16 v[6:21], v[86:89], v[38:41], 0
	global_load_lds_dwordx4 v102, s[6:7]
	s_add_i32 m0, s10, 33792
	s_nop 0
	global_load_lds_dwordx4 v110, s[6:7]
	s_add_i32 m0, s10, 34816
	s_nop 0
	global_load_lds_dwordx4 v112, s[6:7]
	s_add_i32 m0, s10, 35840
	s_nop 0
	global_load_lds_dwordx4 v193, s[6:7]
	s_add_u32 s6, s6, 0x8000
	s_addc_u32 s7, s7, 0
	v_max_f32_e32 v108, 0, v212
	v_max_f32_e32 v109, 0, v213
	v_mul_f32_e32 v0, v22, v108
	v_mul_f32_e32 v1, v23, v109
	v_max_f32_e32 v210, 0, v214
	v_max_f32_e32 v211, 0, v215
	v_fmac_f32_e32 v0, v24, v210
	v_fmac_f32_e32 v1, v25, v211
	v_max_f32_e32 v108, 0, v216
	v_max_f32_e32 v109, 0, v217
	v_fmac_f32_e32 v0, v26, v108
	v_fmac_f32_e32 v1, v27, v109
	v_mfma_f32_32x32x16_bf16 v[6:21], v[90:93], v[42:45], v[6:21]
	v_max_f32_e32 v210, 0, v218
	v_max_f32_e32 v211, 0, v219
	v_fmac_f32_e32 v0, v28, v210
	v_fmac_f32_e32 v1, v29, v211
	v_max_f32_e32 v108, 0, v220
	v_max_f32_e32 v109, 0, v221
	v_fmac_f32_e32 v0, v30, v108
	v_fmac_f32_e32 v1, v31, v109
	v_max_f32_e32 v210, 0, v222
	v_max_f32_e32 v211, 0, v223
	v_fmac_f32_e32 v0, v32, v210
	v_fmac_f32_e32 v1, v33, v211
	v_mfma_f32_32x32x16_bf16 v[6:21], v[94:97], v[46:49], v[6:21]
	v_max_f32_e32 v108, 0, v224
	v_max_f32_e32 v109, 0, v225
	v_fmac_f32_e32 v0, v34, v108
	v_fmac_f32_e32 v1, v35, v109
	v_max_f32_e32 v210, 0, v226
	v_max_f32_e32 v211, 0, v227
	v_fmac_f32_e32 v0, v36, v210
	v_fmac_f32_e32 v1, v37, v211
	v_add_f32_e32 v0, v0, v1
	v_ashrrev_i32_e32 v1, 31, v0
	v_mfma_f32_32x32x16_bf16 v[6:21], v[98:101], v[196:199], v[6:21]
	s_waitcnt vmcnt(10)
	v_add_u32_e32 v228, 0x10000, v5
	ds_read_b128 v[38:41], v228 offset:43264
	v_add_u32_e32 v228, 0x10000, v52
	ds_read_b128 v[42:45], v228 offset:43264
	v_add_u32_e32 v228, 0x10000, v55
	ds_read_b128 v[46:49], v228 offset:43264
	v_add_u32_e32 v228, 0x10000, v56
	ds_read_b128 v[196:199], v228 offset:43264
	v_or_b32_e32 v1, 0x80000000, v1
	s_cmpk_gt_i32 s11, 176
	s_cselect_b64 vcc, -1, 0
	v_xor_b32_e32 v0, v1, v0
	v_cndmask_b32_e32 v156, v123, v0, vcc
	s_nop 3
	s_waitcnt lgkmcnt(3)
	v_mfma_f32_32x32x16_bf16 v[212:227], v[70:73], v[38:41], 0
	v_max_f32_e32 v108, 0, v6
	v_max_f32_e32 v109, 0, v7
	v_mul_f32_e32 v50, v244, v108
	v_mul_f32_e32 v51, v245, v109
	v_max_f32_e32 v210, 0, v8
	v_max_f32_e32 v211, 0, v9
	v_fmac_f32_e32 v50, v246, v210
	v_fmac_f32_e32 v51, v247, v211
	v_max_f32_e32 v108, 0, v10
	v_max_f32_e32 v109, 0, v11
	v_fmac_f32_e32 v50, v248, v108
	v_fmac_f32_e32 v51, v249, v109
	s_waitcnt lgkmcnt(2)
	v_mfma_f32_32x32x16_bf16 v[212:227], v[74:77], v[42:45], v[212:227]
	v_max_f32_e32 v210, 0, v12
	v_max_f32_e32 v211, 0, v13
	v_fmac_f32_e32 v50, v250, v210
	v_fmac_f32_e32 v51, v251, v211
	v_max_f32_e32 v108, 0, v14
	v_max_f32_e32 v109, 0, v15
	v_fmac_f32_e32 v50, v252, v108
	v_fmac_f32_e32 v51, v253, v109
	v_max_f32_e32 v210, 0, v16
	v_max_f32_e32 v211, 0, v17
	v_fmac_f32_e32 v50, v254, v210
	v_fmac_f32_e32 v51, v255, v211
	s_waitcnt lgkmcnt(1)
	v_mfma_f32_32x32x16_bf16 v[212:227], v[78:81], v[46:49], v[212:227]
	v_max_f32_e32 v108, 0, v18
	v_max_f32_e32 v109, 0, v19
	v_fmac_f32_e32 v50, v200, v108
	v_fmac_f32_e32 v51, v201, v109
	v_max_f32_e32 v210, 0, v20
	v_max_f32_e32 v211, 0, v21
	v_fmac_f32_e32 v50, v202, v210
	v_fmac_f32_e32 v51, v203, v211
	v_add_f32_e32 v50, v50, v51
	v_ashrrev_i32_e32 v51, 31, v50
	s_waitcnt lgkmcnt(0)
	v_mfma_f32_32x32x16_bf16 v[212:227], v[82:85], v[196:199], v[212:227]
	v_or_b32_e32 v51, 0x80000000, v51
	s_cmpk_gt_i32 s11, 176
	s_cselect_b64 vcc, -1, 0
	v_xor_b32_e32 v50, v51, v50
	v_cndmask_b32_e32 v50, v123, v50, vcc
	global_store_dword v243, v50, s[8:9]
	s_add_i32 m0, s10, 65536
	v_mfma_f32_32x32x16_bf16 v[6:21], v[86:89], v[38:41], 0
	global_load_lds_dwordx4 v102, s[6:7]
	s_add_i32 m0, s10, 66560
	s_nop 0
	global_load_lds_dwordx4 v110, s[6:7]
	s_add_i32 m0, s10, 67584
	s_nop 0
	global_load_lds_dwordx4 v112, s[6:7]
	s_add_i32 m0, s10, 68608
	s_nop 0
	global_load_lds_dwordx4 v193, s[6:7]
	s_add_u32 s6, s6, 0x8000
	s_addc_u32 s7, s7, 0
	v_max_f32_e32 v108, 0, v212
	v_max_f32_e32 v109, 0, v213
	v_mul_f32_e32 v0, v22, v108
	v_mul_f32_e32 v1, v23, v109
	v_max_f32_e32 v210, 0, v214
	v_max_f32_e32 v211, 0, v215
	v_fmac_f32_e32 v0, v24, v210
	v_fmac_f32_e32 v1, v25, v211
	v_max_f32_e32 v108, 0, v216
	v_max_f32_e32 v109, 0, v217
	v_fmac_f32_e32 v0, v26, v108
	v_fmac_f32_e32 v1, v27, v109
	v_mfma_f32_32x32x16_bf16 v[6:21], v[90:93], v[42:45], v[6:21]
	v_max_f32_e32 v210, 0, v218
	v_max_f32_e32 v211, 0, v219
	v_fmac_f32_e32 v0, v28, v210
	v_fmac_f32_e32 v1, v29, v211
	v_max_f32_e32 v108, 0, v220
	v_max_f32_e32 v109, 0, v221
	v_fmac_f32_e32 v0, v30, v108
	v_fmac_f32_e32 v1, v31, v109
	v_max_f32_e32 v210, 0, v222
	v_max_f32_e32 v211, 0, v223
	v_fmac_f32_e32 v0, v32, v210
	v_fmac_f32_e32 v1, v33, v211
	v_mfma_f32_32x32x16_bf16 v[6:21], v[94:97], v[46:49], v[6:21]
	v_max_f32_e32 v108, 0, v224
	v_max_f32_e32 v109, 0, v225
	v_fmac_f32_e32 v0, v34, v108
	v_fmac_f32_e32 v1, v35, v109
	v_max_f32_e32 v210, 0, v226
	v_max_f32_e32 v211, 0, v227
	v_fmac_f32_e32 v0, v36, v210
	v_fmac_f32_e32 v1, v37, v211
	v_add_f32_e32 v0, v0, v1
	v_ashrrev_i32_e32 v1, 31, v0
	v_mfma_f32_32x32x16_bf16 v[6:21], v[98:101], v[196:199], v[6:21]
	s_waitcnt vmcnt(10)
	ds_read_b128 v[38:41], v5 offset:10496
	ds_read_b128 v[42:45], v52 offset:10496
	ds_read_b128 v[46:49], v55 offset:10496
	ds_read_b128 v[196:199], v56 offset:10496
	v_or_b32_e32 v1, 0x80000000, v1
	s_cmpk_gt_i32 s11, 184
	s_cselect_b64 vcc, -1, 0
	v_xor_b32_e32 v0, v1, v0
	v_cndmask_b32_e32 v155, v123, v0, vcc
	s_nop 3
	v_max_f32_e32 v108, 0, v6
	v_max_f32_e32 v109, 0, v7
	v_mul_f32_e32 v50, v244, v108
	v_mul_f32_e32 v51, v245, v109
	v_max_f32_e32 v210, 0, v8
	v_max_f32_e32 v211, 0, v9
	v_fmac_f32_e32 v50, v246, v210
	v_fmac_f32_e32 v51, v247, v211
	v_max_f32_e32 v108, 0, v10
	v_max_f32_e32 v109, 0, v11
	v_fmac_f32_e32 v50, v248, v108
	v_fmac_f32_e32 v51, v249, v109
	v_max_f32_e32 v210, 0, v12
	v_max_f32_e32 v211, 0, v13
	v_fmac_f32_e32 v50, v250, v210
	v_fmac_f32_e32 v51, v251, v211
	v_max_f32_e32 v108, 0, v14
	v_max_f32_e32 v109, 0, v15
	v_fmac_f32_e32 v50, v252, v108
	v_fmac_f32_e32 v51, v253, v109
	v_max_f32_e32 v210, 0, v16
	v_max_f32_e32 v211, 0, v17
	v_fmac_f32_e32 v50, v254, v210
	v_fmac_f32_e32 v51, v255, v211
	v_max_f32_e32 v108, 0, v18
	v_max_f32_e32 v109, 0, v19
	v_fmac_f32_e32 v50, v200, v108
	v_fmac_f32_e32 v51, v201, v109
	v_max_f32_e32 v210, 0, v20
	v_max_f32_e32 v211, 0, v21
	v_fmac_f32_e32 v50, v202, v210
	v_fmac_f32_e32 v51, v203, v211
	v_add_f32_e32 v50, v50, v51
	v_ashrrev_i32_e32 v51, 31, v50
	v_or_b32_e32 v51, 0x80000000, v51
	s_cmpk_gt_i32 s11, 184
	s_cselect_b64 vcc, -1, 0
	v_xor_b32_e32 v50, v51, v50
	v_cndmask_b32_e32 v50, v123, v50, vcc
	global_store_dword v243, v50, s[8:9] offset:2048
	s_add_u32 s8, s8, 0x1000
	s_addc_u32 s9, s9, 0
	s_cmpk_gt_i32 s81, 24
	s_cbranch_scc0 .Lix_fill_3
	s_waitcnt lgkmcnt(3)
	s_add_i32 m0, s10, 98304
	v_mfma_f32_32x32x16_bf16 v[212:227], v[70:73], v[38:41], 0
	global_load_lds_dwordx4 v102, s[6:7]
	s_waitcnt lgkmcnt(2)
	s_add_i32 m0, s10, 99328
	v_mfma_f32_32x32x16_bf16 v[212:227], v[74:77], v[42:45], v[212:227]
	global_load_lds_dwordx4 v110, s[6:7]
	s_waitcnt lgkmcnt(1)
	s_add_i32 m0, s10, 100352
	v_mfma_f32_32x32x16_bf16 v[212:227], v[78:81], v[46:49], v[212:227]
	global_load_lds_dwordx4 v112, s[6:7]
	s_waitcnt lgkmcnt(0)
	s_add_i32 m0, s10, 101376
	v_mfma_f32_32x32x16_bf16 v[212:227], v[82:85], v[196:199], v[212:227]
	global_load_lds_dwordx4 v193, s[6:7]
	s_add_u32 s6, s6, 0x8000
	s_addc_u32 s7, s7, 0
	v_mfma_f32_32x32x16_bf16 v[6:21], v[86:89], v[38:41], 0
	s_nop 7
	s_nop 2
	v_max_f32_e32 v108, 0, v212
	v_max_f32_e32 v109, 0, v213
	v_mul_f32_e32 v0, v22, v108
	v_mul_f32_e32 v1, v23, v109
	v_max_f32_e32 v210, 0, v214
	v_max_f32_e32 v211, 0, v215
	v_fmac_f32_e32 v0, v24, v210
	v_fmac_f32_e32 v1, v25, v211
	v_max_f32_e32 v108, 0, v216
	v_max_f32_e32 v109, 0, v217
	v_fmac_f32_e32 v0, v26, v108
	v_fmac_f32_e32 v1, v27, v109
	v_mfma_f32_32x32x16_bf16 v[6:21], v[90:93], v[42:45], v[6:21]
	v_max_f32_e32 v210, 0, v218
	v_max_f32_e32 v211, 0, v219
	v_fmac_f32_e32 v0, v28, v210
	v_fmac_f32_e32 v1, v29, v211
	v_max_f32_e32 v108, 0, v220
	v_max_f32_e32 v109, 0, v221
	v_fmac_f32_e32 v0, v30, v108
	v_fmac_f32_e32 v1, v31, v109
	v_max_f32_e32 v210, 0, v222
	v_max_f32_e32 v211, 0, v223
	v_fmac_f32_e32 v0, v32, v210
	v_fmac_f32_e32 v1, v33, v211
	v_mfma_f32_32x32x16_bf16 v[6:21], v[94:97], v[46:49], v[6:21]
	v_max_f32_e32 v108, 0, v224
	v_max_f32_e32 v109, 0, v225
	v_fmac_f32_e32 v0, v34, v108
	v_fmac_f32_e32 v1, v35, v109
	v_max_f32_e32 v210, 0, v226
	v_max_f32_e32 v211, 0, v227
	v_fmac_f32_e32 v0, v36, v210
	v_fmac_f32_e32 v1, v37, v211
	v_add_f32_e32 v0, v0, v1
	v_ashrrev_i32_e32 v1, 31, v0
	v_mfma_f32_32x32x16_bf16 v[6:21], v[98:101], v[196:199], v[6:21]
	s_waitcnt vmcnt(10)
	ds_read_b128 v[38:41], v5 offset:43264
	ds_read_b128 v[42:45], v52 offset:43264
	ds_read_b128 v[46:49], v55 offset:43264
	ds_read_b128 v[196:199], v56 offset:43264
	v_or_b32_e32 v1, 0x80000000, v1
	s_cmpk_gt_i32 s11, 192
	s_cselect_b64 vcc, -1, 0
	v_xor_b32_e32 v0, v1, v0
	v_cndmask_b32_e32 v158, v123, v0, vcc
	s_nop 3
	s_waitcnt lgkmcnt(3)
	v_mfma_f32_32x32x16_bf16 v[212:227], v[70:73], v[38:41], 0
	v_max_f32_e32 v108, 0, v6
	v_max_f32_e32 v109, 0, v7
	v_mul_f32_e32 v50, v244, v108
	v_mul_f32_e32 v51, v245, v109
	v_max_f32_e32 v210, 0, v8
	v_max_f32_e32 v211, 0, v9
	v_fmac_f32_e32 v50, v246, v210
	v_fmac_f32_e32 v51, v247, v211
	v_max_f32_e32 v108, 0, v10
	v_max_f32_e32 v109, 0, v11
	v_fmac_f32_e32 v50, v248, v108
	v_fmac_f32_e32 v51, v249, v109
	s_waitcnt lgkmcnt(2)
	v_mfma_f32_32x32x16_bf16 v[212:227], v[74:77], v[42:45], v[212:227]
	v_max_f32_e32 v210, 0, v12
	v_max_f32_e32 v211, 0, v13
	v_fmac_f32_e32 v50, v250, v210
	v_fmac_f32_e32 v51, v251, v211
	v_max_f32_e32 v108, 0, v14
	v_max_f32_e32 v109, 0, v15
	v_fmac_f32_e32 v50, v252, v108
	v_fmac_f32_e32 v51, v253, v109
	v_max_f32_e32 v210, 0, v16
	v_max_f32_e32 v211, 0, v17
	v_fmac_f32_e32 v50, v254, v210
	v_fmac_f32_e32 v51, v255, v211
	s_waitcnt lgkmcnt(1)
	v_mfma_f32_32x32x16_bf16 v[212:227], v[78:81], v[46:49], v[212:227]
	v_max_f32_e32 v108, 0, v18
	v_max_f32_e32 v109, 0, v19
	v_fmac_f32_e32 v50, v200, v108
	v_fmac_f32_e32 v51, v201, v109
	v_max_f32_e32 v210, 0, v20
	v_max_f32_e32 v211, 0, v21
	v_fmac_f32_e32 v50, v202, v210
	v_fmac_f32_e32 v51, v203, v211
	v_add_f32_e32 v50, v50, v51
	v_ashrrev_i32_e32 v51, 31, v50
	s_waitcnt lgkmcnt(0)
	v_mfma_f32_32x32x16_bf16 v[212:227], v[82:85], v[196:199], v[212:227]
	v_or_b32_e32 v51, 0x80000000, v51
	s_cmpk_gt_i32 s11, 192
	s_cselect_b64 vcc, -1, 0
	v_xor_b32_e32 v50, v51, v50
	v_cndmask_b32_e32 v50, v123, v50, vcc
	global_store_dword v243, v50, s[8:9]
	s_add_i32 m0, s10, 0
	v_mfma_f32_32x32x16_bf16 v[6:21], v[86:89], v[38:41], 0
	global_load_lds_dwordx4 v102, s[6:7]
	s_add_i32 m0, s10, 1024
	s_nop 0
	global_load_lds_dwordx4 v110, s[6:7]
	s_add_i32 m0, s10, 2048
	s_nop 0
	global_load_lds_dwordx4 v112, s[6:7]
	s_add_i32 m0, s10, 3072
	s_nop 0
	global_load_lds_dwordx4 v193, s[6:7]
	s_add_u32 s6, s6, 0x8000
	s_addc_u32 s7, s7, 0
	v_max_f32_e32 v108, 0, v212
	v_max_f32_e32 v109, 0, v213
	v_mul_f32_e32 v0, v22, v108
	v_mul_f32_e32 v1, v23, v109
	v_max_f32_e32 v210, 0, v214
	v_max_f32_e32 v211, 0, v215
	v_fmac_f32_e32 v0, v24, v210
	v_fmac_f32_e32 v1, v25, v211
	v_max_f32_e32 v108, 0, v216
	v_max_f32_e32 v109, 0, v217
	v_fmac_f32_e32 v0, v26, v108
	v_fmac_f32_e32 v1, v27, v109
	v_mfma_f32_32x32x16_bf16 v[6:21], v[90:93], v[42:45], v[6:21]
	v_max_f32_e32 v210, 0, v218
	v_max_f32_e32 v211, 0, v219
	v_fmac_f32_e32 v0, v28, v210
	v_fmac_f32_e32 v1, v29, v211
	v_max_f32_e32 v108, 0, v220
	v_max_f32_e32 v109, 0, v221
	v_fmac_f32_e32 v0, v30, v108
	v_fmac_f32_e32 v1, v31, v109
	v_max_f32_e32 v210, 0, v222
	v_max_f32_e32 v211, 0, v223
	v_fmac_f32_e32 v0, v32, v210
	v_fmac_f32_e32 v1, v33, v211
	v_mfma_f32_32x32x16_bf16 v[6:21], v[94:97], v[46:49], v[6:21]
	v_max_f32_e32 v108, 0, v224
	v_max_f32_e32 v109, 0, v225
	v_fmac_f32_e32 v0, v34, v108
	v_fmac_f32_e32 v1, v35, v109
	v_max_f32_e32 v210, 0, v226
	v_max_f32_e32 v211, 0, v227
	v_fmac_f32_e32 v0, v36, v210
	v_fmac_f32_e32 v1, v37, v211
	v_add_f32_e32 v0, v0, v1
	v_ashrrev_i32_e32 v1, 31, v0
	v_mfma_f32_32x32x16_bf16 v[6:21], v[98:101], v[196:199], v[6:21]
	s_waitcnt vmcnt(10)
	v_add_u32_e32 v228, 0x10000, v5
	ds_read_b128 v[38:41], v228 offset:10496
	v_add_u32_e32 v228, 0x10000, v52
	ds_read_b128 v[42:45], v228 offset:10496
	v_add_u32_e32 v228, 0x10000, v55
	ds_read_b128 v[46:49], v228 offset:10496
	v_add_u32_e32 v228, 0x10000, v56
	ds_read_b128 v[196:199], v228 offset:10496
	v_or_b32_e32 v1, 0x80000000, v1
	s_cmpk_gt_i32 s11, 200
	s_cselect_b64 vcc, -1, 0
	v_xor_b32_e32 v0, v1, v0
	v_cndmask_b32_e32 v157, v123, v0, vcc
	s_nop 3
	s_waitcnt lgkmcnt(3)
	v_mfma_f32_32x32x16_bf16 v[212:227], v[70:73], v[38:41], 0
	v_max_f32_e32 v108, 0, v6
	v_max_f32_e32 v109, 0, v7
	v_mul_f32_e32 v50, v244, v108
	v_mul_f32_e32 v51, v245, v109
	v_max_f32_e32 v210, 0, v8
	v_max_f32_e32 v211, 0, v9
	v_fmac_f32_e32 v50, v246, v210
	v_fmac_f32_e32 v51, v247, v211
	v_max_f32_e32 v108, 0, v10
	v_max_f32_e32 v109, 0, v11
	v_fmac_f32_e32 v50, v248, v108
	v_fmac_f32_e32 v51, v249, v109
	s_waitcnt lgkmcnt(2)
	v_mfma_f32_32x32x16_bf16 v[212:227], v[74:77], v[42:45], v[212:227]
	v_max_f32_e32 v210, 0, v12
	v_max_f32_e32 v211, 0, v13
	v_fmac_f32_e32 v50, v250, v210
	v_fmac_f32_e32 v51, v251, v211
	v_max_f32_e32 v108, 0, v14
	v_max_f32_e32 v109, 0, v15
	v_fmac_f32_e32 v50, v252, v108
	v_fmac_f32_e32 v51, v253, v109
	v_max_f32_e32 v210, 0, v16
	v_max_f32_e32 v211, 0, v17
	v_fmac_f32_e32 v50, v254, v210
	v_fmac_f32_e32 v51, v255, v211
	s_waitcnt lgkmcnt(1)
	v_mfma_f32_32x32x16_bf16 v[212:227], v[78:81], v[46:49], v[212:227]
	v_max_f32_e32 v108, 0, v18
	v_max_f32_e32 v109, 0, v19
	v_fmac_f32_e32 v50, v200, v108
	v_fmac_f32_e32 v51, v201, v109
	v_max_f32_e32 v210, 0, v20
	v_max_f32_e32 v211, 0, v21
	v_fmac_f32_e32 v50, v202, v210
	v_fmac_f32_e32 v51, v203, v211
	v_add_f32_e32 v50, v50, v51
	v_ashrrev_i32_e32 v51, 31, v50
	s_waitcnt lgkmcnt(0)
	v_mfma_f32_32x32x16_bf16 v[212:227], v[82:85], v[196:199], v[212:227]
	v_or_b32_e32 v51, 0x80000000, v51
	s_cmpk_gt_i32 s11, 200
	s_cselect_b64 vcc, -1, 0
	v_xor_b32_e32 v50, v51, v50
	v_cndmask_b32_e32 v50, v123, v50, vcc
	global_store_dword v243, v50, s[8:9] offset:2048
	s_add_u32 s8, s8, 0x1000
	s_addc_u32 s9, s9, 0
	s_add_i32 m0, s10, 32768
	v_mfma_f32_32x32x16_bf16 v[6:21], v[86:89], v[38:41], 0
	global_load_lds_dwordx4 v102, s[6:7]
	s_add_i32 m0, s10, 33792
	s_nop 0
	global_load_lds_dwordx4 v110, s[6:7]
	s_add_i32 m0, s10, 34816
	s_nop 0
	global_load_lds_dwordx4 v112, s[6:7]
	s_add_i32 m0, s10, 35840
	s_nop 0
	global_load_lds_dwordx4 v193, s[6:7]
	s_add_u32 s6, s6, 0x8000
	s_addc_u32 s7, s7, 0
	v_max_f32_e32 v108, 0, v212
	v_max_f32_e32 v109, 0, v213
	v_mul_f32_e32 v0, v22, v108
	v_mul_f32_e32 v1, v23, v109
	v_max_f32_e32 v210, 0, v214
	v_max_f32_e32 v211, 0, v215
	v_fmac_f32_e32 v0, v24, v210
	v_fmac_f32_e32 v1, v25, v211
	v_max_f32_e32 v108, 0, v216
	v_max_f32_e32 v109, 0, v217
	v_fmac_f32_e32 v0, v26, v108
	v_fmac_f32_e32 v1, v27, v109
	v_mfma_f32_32x32x16_bf16 v[6:21], v[90:93], v[42:45], v[6:21]
	v_max_f32_e32 v210, 0, v218
	v_max_f32_e32 v211, 0, v219
	v_fmac_f32_e32 v0, v28, v210
	v_fmac_f32_e32 v1, v29, v211
	v_max_f32_e32 v108, 0, v220
	v_max_f32_e32 v109, 0, v221
	v_fmac_f32_e32 v0, v30, v108
	v_fmac_f32_e32 v1, v31, v109
	v_max_f32_e32 v210, 0, v222
	v_max_f32_e32 v211, 0, v223
	v_fmac_f32_e32 v0, v32, v210
	v_fmac_f32_e32 v1, v33, v211
	v_mfma_f32_32x32x16_bf16 v[6:21], v[94:97], v[46:49], v[6:21]
	v_max_f32_e32 v108, 0, v224
	v_max_f32_e32 v109, 0, v225
	v_fmac_f32_e32 v0, v34, v108
	v_fmac_f32_e32 v1, v35, v109
	v_max_f32_e32 v210, 0, v226
	v_max_f32_e32 v211, 0, v227
	v_fmac_f32_e32 v0, v36, v210
	v_fmac_f32_e32 v1, v37, v211
	v_add_f32_e32 v0, v0, v1
	v_ashrrev_i32_e32 v1, 31, v0
	v_mfma_f32_32x32x16_bf16 v[6:21], v[98:101], v[196:199], v[6:21]
	s_waitcnt vmcnt(10)
	v_add_u32_e32 v228, 0x10000, v5
	ds_read_b128 v[38:41], v228 offset:43264
	v_add_u32_e32 v228, 0x10000, v52
	ds_read_b128 v[42:45], v228 offset:43264
	v_add_u32_e32 v228, 0x10000, v55
	ds_read_b128 v[46:49], v228 offset:43264
	v_add_u32_e32 v228, 0x10000, v56
	ds_read_b128 v[196:199], v228 offset:43264
	v_or_b32_e32 v1, 0x80000000, v1
	s_cmpk_gt_i32 s11, 208
	s_cselect_b64 vcc, -1, 0
	v_xor_b32_e32 v0, v1, v0
	v_cndmask_b32_e32 v160, v123, v0, vcc
	s_nop 3
	s_waitcnt lgkmcnt(3)
	v_mfma_f32_32x32x16_bf16 v[212:227], v[70:73], v[38:41], 0
	v_max_f32_e32 v108, 0, v6
	v_max_f32_e32 v109, 0, v7
	v_mul_f32_e32 v50, v244, v108
	v_mul_f32_e32 v51, v245, v109
	v_max_f32_e32 v210, 0, v8
	v_max_f32_e32 v211, 0, v9
	v_fmac_f32_e32 v50, v246, v210
	v_fmac_f32_e32 v51, v247, v211
	v_max_f32_e32 v108, 0, v10
	v_max_f32_e32 v109, 0, v11
	v_fmac_f32_e32 v50, v248, v108
	v_fmac_f32_e32 v51, v249, v109
	s_waitcnt lgkmcnt(2)
	v_mfma_f32_32x32x16_bf16 v[212:227], v[74:77], v[42:45], v[212:227]
	v_max_f32_e32 v210, 0, v12
	v_max_f32_e32 v211, 0, v13
	v_fmac_f32_e32 v50, v250, v210
	v_fmac_f32_e32 v51, v251, v211
	v_max_f32_e32 v108, 0, v14
	v_max_f32_e32 v109, 0, v15
	v_fmac_f32_e32 v50, v252, v108
	v_fmac_f32_e32 v51, v253, v109
	v_max_f32_e32 v210, 0, v16
	v_max_f32_e32 v211, 0, v17
	v_fmac_f32_e32 v50, v254, v210
	v_fmac_f32_e32 v51, v255, v211
	s_waitcnt lgkmcnt(1)
	v_mfma_f32_32x32x16_bf16 v[212:227], v[78:81], v[46:49], v[212:227]
	v_max_f32_e32 v108, 0, v18
	v_max_f32_e32 v109, 0, v19
	v_fmac_f32_e32 v50, v200, v108
	v_fmac_f32_e32 v51, v201, v109
	v_max_f32_e32 v210, 0, v20
	v_max_f32_e32 v211, 0, v21
	v_fmac_f32_e32 v50, v202, v210
	v_fmac_f32_e32 v51, v203, v211
	v_add_f32_e32 v50, v50, v51
	v_ashrrev_i32_e32 v51, 31, v50
	s_waitcnt lgkmcnt(0)
	v_mfma_f32_32x32x16_bf16 v[212:227], v[82:85], v[196:199], v[212:227]
	v_or_b32_e32 v51, 0x80000000, v51
	s_cmpk_gt_i32 s11, 208
	s_cselect_b64 vcc, -1, 0
	v_xor_b32_e32 v50, v51, v50
	v_cndmask_b32_e32 v50, v123, v50, vcc
	global_store_dword v243, v50, s[8:9]
	s_add_i32 m0, s10, 65536
	v_mfma_f32_32x32x16_bf16 v[6:21], v[86:89], v[38:41], 0
	global_load_lds_dwordx4 v102, s[6:7]
	s_add_i32 m0, s10, 66560
	s_nop 0
	global_load_lds_dwordx4 v110, s[6:7]
	s_add_i32 m0, s10, 67584
	s_nop 0
	global_load_lds_dwordx4 v112, s[6:7]
	s_add_i32 m0, s10, 68608
	s_nop 0
	global_load_lds_dwordx4 v193, s[6:7]
	s_add_u32 s6, s6, 0x8000
	s_addc_u32 s7, s7, 0
	v_max_f32_e32 v108, 0, v212
	v_max_f32_e32 v109, 0, v213
	v_mul_f32_e32 v0, v22, v108
	v_mul_f32_e32 v1, v23, v109
	v_max_f32_e32 v210, 0, v214
	v_max_f32_e32 v211, 0, v215
	v_fmac_f32_e32 v0, v24, v210
	v_fmac_f32_e32 v1, v25, v211
	v_max_f32_e32 v108, 0, v216
	v_max_f32_e32 v109, 0, v217
	v_fmac_f32_e32 v0, v26, v108
	v_fmac_f32_e32 v1, v27, v109
	v_mfma_f32_32x32x16_bf16 v[6:21], v[90:93], v[42:45], v[6:21]
	v_max_f32_e32 v210, 0, v218
	v_max_f32_e32 v211, 0, v219
	v_fmac_f32_e32 v0, v28, v210
	v_fmac_f32_e32 v1, v29, v211
	v_max_f32_e32 v108, 0, v220
	v_max_f32_e32 v109, 0, v221
	v_fmac_f32_e32 v0, v30, v108
	v_fmac_f32_e32 v1, v31, v109
	v_max_f32_e32 v210, 0, v222
	v_max_f32_e32 v211, 0, v223
	v_fmac_f32_e32 v0, v32, v210
	v_fmac_f32_e32 v1, v33, v211
	v_mfma_f32_32x32x16_bf16 v[6:21], v[94:97], v[46:49], v[6:21]
	v_max_f32_e32 v108, 0, v224
	v_max_f32_e32 v109, 0, v225
	v_fmac_f32_e32 v0, v34, v108
	v_fmac_f32_e32 v1, v35, v109
	v_max_f32_e32 v210, 0, v226
	v_max_f32_e32 v211, 0, v227
	v_fmac_f32_e32 v0, v36, v210
	v_fmac_f32_e32 v1, v37, v211
	v_add_f32_e32 v0, v0, v1
	v_ashrrev_i32_e32 v1, 31, v0
	v_mfma_f32_32x32x16_bf16 v[6:21], v[98:101], v[196:199], v[6:21]
	s_waitcnt vmcnt(10)
	ds_read_b128 v[38:41], v5 offset:10496
	ds_read_b128 v[42:45], v52 offset:10496
	ds_read_b128 v[46:49], v55 offset:10496
	ds_read_b128 v[196:199], v56 offset:10496
	v_or_b32_e32 v1, 0x80000000, v1
	s_cmpk_gt_i32 s11, 216
	s_cselect_b64 vcc, -1, 0
	v_xor_b32_e32 v0, v1, v0
	v_cndmask_b32_e32 v159, v123, v0, vcc
	s_nop 3
	s_waitcnt lgkmcnt(3)
	v_mfma_f32_32x32x16_bf16 v[212:227], v[70:73], v[38:41], 0
	v_max_f32_e32 v108, 0, v6
	v_max_f32_e32 v109, 0, v7
	v_mul_f32_e32 v50, v244, v108
	v_mul_f32_e32 v51, v245, v109
	v_max_f32_e32 v210, 0, v8
	v_max_f32_e32 v211, 0, v9
	v_fmac_f32_e32 v50, v246, v210
	v_fmac_f32_e32 v51, v247, v211
	v_max_f32_e32 v108, 0, v10
	v_max_f32_e32 v109, 0, v11
	v_fmac_f32_e32 v50, v248, v108
	v_fmac_f32_e32 v51, v249, v109
	s_waitcnt lgkmcnt(2)
	v_mfma_f32_32x32x16_bf16 v[212:227], v[74:77], v[42:45], v[212:227]
	v_max_f32_e32 v210, 0, v12
	v_max_f32_e32 v211, 0, v13
	v_fmac_f32_e32 v50, v250, v210
	v_fmac_f32_e32 v51, v251, v211
	v_max_f32_e32 v108, 0, v14
	v_max_f32_e32 v109, 0, v15
	v_fmac_f32_e32 v50, v252, v108
	v_fmac_f32_e32 v51, v253, v109
	v_max_f32_e32 v210, 0, v16
	v_max_f32_e32 v211, 0, v17
	v_fmac_f32_e32 v50, v254, v210
	v_fmac_f32_e32 v51, v255, v211
	s_waitcnt lgkmcnt(1)
	v_mfma_f32_32x32x16_bf16 v[212:227], v[78:81], v[46:49], v[212:227]
	v_max_f32_e32 v108, 0, v18
	v_max_f32_e32 v109, 0, v19
	v_fmac_f32_e32 v50, v200, v108
	v_fmac_f32_e32 v51, v201, v109
	v_max_f32_e32 v210, 0, v20
	v_max_f32_e32 v211, 0, v21
	v_fmac_f32_e32 v50, v202, v210
	v_fmac_f32_e32 v51, v203, v211
	v_add_f32_e32 v50, v50, v51
	v_ashrrev_i32_e32 v51, 31, v50
	s_waitcnt lgkmcnt(0)
	v_mfma_f32_32x32x16_bf16 v[212:227], v[82:85], v[196:199], v[212:227]
	v_or_b32_e32 v51, 0x80000000, v51
	s_cmpk_gt_i32 s11, 216
	s_cselect_b64 vcc, -1, 0
	v_xor_b32_e32 v50, v51, v50
	v_cndmask_b32_e32 v50, v123, v50, vcc
	global_store_dword v243, v50, s[8:9] offset:2048
	s_add_u32 s8, s8, 0x1000
	s_addc_u32 s9, s9, 0
	s_add_i32 m0, s10, 98304
	v_mfma_f32_32x32x16_bf16 v[6:21], v[86:89], v[38:41], 0
	global_load_lds_dwordx4 v102, s[6:7]
	s_add_i32 m0, s10, 99328
	s_nop 0
	global_load_lds_dwordx4 v110, s[6:7]
	s_add_i32 m0, s10, 100352
	s_nop 0
	global_load_lds_dwordx4 v112, s[6:7]
	s_add_i32 m0, s10, 101376
	s_nop 0
	global_load_lds_dwordx4 v193, s[6:7]
	s_add_u32 s6, s6, 0x8000
	s_addc_u32 s7, s7, 0
	v_max_f32_e32 v108, 0, v212
	v_max_f32_e32 v109, 0, v213
	v_mul_f32_e32 v0, v22, v108
	v_mul_f32_e32 v1, v23, v109
	v_max_f32_e32 v210, 0, v214
	v_max_f32_e32 v211, 0, v215
	v_fmac_f32_e32 v0, v24, v210
	v_fmac_f32_e32 v1, v25, v211
	v_max_f32_e32 v108, 0, v216
	v_max_f32_e32 v109, 0, v217
	v_fmac_f32_e32 v0, v26, v108
	v_fmac_f32_e32 v1, v27, v109
	v_mfma_f32_32x32x16_bf16 v[6:21], v[90:93], v[42:45], v[6:21]
	v_max_f32_e32 v210, 0, v218
	v_max_f32_e32 v211, 0, v219
	v_fmac_f32_e32 v0, v28, v210
	v_fmac_f32_e32 v1, v29, v211
	v_max_f32_e32 v108, 0, v220
	v_max_f32_e32 v109, 0, v221
	v_fmac_f32_e32 v0, v30, v108
	v_fmac_f32_e32 v1, v31, v109
	v_max_f32_e32 v210, 0, v222
	v_max_f32_e32 v211, 0, v223
	v_fmac_f32_e32 v0, v32, v210
	v_fmac_f32_e32 v1, v33, v211
	v_mfma_f32_32x32x16_bf16 v[6:21], v[94:97], v[46:49], v[6:21]
	v_max_f32_e32 v108, 0, v224
	v_max_f32_e32 v109, 0, v225
	v_fmac_f32_e32 v0, v34, v108
	v_fmac_f32_e32 v1, v35, v109
	v_max_f32_e32 v210, 0, v226
	v_max_f32_e32 v211, 0, v227
	v_fmac_f32_e32 v0, v36, v210
	v_fmac_f32_e32 v1, v37, v211
	v_add_f32_e32 v0, v0, v1
	v_ashrrev_i32_e32 v1, 31, v0
	v_mfma_f32_32x32x16_bf16 v[6:21], v[98:101], v[196:199], v[6:21]
	s_waitcnt vmcnt(10)
	ds_read_b128 v[38:41], v5 offset:43264
	ds_read_b128 v[42:45], v52 offset:43264
	ds_read_b128 v[46:49], v55 offset:43264
	ds_read_b128 v[196:199], v56 offset:43264
	v_or_b32_e32 v1, 0x80000000, v1
	s_cmpk_gt_i32 s11, 224
	s_cselect_b64 vcc, -1, 0
	v_xor_b32_e32 v0, v1, v0
	v_cndmask_b32_e32 v162, v123, v0, vcc
	s_nop 3
	s_waitcnt lgkmcnt(3)
	v_mfma_f32_32x32x16_bf16 v[212:227], v[70:73], v[38:41], 0
	v_max_f32_e32 v108, 0, v6
	v_max_f32_e32 v109, 0, v7
	v_mul_f32_e32 v50, v244, v108
	v_mul_f32_e32 v51, v245, v109
	v_max_f32_e32 v210, 0, v8
	v_max_f32_e32 v211, 0, v9
	v_fmac_f32_e32 v50, v246, v210
	v_fmac_f32_e32 v51, v247, v211
	v_max_f32_e32 v108, 0, v10
	v_max_f32_e32 v109, 0, v11
	v_fmac_f32_e32 v50, v248, v108
	v_fmac_f32_e32 v51, v249, v109
	s_waitcnt lgkmcnt(2)
	v_mfma_f32_32x32x16_bf16 v[212:227], v[74:77], v[42:45], v[212:227]
	v_max_f32_e32 v210, 0, v12
	v_max_f32_e32 v211, 0, v13
	v_fmac_f32_e32 v50, v250, v210
	v_fmac_f32_e32 v51, v251, v211
	v_max_f32_e32 v108, 0, v14
	v_max_f32_e32 v109, 0, v15
	v_fmac_f32_e32 v50, v252, v108
	v_fmac_f32_e32 v51, v253, v109
	v_max_f32_e32 v210, 0, v16
	v_max_f32_e32 v211, 0, v17
	v_fmac_f32_e32 v50, v254, v210
	v_fmac_f32_e32 v51, v255, v211
	s_waitcnt lgkmcnt(1)
	v_mfma_f32_32x32x16_bf16 v[212:227], v[78:81], v[46:49], v[212:227]
	v_max_f32_e32 v108, 0, v18
	v_max_f32_e32 v109, 0, v19
	v_fmac_f32_e32 v50, v200, v108
	v_fmac_f32_e32 v51, v201, v109
	v_max_f32_e32 v210, 0, v20
	v_max_f32_e32 v211, 0, v21
	v_fmac_f32_e32 v50, v202, v210
	v_fmac_f32_e32 v51, v203, v211
	v_add_f32_e32 v50, v50, v51
	v_ashrrev_i32_e32 v51, 31, v50
	s_waitcnt lgkmcnt(0)
	v_mfma_f32_32x32x16_bf16 v[212:227], v[82:85], v[196:199], v[212:227]
	v_or_b32_e32 v51, 0x80000000, v51
	s_cmpk_gt_i32 s11, 224
	s_cselect_b64 vcc, -1, 0
	v_xor_b32_e32 v50, v51, v50
	v_cndmask_b32_e32 v50, v123, v50, vcc
	global_store_dword v243, v50, s[8:9]
	s_add_i32 m0, s10, 0
	v_mfma_f32_32x32x16_bf16 v[6:21], v[86:89], v[38:41], 0
	global_load_lds_dwordx4 v102, s[6:7]
	s_add_i32 m0, s10, 1024
	s_nop 0
	global_load_lds_dwordx4 v110, s[6:7]
	s_add_i32 m0, s10, 2048
	s_nop 0
	global_load_lds_dwordx4 v112, s[6:7]
	s_add_i32 m0, s10, 3072
	s_nop 0
	global_load_lds_dwordx4 v193, s[6:7]
	s_add_u32 s6, s6, 0x8000
	s_addc_u32 s7, s7, 0
	v_max_f32_e32 v108, 0, v212
	v_max_f32_e32 v109, 0, v213
	v_mul_f32_e32 v0, v22, v108
	v_mul_f32_e32 v1, v23, v109
	v_max_f32_e32 v210, 0, v214
	v_max_f32_e32 v211, 0, v215
	v_fmac_f32_e32 v0, v24, v210
	v_fmac_f32_e32 v1, v25, v211
	v_max_f32_e32 v108, 0, v216
	v_max_f32_e32 v109, 0, v217
	v_fmac_f32_e32 v0, v26, v108
	v_fmac_f32_e32 v1, v27, v109
	v_mfma_f32_32x32x16_bf16 v[6:21], v[90:93], v[42:45], v[6:21]
	v_max_f32_e32 v210, 0, v218
	v_max_f32_e32 v211, 0, v219
	v_fmac_f32_e32 v0, v28, v210
	v_fmac_f32_e32 v1, v29, v211
	v_max_f32_e32 v108, 0, v220
	v_max_f32_e32 v109, 0, v221
	v_fmac_f32_e32 v0, v30, v108
	v_fmac_f32_e32 v1, v31, v109
	v_max_f32_e32 v210, 0, v222
	v_max_f32_e32 v211, 0, v223
	v_fmac_f32_e32 v0, v32, v210
	v_fmac_f32_e32 v1, v33, v211
	v_mfma_f32_32x32x16_bf16 v[6:21], v[94:97], v[46:49], v[6:21]
	v_max_f32_e32 v108, 0, v224
	v_max_f32_e32 v109, 0, v225
	v_fmac_f32_e32 v0, v34, v108
	v_fmac_f32_e32 v1, v35, v109
	v_max_f32_e32 v210, 0, v226
	v_max_f32_e32 v211, 0, v227
	v_fmac_f32_e32 v0, v36, v210
	v_fmac_f32_e32 v1, v37, v211
	v_add_f32_e32 v0, v0, v1
	v_ashrrev_i32_e32 v1, 31, v0
	v_mfma_f32_32x32x16_bf16 v[6:21], v[98:101], v[196:199], v[6:21]
	s_waitcnt vmcnt(10)
	v_add_u32_e32 v228, 0x10000, v5
	ds_read_b128 v[38:41], v228 offset:10496
	v_add_u32_e32 v228, 0x10000, v52
	ds_read_b128 v[42:45], v228 offset:10496
	v_add_u32_e32 v228, 0x10000, v55
	ds_read_b128 v[46:49], v228 offset:10496
	v_add_u32_e32 v228, 0x10000, v56
	ds_read_b128 v[196:199], v228 offset:10496
	v_or_b32_e32 v1, 0x80000000, v1
	s_cmpk_gt_i32 s11, 232
	s_cselect_b64 vcc, -1, 0
	v_xor_b32_e32 v0, v1, v0
	v_cndmask_b32_e32 v161, v123, v0, vcc
	s_nop 3
	s_waitcnt lgkmcnt(3)
	v_mfma_f32_32x32x16_bf16 v[212:227], v[70:73], v[38:41], 0
	v_max_f32_e32 v108, 0, v6
	v_max_f32_e32 v109, 0, v7
	v_mul_f32_e32 v50, v244, v108
	v_mul_f32_e32 v51, v245, v109
	v_max_f32_e32 v210, 0, v8
	v_max_f32_e32 v211, 0, v9
	v_fmac_f32_e32 v50, v246, v210
	v_fmac_f32_e32 v51, v247, v211
	v_max_f32_e32 v108, 0, v10
	v_max_f32_e32 v109, 0, v11
	v_fmac_f32_e32 v50, v248, v108
	v_fmac_f32_e32 v51, v249, v109
	s_waitcnt lgkmcnt(2)
	v_mfma_f32_32x32x16_bf16 v[212:227], v[74:77], v[42:45], v[212:227]
	v_max_f32_e32 v210, 0, v12
	v_max_f32_e32 v211, 0, v13
	v_fmac_f32_e32 v50, v250, v210
	v_fmac_f32_e32 v51, v251, v211
	v_max_f32_e32 v108, 0, v14
	v_max_f32_e32 v109, 0, v15
	v_fmac_f32_e32 v50, v252, v108
	v_fmac_f32_e32 v51, v253, v109
	v_max_f32_e32 v210, 0, v16
	v_max_f32_e32 v211, 0, v17
	v_fmac_f32_e32 v50, v254, v210
	v_fmac_f32_e32 v51, v255, v211
	s_waitcnt lgkmcnt(1)
	v_mfma_f32_32x32x16_bf16 v[212:227], v[78:81], v[46:49], v[212:227]
	v_max_f32_e32 v108, 0, v18
	v_max_f32_e32 v109, 0, v19
	v_fmac_f32_e32 v50, v200, v108
	v_fmac_f32_e32 v51, v201, v109
	v_max_f32_e32 v210, 0, v20
	v_max_f32_e32 v211, 0, v21
	v_fmac_f32_e32 v50, v202, v210
	v_fmac_f32_e32 v51, v203, v211
	v_add_f32_e32 v50, v50, v51
	v_ashrrev_i32_e32 v51, 31, v50
	s_waitcnt lgkmcnt(0)
	v_mfma_f32_32x32x16_bf16 v[212:227], v[82:85], v[196:199], v[212:227]
	v_or_b32_e32 v51, 0x80000000, v51
	s_cmpk_gt_i32 s11, 232
	s_cselect_b64 vcc, -1, 0
	v_xor_b32_e32 v50, v51, v50
	v_cndmask_b32_e32 v50, v123, v50, vcc
	global_store_dword v243, v50, s[8:9] offset:2048
	s_add_u32 s8, s8, 0x1000
	s_addc_u32 s9, s9, 0
	s_add_i32 m0, s10, 32768
	v_mfma_f32_32x32x16_bf16 v[6:21], v[86:89], v[38:41], 0
	global_load_lds_dwordx4 v102, s[6:7]
	s_add_i32 m0, s10, 33792
	s_nop 0
	global_load_lds_dwordx4 v110, s[6:7]
	s_add_i32 m0, s10, 34816
	s_nop 0
	global_load_lds_dwordx4 v112, s[6:7]
	s_add_i32 m0, s10, 35840
	s_nop 0
	global_load_lds_dwordx4 v193, s[6:7]
	s_add_u32 s6, s6, 0x8000
	s_addc_u32 s7, s7, 0
	v_max_f32_e32 v108, 0, v212
	v_max_f32_e32 v109, 0, v213
	v_mul_f32_e32 v0, v22, v108
	v_mul_f32_e32 v1, v23, v109
	v_max_f32_e32 v210, 0, v214
	v_max_f32_e32 v211, 0, v215
	v_fmac_f32_e32 v0, v24, v210
	v_fmac_f32_e32 v1, v25, v211
	v_max_f32_e32 v108, 0, v216
	v_max_f32_e32 v109, 0, v217
	v_fmac_f32_e32 v0, v26, v108
	v_fmac_f32_e32 v1, v27, v109
	v_mfma_f32_32x32x16_bf16 v[6:21], v[90:93], v[42:45], v[6:21]
	v_max_f32_e32 v210, 0, v218
	v_max_f32_e32 v211, 0, v219
	v_fmac_f32_e32 v0, v28, v210
	v_fmac_f32_e32 v1, v29, v211
	v_max_f32_e32 v108, 0, v220
	v_max_f32_e32 v109, 0, v221
	v_fmac_f32_e32 v0, v30, v108
	v_fmac_f32_e32 v1, v31, v109
	v_max_f32_e32 v210, 0, v222
	v_max_f32_e32 v211, 0, v223
	v_fmac_f32_e32 v0, v32, v210
	v_fmac_f32_e32 v1, v33, v211
	v_mfma_f32_32x32x16_bf16 v[6:21], v[94:97], v[46:49], v[6:21]
	v_max_f32_e32 v108, 0, v224
	v_max_f32_e32 v109, 0, v225
	v_fmac_f32_e32 v0, v34, v108
	v_fmac_f32_e32 v1, v35, v109
	v_max_f32_e32 v210, 0, v226
	v_max_f32_e32 v211, 0, v227
	v_fmac_f32_e32 v0, v36, v210
	v_fmac_f32_e32 v1, v37, v211
	v_add_f32_e32 v0, v0, v1
	v_ashrrev_i32_e32 v1, 31, v0
	v_mfma_f32_32x32x16_bf16 v[6:21], v[98:101], v[196:199], v[6:21]
	s_waitcnt vmcnt(10)
	v_add_u32_e32 v228, 0x10000, v5
	ds_read_b128 v[38:41], v228 offset:43264
	v_add_u32_e32 v228, 0x10000, v52
	ds_read_b128 v[42:45], v228 offset:43264
	v_add_u32_e32 v228, 0x10000, v55
	ds_read_b128 v[46:49], v228 offset:43264
	v_add_u32_e32 v228, 0x10000, v56
	ds_read_b128 v[196:199], v228 offset:43264
	v_or_b32_e32 v1, 0x80000000, v1
	s_cmpk_gt_i32 s11, 240
	s_cselect_b64 vcc, -1, 0
	v_xor_b32_e32 v0, v1, v0
	v_cndmask_b32_e32 v163, v123, v0, vcc
	s_nop 3
	s_waitcnt lgkmcnt(3)
	v_mfma_f32_32x32x16_bf16 v[212:227], v[70:73], v[38:41], 0
	v_max_f32_e32 v108, 0, v6
	v_max_f32_e32 v109, 0, v7
	v_mul_f32_e32 v50, v244, v108
	v_mul_f32_e32 v51, v245, v109
	v_max_f32_e32 v210, 0, v8
	v_max_f32_e32 v211, 0, v9
	v_fmac_f32_e32 v50, v246, v210
	v_fmac_f32_e32 v51, v247, v211
	v_max_f32_e32 v108, 0, v10
	v_max_f32_e32 v109, 0, v11
	v_fmac_f32_e32 v50, v248, v108
	v_fmac_f32_e32 v51, v249, v109
	s_waitcnt lgkmcnt(2)
	v_mfma_f32_32x32x16_bf16 v[212:227], v[74:77], v[42:45], v[212:227]
	v_max_f32_e32 v210, 0, v12
	v_max_f32_e32 v211, 0, v13
	v_fmac_f32_e32 v50, v250, v210
	v_fmac_f32_e32 v51, v251, v211
	v_max_f32_e32 v108, 0, v14
	v_max_f32_e32 v109, 0, v15
	v_fmac_f32_e32 v50, v252, v108
	v_fmac_f32_e32 v51, v253, v109
	v_max_f32_e32 v210, 0, v16
	v_max_f32_e32 v211, 0, v17
	v_fmac_f32_e32 v50, v254, v210
	v_fmac_f32_e32 v51, v255, v211
	s_waitcnt lgkmcnt(1)
	v_mfma_f32_32x32x16_bf16 v[212:227], v[78:81], v[46:49], v[212:227]
	v_max_f32_e32 v108, 0, v18
	v_max_f32_e32 v109, 0, v19
	v_fmac_f32_e32 v50, v200, v108
	v_fmac_f32_e32 v51, v201, v109
	v_max_f32_e32 v210, 0, v20
	v_max_f32_e32 v211, 0, v21
	v_fmac_f32_e32 v50, v202, v210
	v_fmac_f32_e32 v51, v203, v211
	v_add_f32_e32 v50, v50, v51
	v_ashrrev_i32_e32 v51, 31, v50
	s_waitcnt lgkmcnt(0)
	v_mfma_f32_32x32x16_bf16 v[212:227], v[82:85], v[196:199], v[212:227]
	v_or_b32_e32 v51, 0x80000000, v51
	s_cmpk_gt_i32 s11, 240
	s_cselect_b64 vcc, -1, 0
	v_xor_b32_e32 v50, v51, v50
	v_cndmask_b32_e32 v50, v123, v50, vcc
	global_store_dword v243, v50, s[8:9]
	s_add_i32 m0, s10, 65536
	v_mfma_f32_32x32x16_bf16 v[6:21], v[86:89], v[38:41], 0
	global_load_lds_dwordx4 v102, s[6:7]
	s_add_i32 m0, s10, 66560
	s_nop 0
	global_load_lds_dwordx4 v110, s[6:7]
	s_add_i32 m0, s10, 67584
	s_nop 0
	global_load_lds_dwordx4 v112, s[6:7]
	s_add_i32 m0, s10, 68608
	s_nop 0
	global_load_lds_dwordx4 v193, s[6:7]
	s_add_u32 s6, s6, 0x8000
	s_addc_u32 s7, s7, 0
	v_max_f32_e32 v108, 0, v212
	v_max_f32_e32 v109, 0, v213
	v_mul_f32_e32 v0, v22, v108
	v_mul_f32_e32 v1, v23, v109
	v_max_f32_e32 v210, 0, v214
	v_max_f32_e32 v211, 0, v215
	v_fmac_f32_e32 v0, v24, v210
	v_fmac_f32_e32 v1, v25, v211
	v_max_f32_e32 v108, 0, v216
	v_max_f32_e32 v109, 0, v217
	v_fmac_f32_e32 v0, v26, v108
	v_fmac_f32_e32 v1, v27, v109
	v_mfma_f32_32x32x16_bf16 v[6:21], v[90:93], v[42:45], v[6:21]
	v_max_f32_e32 v210, 0, v218
	v_max_f32_e32 v211, 0, v219
	v_fmac_f32_e32 v0, v28, v210
	v_fmac_f32_e32 v1, v29, v211
	v_max_f32_e32 v108, 0, v220
	v_max_f32_e32 v109, 0, v221
	v_fmac_f32_e32 v0, v30, v108
	v_fmac_f32_e32 v1, v31, v109
	v_max_f32_e32 v210, 0, v222
	v_max_f32_e32 v211, 0, v223
	v_fmac_f32_e32 v0, v32, v210
	v_fmac_f32_e32 v1, v33, v211
	v_mfma_f32_32x32x16_bf16 v[6:21], v[94:97], v[46:49], v[6:21]
	v_max_f32_e32 v108, 0, v224
	v_max_f32_e32 v109, 0, v225
	v_fmac_f32_e32 v0, v34, v108
	v_fmac_f32_e32 v1, v35, v109
	v_max_f32_e32 v210, 0, v226
	v_max_f32_e32 v211, 0, v227
	v_fmac_f32_e32 v0, v36, v210
	v_fmac_f32_e32 v1, v37, v211
	v_add_f32_e32 v0, v0, v1
	v_ashrrev_i32_e32 v1, 31, v0
	v_mfma_f32_32x32x16_bf16 v[6:21], v[98:101], v[196:199], v[6:21]
	s_waitcnt vmcnt(10)
	ds_read_b128 v[38:41], v5 offset:10496
	ds_read_b128 v[42:45], v52 offset:10496
	ds_read_b128 v[46:49], v55 offset:10496
	ds_read_b128 v[196:199], v56 offset:10496
	v_or_b32_e32 v1, 0x80000000, v1
	s_cmpk_gt_i32 s11, 248
	s_cselect_b64 vcc, -1, 0
	v_xor_b32_e32 v0, v1, v0
	v_cndmask_b32_e32 v152, v123, v0, vcc
	s_nop 3
	v_max_f32_e32 v108, 0, v6
	v_max_f32_e32 v109, 0, v7
	v_mul_f32_e32 v50, v244, v108
	v_mul_f32_e32 v51, v245, v109
	v_max_f32_e32 v210, 0, v8
	v_max_f32_e32 v211, 0, v9
	v_fmac_f32_e32 v50, v246, v210
	v_fmac_f32_e32 v51, v247, v211
	v_max_f32_e32 v108, 0, v10
	v_max_f32_e32 v109, 0, v11
	v_fmac_f32_e32 v50, v248, v108
	v_fmac_f32_e32 v51, v249, v109
	v_max_f32_e32 v210, 0, v12
	v_max_f32_e32 v211, 0, v13
	v_fmac_f32_e32 v50, v250, v210
	v_fmac_f32_e32 v51, v251, v211
	v_max_f32_e32 v108, 0, v14
	v_max_f32_e32 v109, 0, v15
	v_fmac_f32_e32 v50, v252, v108
	v_fmac_f32_e32 v51, v253, v109
	v_max_f32_e32 v210, 0, v16
	v_max_f32_e32 v211, 0, v17
	v_fmac_f32_e32 v50, v254, v210
	v_fmac_f32_e32 v51, v255, v211
	v_max_f32_e32 v108, 0, v18
	v_max_f32_e32 v109, 0, v19
	v_fmac_f32_e32 v50, v200, v108
	v_fmac_f32_e32 v51, v201, v109
	v_max_f32_e32 v210, 0, v20
	v_max_f32_e32 v211, 0, v21
	v_fmac_f32_e32 v50, v202, v210
	v_fmac_f32_e32 v51, v203, v211
	v_add_f32_e32 v50, v50, v51
	v_ashrrev_i32_e32 v51, 31, v50
	v_or_b32_e32 v51, 0x80000000, v51
	s_cmpk_gt_i32 s11, 248
	s_cselect_b64 vcc, -1, 0
	v_xor_b32_e32 v50, v51, v50
	v_cndmask_b32_e32 v50, v123, v50, vcc
	global_store_dword v243, v50, s[8:9] offset:2048
	s_add_u32 s8, s8, 0x1000
	s_addc_u32 s9, s9, 0
	s_cmpk_gt_i32 s81, 32
	s_cbranch_scc0 .Lix_fill_4
	s_waitcnt lgkmcnt(3)
	s_add_i32 m0, s10, 98304
	v_mfma_f32_32x32x16_bf16 v[212:227], v[70:73], v[38:41], 0
	global_load_lds_dwordx4 v102, s[6:7]
	s_waitcnt lgkmcnt(2)
	s_add_i32 m0, s10, 99328
	v_mfma_f32_32x32x16_bf16 v[212:227], v[74:77], v[42:45], v[212:227]
	global_load_lds_dwordx4 v110, s[6:7]
	s_waitcnt lgkmcnt(1)
	s_add_i32 m0, s10, 100352
	v_mfma_f32_32x32x16_bf16 v[212:227], v[78:81], v[46:49], v[212:227]
	global_load_lds_dwordx4 v112, s[6:7]
	s_waitcnt lgkmcnt(0)
	s_add_i32 m0, s10, 101376
	v_mfma_f32_32x32x16_bf16 v[212:227], v[82:85], v[196:199], v[212:227]
	global_load_lds_dwordx4 v193, s[6:7]
	s_add_u32 s6, s6, 0x8000
	s_addc_u32 s7, s7, 0
	v_mfma_f32_32x32x16_bf16 v[6:21], v[86:89], v[38:41], 0
	s_nop 7
	s_nop 2
	v_max_f32_e32 v108, 0, v212
	v_max_f32_e32 v109, 0, v213
	v_mul_f32_e32 v0, v22, v108
	v_mul_f32_e32 v1, v23, v109
	v_max_f32_e32 v210, 0, v214
	v_max_f32_e32 v211, 0, v215
	v_fmac_f32_e32 v0, v24, v210
	v_fmac_f32_e32 v1, v25, v211
	v_max_f32_e32 v108, 0, v216
	v_max_f32_e32 v109, 0, v217
	v_fmac_f32_e32 v0, v26, v108
	v_fmac_f32_e32 v1, v27, v109
	v_mfma_f32_32x32x16_bf16 v[6:21], v[90:93], v[42:45], v[6:21]
	v_max_f32_e32 v210, 0, v218
	v_max_f32_e32 v211, 0, v219
	v_fmac_f32_e32 v0, v28, v210
	v_fmac_f32_e32 v1, v29, v211
	v_max_f32_e32 v108, 0, v220
	v_max_f32_e32 v109, 0, v221
	v_fmac_f32_e32 v0, v30, v108
	v_fmac_f32_e32 v1, v31, v109
	v_max_f32_e32 v210, 0, v222
	v_max_f32_e32 v211, 0, v223
	v_fmac_f32_e32 v0, v32, v210
	v_fmac_f32_e32 v1, v33, v211
	v_mfma_f32_32x32x16_bf16 v[6:21], v[94:97], v[46:49], v[6:21]
	v_max_f32_e32 v108, 0, v224
	v_max_f32_e32 v109, 0, v225
	v_fmac_f32_e32 v0, v34, v108
	v_fmac_f32_e32 v1, v35, v109
	v_max_f32_e32 v210, 0, v226
	v_max_f32_e32 v211, 0, v227
	v_fmac_f32_e32 v0, v36, v210
	v_fmac_f32_e32 v1, v37, v211
	v_add_f32_e32 v0, v0, v1
	v_ashrrev_i32_e32 v1, 31, v0
	v_mfma_f32_32x32x16_bf16 v[6:21], v[98:101], v[196:199], v[6:21]
	s_waitcnt vmcnt(10)
	ds_read_b128 v[38:41], v5 offset:43264
	ds_read_b128 v[42:45], v52 offset:43264
	ds_read_b128 v[46:49], v55 offset:43264
	ds_read_b128 v[196:199], v56 offset:43264
	v_or_b32_e32 v1, 0x80000000, v1
	s_cmpk_gt_i32 s11, 256
	s_cselect_b64 vcc, -1, 0
	v_xor_b32_e32 v0, v1, v0
	v_cndmask_b32_e32 v165, v123, v0, vcc
	s_nop 3
	s_waitcnt lgkmcnt(3)
	v_mfma_f32_32x32x16_bf16 v[212:227], v[70:73], v[38:41], 0
	v_max_f32_e32 v108, 0, v6
	v_max_f32_e32 v109, 0, v7
	v_mul_f32_e32 v50, v244, v108
	v_mul_f32_e32 v51, v245, v109
	v_max_f32_e32 v210, 0, v8
	v_max_f32_e32 v211, 0, v9
	v_fmac_f32_e32 v50, v246, v210
	v_fmac_f32_e32 v51, v247, v211
	v_max_f32_e32 v108, 0, v10
	v_max_f32_e32 v109, 0, v11
	v_fmac_f32_e32 v50, v248, v108
	v_fmac_f32_e32 v51, v249, v109
	s_waitcnt lgkmcnt(2)
	v_mfma_f32_32x32x16_bf16 v[212:227], v[74:77], v[42:45], v[212:227]
	v_max_f32_e32 v210, 0, v12
	v_max_f32_e32 v211, 0, v13
	v_fmac_f32_e32 v50, v250, v210
	v_fmac_f32_e32 v51, v251, v211
	v_max_f32_e32 v108, 0, v14
	v_max_f32_e32 v109, 0, v15
	v_fmac_f32_e32 v50, v252, v108
	v_fmac_f32_e32 v51, v253, v109
	v_max_f32_e32 v210, 0, v16
	v_max_f32_e32 v211, 0, v17
	v_fmac_f32_e32 v50, v254, v210
	v_fmac_f32_e32 v51, v255, v211
	s_waitcnt lgkmcnt(1)
	v_mfma_f32_32x32x16_bf16 v[212:227], v[78:81], v[46:49], v[212:227]
	v_max_f32_e32 v108, 0, v18
	v_max_f32_e32 v109, 0, v19
	v_fmac_f32_e32 v50, v200, v108
	v_fmac_f32_e32 v51, v201, v109
	v_max_f32_e32 v210, 0, v20
	v_max_f32_e32 v211, 0, v21
	v_fmac_f32_e32 v50, v202, v210
	v_fmac_f32_e32 v51, v203, v211
	v_add_f32_e32 v50, v50, v51
	v_ashrrev_i32_e32 v51, 31, v50
	s_waitcnt lgkmcnt(0)
	v_mfma_f32_32x32x16_bf16 v[212:227], v[82:85], v[196:199], v[212:227]
	v_or_b32_e32 v51, 0x80000000, v51
	s_cmpk_gt_i32 s11, 256
	s_cselect_b64 vcc, -1, 0
	v_xor_b32_e32 v50, v51, v50
	v_cndmask_b32_e32 v50, v123, v50, vcc
	global_store_dword v243, v50, s[8:9]
	s_add_i32 m0, s10, 0
	v_mfma_f32_32x32x16_bf16 v[6:21], v[86:89], v[38:41], 0
	global_load_lds_dwordx4 v102, s[6:7]
	s_add_i32 m0, s10, 1024
	s_nop 0
	global_load_lds_dwordx4 v110, s[6:7]
	s_add_i32 m0, s10, 2048
	s_nop 0
	global_load_lds_dwordx4 v112, s[6:7]
	s_add_i32 m0, s10, 3072
	s_nop 0
	global_load_lds_dwordx4 v193, s[6:7]
	s_add_u32 s6, s6, 0x8000
	s_addc_u32 s7, s7, 0
	v_max_f32_e32 v108, 0, v212
	v_max_f32_e32 v109, 0, v213
	v_mul_f32_e32 v0, v22, v108
	v_mul_f32_e32 v1, v23, v109
	v_max_f32_e32 v210, 0, v214
	v_max_f32_e32 v211, 0, v215
	v_fmac_f32_e32 v0, v24, v210
	v_fmac_f32_e32 v1, v25, v211
	v_max_f32_e32 v108, 0, v216
	v_max_f32_e32 v109, 0, v217
	v_fmac_f32_e32 v0, v26, v108
	v_fmac_f32_e32 v1, v27, v109
	v_mfma_f32_32x32x16_bf16 v[6:21], v[90:93], v[42:45], v[6:21]
	v_max_f32_e32 v210, 0, v218
	v_max_f32_e32 v211, 0, v219
	v_fmac_f32_e32 v0, v28, v210
	v_fmac_f32_e32 v1, v29, v211
	v_max_f32_e32 v108, 0, v220
	v_max_f32_e32 v109, 0, v221
	v_fmac_f32_e32 v0, v30, v108
	v_fmac_f32_e32 v1, v31, v109
	v_max_f32_e32 v210, 0, v222
	v_max_f32_e32 v211, 0, v223
	v_fmac_f32_e32 v0, v32, v210
	v_fmac_f32_e32 v1, v33, v211
	v_mfma_f32_32x32x16_bf16 v[6:21], v[94:97], v[46:49], v[6:21]
	v_max_f32_e32 v108, 0, v224
	v_max_f32_e32 v109, 0, v225
	v_fmac_f32_e32 v0, v34, v108
	v_fmac_f32_e32 v1, v35, v109
	v_max_f32_e32 v210, 0, v226
	v_max_f32_e32 v211, 0, v227
	v_fmac_f32_e32 v0, v36, v210
	v_fmac_f32_e32 v1, v37, v211
	v_add_f32_e32 v0, v0, v1
	v_ashrrev_i32_e32 v1, 31, v0
	v_mfma_f32_32x32x16_bf16 v[6:21], v[98:101], v[196:199], v[6:21]
	s_waitcnt vmcnt(10)
	v_add_u32_e32 v228, 0x10000, v5
	ds_read_b128 v[38:41], v228 offset:10496
	v_add_u32_e32 v228, 0x10000, v52
	ds_read_b128 v[42:45], v228 offset:10496
	v_add_u32_e32 v228, 0x10000, v55
	ds_read_b128 v[46:49], v228 offset:10496
	v_add_u32_e32 v228, 0x10000, v56
	ds_read_b128 v[196:199], v228 offset:10496
	v_or_b32_e32 v1, 0x80000000, v1
	s_cmpk_gt_i32 s11, 264
	s_cselect_b64 vcc, -1, 0
	v_xor_b32_e32 v0, v1, v0
	v_cndmask_b32_e32 v164, v123, v0, vcc
	s_nop 3
	s_waitcnt lgkmcnt(3)
	v_mfma_f32_32x32x16_bf16 v[212:227], v[70:73], v[38:41], 0
	v_max_f32_e32 v108, 0, v6
	v_max_f32_e32 v109, 0, v7
	v_mul_f32_e32 v50, v244, v108
	v_mul_f32_e32 v51, v245, v109
	v_max_f32_e32 v210, 0, v8
	v_max_f32_e32 v211, 0, v9
	v_fmac_f32_e32 v50, v246, v210
	v_fmac_f32_e32 v51, v247, v211
	v_max_f32_e32 v108, 0, v10
	v_max_f32_e32 v109, 0, v11
	v_fmac_f32_e32 v50, v248, v108
	v_fmac_f32_e32 v51, v249, v109
	s_waitcnt lgkmcnt(2)
	v_mfma_f32_32x32x16_bf16 v[212:227], v[74:77], v[42:45], v[212:227]
	v_max_f32_e32 v210, 0, v12
	v_max_f32_e32 v211, 0, v13
	v_fmac_f32_e32 v50, v250, v210
	v_fmac_f32_e32 v51, v251, v211
	v_max_f32_e32 v108, 0, v14
	v_max_f32_e32 v109, 0, v15
	v_fmac_f32_e32 v50, v252, v108
	v_fmac_f32_e32 v51, v253, v109
	v_max_f32_e32 v210, 0, v16
	v_max_f32_e32 v211, 0, v17
	v_fmac_f32_e32 v50, v254, v210
	v_fmac_f32_e32 v51, v255, v211
	s_waitcnt lgkmcnt(1)
	v_mfma_f32_32x32x16_bf16 v[212:227], v[78:81], v[46:49], v[212:227]
	v_max_f32_e32 v108, 0, v18
	v_max_f32_e32 v109, 0, v19
	v_fmac_f32_e32 v50, v200, v108
	v_fmac_f32_e32 v51, v201, v109
	v_max_f32_e32 v210, 0, v20
	v_max_f32_e32 v211, 0, v21
	v_fmac_f32_e32 v50, v202, v210
	v_fmac_f32_e32 v51, v203, v211
	v_add_f32_e32 v50, v50, v51
	v_ashrrev_i32_e32 v51, 31, v50
	s_waitcnt lgkmcnt(0)
	v_mfma_f32_32x32x16_bf16 v[212:227], v[82:85], v[196:199], v[212:227]
	v_or_b32_e32 v51, 0x80000000, v51
	s_cmpk_gt_i32 s11, 264
	s_cselect_b64 vcc, -1, 0
	v_xor_b32_e32 v50, v51, v50
	v_cndmask_b32_e32 v50, v123, v50, vcc
	global_store_dword v243, v50, s[8:9] offset:2048
	s_add_u32 s8, s8, 0x1000
	s_addc_u32 s9, s9, 0
	s_add_i32 m0, s10, 32768
	v_mfma_f32_32x32x16_bf16 v[6:21], v[86:89], v[38:41], 0
	global_load_lds_dwordx4 v102, s[6:7]
	s_add_i32 m0, s10, 33792
	s_nop 0
	global_load_lds_dwordx4 v110, s[6:7]
	s_add_i32 m0, s10, 34816
	s_nop 0
	global_load_lds_dwordx4 v112, s[6:7]
	s_add_i32 m0, s10, 35840
	s_nop 0
	global_load_lds_dwordx4 v193, s[6:7]
	s_add_u32 s6, s6, 0x8000
	s_addc_u32 s7, s7, 0
	v_max_f32_e32 v108, 0, v212
	v_max_f32_e32 v109, 0, v213
	v_mul_f32_e32 v0, v22, v108
	v_mul_f32_e32 v1, v23, v109
	v_max_f32_e32 v210, 0, v214
	v_max_f32_e32 v211, 0, v215
	v_fmac_f32_e32 v0, v24, v210
	v_fmac_f32_e32 v1, v25, v211
	v_max_f32_e32 v108, 0, v216
	v_max_f32_e32 v109, 0, v217
	v_fmac_f32_e32 v0, v26, v108
	v_fmac_f32_e32 v1, v27, v109
	v_mfma_f32_32x32x16_bf16 v[6:21], v[90:93], v[42:45], v[6:21]
	v_max_f32_e32 v210, 0, v218
	v_max_f32_e32 v211, 0, v219
	v_fmac_f32_e32 v0, v28, v210
	v_fmac_f32_e32 v1, v29, v211
	v_max_f32_e32 v108, 0, v220
	v_max_f32_e32 v109, 0, v221
	v_fmac_f32_e32 v0, v30, v108
	v_fmac_f32_e32 v1, v31, v109
	v_max_f32_e32 v210, 0, v222
	v_max_f32_e32 v211, 0, v223
	v_fmac_f32_e32 v0, v32, v210
	v_fmac_f32_e32 v1, v33, v211
	v_mfma_f32_32x32x16_bf16 v[6:21], v[94:97], v[46:49], v[6:21]
	v_max_f32_e32 v108, 0, v224
	v_max_f32_e32 v109, 0, v225
	v_fmac_f32_e32 v0, v34, v108
	v_fmac_f32_e32 v1, v35, v109
	v_max_f32_e32 v210, 0, v226
	v_max_f32_e32 v211, 0, v227
	v_fmac_f32_e32 v0, v36, v210
	v_fmac_f32_e32 v1, v37, v211
	v_add_f32_e32 v0, v0, v1
	v_ashrrev_i32_e32 v1, 31, v0
	v_mfma_f32_32x32x16_bf16 v[6:21], v[98:101], v[196:199], v[6:21]
	s_waitcnt vmcnt(10)
	v_add_u32_e32 v228, 0x10000, v5
	ds_read_b128 v[38:41], v228 offset:43264
	v_add_u32_e32 v228, 0x10000, v52
	ds_read_b128 v[42:45], v228 offset:43264
	v_add_u32_e32 v228, 0x10000, v55
	ds_read_b128 v[46:49], v228 offset:43264
	v_add_u32_e32 v228, 0x10000, v56
	ds_read_b128 v[196:199], v228 offset:43264
	v_or_b32_e32 v1, 0x80000000, v1
	s_cmpk_gt_i32 s11, 272
	s_cselect_b64 vcc, -1, 0
	v_xor_b32_e32 v0, v1, v0
	v_cndmask_b32_e32 v167, v123, v0, vcc
	s_nop 3
	s_waitcnt lgkmcnt(3)
	v_mfma_f32_32x32x16_bf16 v[212:227], v[70:73], v[38:41], 0
	v_max_f32_e32 v108, 0, v6
	v_max_f32_e32 v109, 0, v7
	v_mul_f32_e32 v50, v244, v108
	v_mul_f32_e32 v51, v245, v109
	v_max_f32_e32 v210, 0, v8
	v_max_f32_e32 v211, 0, v9
	v_fmac_f32_e32 v50, v246, v210
	v_fmac_f32_e32 v51, v247, v211
	v_max_f32_e32 v108, 0, v10
	v_max_f32_e32 v109, 0, v11
	v_fmac_f32_e32 v50, v248, v108
	v_fmac_f32_e32 v51, v249, v109
	s_waitcnt lgkmcnt(2)
	v_mfma_f32_32x32x16_bf16 v[212:227], v[74:77], v[42:45], v[212:227]
	v_max_f32_e32 v210, 0, v12
	v_max_f32_e32 v211, 0, v13
	v_fmac_f32_e32 v50, v250, v210
	v_fmac_f32_e32 v51, v251, v211
	v_max_f32_e32 v108, 0, v14
	v_max_f32_e32 v109, 0, v15
	v_fmac_f32_e32 v50, v252, v108
	v_fmac_f32_e32 v51, v253, v109
	v_max_f32_e32 v210, 0, v16
	v_max_f32_e32 v211, 0, v17
	v_fmac_f32_e32 v50, v254, v210
	v_fmac_f32_e32 v51, v255, v211
	s_waitcnt lgkmcnt(1)
	v_mfma_f32_32x32x16_bf16 v[212:227], v[78:81], v[46:49], v[212:227]
	v_max_f32_e32 v108, 0, v18
	v_max_f32_e32 v109, 0, v19
	v_fmac_f32_e32 v50, v200, v108
	v_fmac_f32_e32 v51, v201, v109
	v_max_f32_e32 v210, 0, v20
	v_max_f32_e32 v211, 0, v21
	v_fmac_f32_e32 v50, v202, v210
	v_fmac_f32_e32 v51, v203, v211
	v_add_f32_e32 v50, v50, v51
	v_ashrrev_i32_e32 v51, 31, v50
	s_waitcnt lgkmcnt(0)
	v_mfma_f32_32x32x16_bf16 v[212:227], v[82:85], v[196:199], v[212:227]
	v_or_b32_e32 v51, 0x80000000, v51
	s_cmpk_gt_i32 s11, 272
	s_cselect_b64 vcc, -1, 0
	v_xor_b32_e32 v50, v51, v50
	v_cndmask_b32_e32 v50, v123, v50, vcc
	global_store_dword v243, v50, s[8:9]
	s_add_i32 m0, s10, 65536
	v_mfma_f32_32x32x16_bf16 v[6:21], v[86:89], v[38:41], 0
	global_load_lds_dwordx4 v102, s[6:7]
	s_add_i32 m0, s10, 66560
	s_nop 0
	global_load_lds_dwordx4 v110, s[6:7]
	s_add_i32 m0, s10, 67584
	s_nop 0
	global_load_lds_dwordx4 v112, s[6:7]
	s_add_i32 m0, s10, 68608
	s_nop 0
	global_load_lds_dwordx4 v193, s[6:7]
	s_add_u32 s6, s6, 0x8000
	s_addc_u32 s7, s7, 0
	v_max_f32_e32 v108, 0, v212
	v_max_f32_e32 v109, 0, v213
	v_mul_f32_e32 v0, v22, v108
	v_mul_f32_e32 v1, v23, v109
	v_max_f32_e32 v210, 0, v214
	v_max_f32_e32 v211, 0, v215
	v_fmac_f32_e32 v0, v24, v210
	v_fmac_f32_e32 v1, v25, v211
	v_max_f32_e32 v108, 0, v216
	v_max_f32_e32 v109, 0, v217
	v_fmac_f32_e32 v0, v26, v108
	v_fmac_f32_e32 v1, v27, v109
	v_mfma_f32_32x32x16_bf16 v[6:21], v[90:93], v[42:45], v[6:21]
	v_max_f32_e32 v210, 0, v218
	v_max_f32_e32 v211, 0, v219
	v_fmac_f32_e32 v0, v28, v210
	v_fmac_f32_e32 v1, v29, v211
	v_max_f32_e32 v108, 0, v220
	v_max_f32_e32 v109, 0, v221
	v_fmac_f32_e32 v0, v30, v108
	v_fmac_f32_e32 v1, v31, v109
	v_max_f32_e32 v210, 0, v222
	v_max_f32_e32 v211, 0, v223
	v_fmac_f32_e32 v0, v32, v210
	v_fmac_f32_e32 v1, v33, v211
	v_mfma_f32_32x32x16_bf16 v[6:21], v[94:97], v[46:49], v[6:21]
	v_max_f32_e32 v108, 0, v224
	v_max_f32_e32 v109, 0, v225
	v_fmac_f32_e32 v0, v34, v108
	v_fmac_f32_e32 v1, v35, v109
	v_max_f32_e32 v210, 0, v226
	v_max_f32_e32 v211, 0, v227
	v_fmac_f32_e32 v0, v36, v210
	v_fmac_f32_e32 v1, v37, v211
	v_add_f32_e32 v0, v0, v1
	v_ashrrev_i32_e32 v1, 31, v0
	v_mfma_f32_32x32x16_bf16 v[6:21], v[98:101], v[196:199], v[6:21]
	s_waitcnt vmcnt(10)
	ds_read_b128 v[38:41], v5 offset:10496
	ds_read_b128 v[42:45], v52 offset:10496
	ds_read_b128 v[46:49], v55 offset:10496
	ds_read_b128 v[196:199], v56 offset:10496
	v_or_b32_e32 v1, 0x80000000, v1
	s_cmpk_gt_i32 s11, 280
	s_cselect_b64 vcc, -1, 0
	v_xor_b32_e32 v0, v1, v0
	v_cndmask_b32_e32 v166, v123, v0, vcc
	s_nop 3
	s_waitcnt lgkmcnt(3)
	v_mfma_f32_32x32x16_bf16 v[212:227], v[70:73], v[38:41], 0
	v_max_f32_e32 v108, 0, v6
	v_max_f32_e32 v109, 0, v7
	v_mul_f32_e32 v50, v244, v108
	v_mul_f32_e32 v51, v245, v109
	v_max_f32_e32 v210, 0, v8
	v_max_f32_e32 v211, 0, v9
	v_fmac_f32_e32 v50, v246, v210
	v_fmac_f32_e32 v51, v247, v211
	v_max_f32_e32 v108, 0, v10
	v_max_f32_e32 v109, 0, v11
	v_fmac_f32_e32 v50, v248, v108
	v_fmac_f32_e32 v51, v249, v109
	s_waitcnt lgkmcnt(2)
	v_mfma_f32_32x32x16_bf16 v[212:227], v[74:77], v[42:45], v[212:227]
	v_max_f32_e32 v210, 0, v12
	v_max_f32_e32 v211, 0, v13
	v_fmac_f32_e32 v50, v250, v210
	v_fmac_f32_e32 v51, v251, v211
	v_max_f32_e32 v108, 0, v14
	v_max_f32_e32 v109, 0, v15
	v_fmac_f32_e32 v50, v252, v108
	v_fmac_f32_e32 v51, v253, v109
	v_max_f32_e32 v210, 0, v16
	v_max_f32_e32 v211, 0, v17
	v_fmac_f32_e32 v50, v254, v210
	v_fmac_f32_e32 v51, v255, v211
	s_waitcnt lgkmcnt(1)
	v_mfma_f32_32x32x16_bf16 v[212:227], v[78:81], v[46:49], v[212:227]
	v_max_f32_e32 v108, 0, v18
	v_max_f32_e32 v109, 0, v19
	v_fmac_f32_e32 v50, v200, v108
	v_fmac_f32_e32 v51, v201, v109
	v_max_f32_e32 v210, 0, v20
	v_max_f32_e32 v211, 0, v21
	v_fmac_f32_e32 v50, v202, v210
	v_fmac_f32_e32 v51, v203, v211
	v_add_f32_e32 v50, v50, v51
	v_ashrrev_i32_e32 v51, 31, v50
	s_waitcnt lgkmcnt(0)
	v_mfma_f32_32x32x16_bf16 v[212:227], v[82:85], v[196:199], v[212:227]
	v_or_b32_e32 v51, 0x80000000, v51
	s_cmpk_gt_i32 s11, 280
	s_cselect_b64 vcc, -1, 0
	v_xor_b32_e32 v50, v51, v50
	v_cndmask_b32_e32 v50, v123, v50, vcc
	global_store_dword v243, v50, s[8:9] offset:2048
	s_add_u32 s8, s8, 0x1000
	s_addc_u32 s9, s9, 0
	s_add_i32 m0, s10, 98304
	v_mfma_f32_32x32x16_bf16 v[6:21], v[86:89], v[38:41], 0
	global_load_lds_dwordx4 v102, s[6:7]
	s_add_i32 m0, s10, 99328
	s_nop 0
	global_load_lds_dwordx4 v110, s[6:7]
	s_add_i32 m0, s10, 100352
	s_nop 0
	global_load_lds_dwordx4 v112, s[6:7]
	s_add_i32 m0, s10, 101376
	s_nop 0
	global_load_lds_dwordx4 v193, s[6:7]
	s_add_u32 s6, s6, 0x8000
	s_addc_u32 s7, s7, 0
	v_max_f32_e32 v108, 0, v212
	v_max_f32_e32 v109, 0, v213
	v_mul_f32_e32 v0, v22, v108
	v_mul_f32_e32 v1, v23, v109
	v_max_f32_e32 v210, 0, v214
	v_max_f32_e32 v211, 0, v215
	v_fmac_f32_e32 v0, v24, v210
	v_fmac_f32_e32 v1, v25, v211
	v_max_f32_e32 v108, 0, v216
	v_max_f32_e32 v109, 0, v217
	v_fmac_f32_e32 v0, v26, v108
	v_fmac_f32_e32 v1, v27, v109
	v_mfma_f32_32x32x16_bf16 v[6:21], v[90:93], v[42:45], v[6:21]
	v_max_f32_e32 v210, 0, v218
	v_max_f32_e32 v211, 0, v219
	v_fmac_f32_e32 v0, v28, v210
	v_fmac_f32_e32 v1, v29, v211
	v_max_f32_e32 v108, 0, v220
	v_max_f32_e32 v109, 0, v221
	v_fmac_f32_e32 v0, v30, v108
	v_fmac_f32_e32 v1, v31, v109
	v_max_f32_e32 v210, 0, v222
	v_max_f32_e32 v211, 0, v223
	v_fmac_f32_e32 v0, v32, v210
	v_fmac_f32_e32 v1, v33, v211
	v_mfma_f32_32x32x16_bf16 v[6:21], v[94:97], v[46:49], v[6:21]
	v_max_f32_e32 v108, 0, v224
	v_max_f32_e32 v109, 0, v225
	v_fmac_f32_e32 v0, v34, v108
	v_fmac_f32_e32 v1, v35, v109
	v_max_f32_e32 v210, 0, v226
	v_max_f32_e32 v211, 0, v227
	v_fmac_f32_e32 v0, v36, v210
	v_fmac_f32_e32 v1, v37, v211
	v_add_f32_e32 v0, v0, v1
	v_ashrrev_i32_e32 v1, 31, v0
	v_mfma_f32_32x32x16_bf16 v[6:21], v[98:101], v[196:199], v[6:21]
	s_waitcnt vmcnt(10)
	ds_read_b128 v[38:41], v5 offset:43264
	ds_read_b128 v[42:45], v52 offset:43264
	ds_read_b128 v[46:49], v55 offset:43264
	ds_read_b128 v[196:199], v56 offset:43264
	v_or_b32_e32 v1, 0x80000000, v1
	s_cmpk_gt_i32 s11, 288
	s_cselect_b64 vcc, -1, 0
	v_xor_b32_e32 v0, v1, v0
	v_cndmask_b32_e32 v170, v123, v0, vcc
	s_nop 3
	s_waitcnt lgkmcnt(3)
	v_mfma_f32_32x32x16_bf16 v[212:227], v[70:73], v[38:41], 0
	v_max_f32_e32 v108, 0, v6
	v_max_f32_e32 v109, 0, v7
	v_mul_f32_e32 v50, v244, v108
	v_mul_f32_e32 v51, v245, v109
	v_max_f32_e32 v210, 0, v8
	v_max_f32_e32 v211, 0, v9
	v_fmac_f32_e32 v50, v246, v210
	v_fmac_f32_e32 v51, v247, v211
	v_max_f32_e32 v108, 0, v10
	v_max_f32_e32 v109, 0, v11
	v_fmac_f32_e32 v50, v248, v108
	v_fmac_f32_e32 v51, v249, v109
	s_waitcnt lgkmcnt(2)
	v_mfma_f32_32x32x16_bf16 v[212:227], v[74:77], v[42:45], v[212:227]
	v_max_f32_e32 v210, 0, v12
	v_max_f32_e32 v211, 0, v13
	v_fmac_f32_e32 v50, v250, v210
	v_fmac_f32_e32 v51, v251, v211
	v_max_f32_e32 v108, 0, v14
	v_max_f32_e32 v109, 0, v15
	v_fmac_f32_e32 v50, v252, v108
	v_fmac_f32_e32 v51, v253, v109
	v_max_f32_e32 v210, 0, v16
	v_max_f32_e32 v211, 0, v17
	v_fmac_f32_e32 v50, v254, v210
	v_fmac_f32_e32 v51, v255, v211
	s_waitcnt lgkmcnt(1)
	v_mfma_f32_32x32x16_bf16 v[212:227], v[78:81], v[46:49], v[212:227]
	v_max_f32_e32 v108, 0, v18
	v_max_f32_e32 v109, 0, v19
	v_fmac_f32_e32 v50, v200, v108
	v_fmac_f32_e32 v51, v201, v109
	v_max_f32_e32 v210, 0, v20
	v_max_f32_e32 v211, 0, v21
	v_fmac_f32_e32 v50, v202, v210
	v_fmac_f32_e32 v51, v203, v211
	v_add_f32_e32 v50, v50, v51
	v_ashrrev_i32_e32 v51, 31, v50
	s_waitcnt lgkmcnt(0)
	v_mfma_f32_32x32x16_bf16 v[212:227], v[82:85], v[196:199], v[212:227]
	v_or_b32_e32 v51, 0x80000000, v51
	s_cmpk_gt_i32 s11, 288
	s_cselect_b64 vcc, -1, 0
	v_xor_b32_e32 v50, v51, v50
	v_cndmask_b32_e32 v50, v123, v50, vcc
	global_store_dword v243, v50, s[8:9]
	s_add_i32 m0, s10, 0
	v_mfma_f32_32x32x16_bf16 v[6:21], v[86:89], v[38:41], 0
	global_load_lds_dwordx4 v102, s[6:7]
	s_add_i32 m0, s10, 1024
	s_nop 0
	global_load_lds_dwordx4 v110, s[6:7]
	s_add_i32 m0, s10, 2048
	s_nop 0
	global_load_lds_dwordx4 v112, s[6:7]
	s_add_i32 m0, s10, 3072
	s_nop 0
	global_load_lds_dwordx4 v193, s[6:7]
	s_add_u32 s6, s6, 0x8000
	s_addc_u32 s7, s7, 0
	v_max_f32_e32 v108, 0, v212
	v_max_f32_e32 v109, 0, v213
	v_mul_f32_e32 v0, v22, v108
	v_mul_f32_e32 v1, v23, v109
	v_max_f32_e32 v210, 0, v214
	v_max_f32_e32 v211, 0, v215
	v_fmac_f32_e32 v0, v24, v210
	v_fmac_f32_e32 v1, v25, v211
	v_max_f32_e32 v108, 0, v216
	v_max_f32_e32 v109, 0, v217
	v_fmac_f32_e32 v0, v26, v108
	v_fmac_f32_e32 v1, v27, v109
	v_mfma_f32_32x32x16_bf16 v[6:21], v[90:93], v[42:45], v[6:21]
	v_max_f32_e32 v210, 0, v218
	v_max_f32_e32 v211, 0, v219
	v_fmac_f32_e32 v0, v28, v210
	v_fmac_f32_e32 v1, v29, v211
	v_max_f32_e32 v108, 0, v220
	v_max_f32_e32 v109, 0, v221
	v_fmac_f32_e32 v0, v30, v108
	v_fmac_f32_e32 v1, v31, v109
	v_max_f32_e32 v210, 0, v222
	v_max_f32_e32 v211, 0, v223
	v_fmac_f32_e32 v0, v32, v210
	v_fmac_f32_e32 v1, v33, v211
	v_mfma_f32_32x32x16_bf16 v[6:21], v[94:97], v[46:49], v[6:21]
	v_max_f32_e32 v108, 0, v224
	v_max_f32_e32 v109, 0, v225
	v_fmac_f32_e32 v0, v34, v108
	v_fmac_f32_e32 v1, v35, v109
	v_max_f32_e32 v210, 0, v226
	v_max_f32_e32 v211, 0, v227
	v_fmac_f32_e32 v0, v36, v210
	v_fmac_f32_e32 v1, v37, v211
	v_add_f32_e32 v0, v0, v1
	v_ashrrev_i32_e32 v1, 31, v0
	v_mfma_f32_32x32x16_bf16 v[6:21], v[98:101], v[196:199], v[6:21]
	s_waitcnt vmcnt(10)
	v_add_u32_e32 v228, 0x10000, v5
	ds_read_b128 v[38:41], v228 offset:10496
	v_add_u32_e32 v228, 0x10000, v52
	ds_read_b128 v[42:45], v228 offset:10496
	v_add_u32_e32 v228, 0x10000, v55
	ds_read_b128 v[46:49], v228 offset:10496
	v_add_u32_e32 v228, 0x10000, v56
	ds_read_b128 v[196:199], v228 offset:10496
	v_or_b32_e32 v1, 0x80000000, v1
	s_cmpk_gt_i32 s11, 296
	s_cselect_b64 vcc, -1, 0
	v_xor_b32_e32 v0, v1, v0
	v_cndmask_b32_e32 v169, v123, v0, vcc
	s_nop 3
	s_waitcnt lgkmcnt(3)
	v_mfma_f32_32x32x16_bf16 v[212:227], v[70:73], v[38:41], 0
	v_max_f32_e32 v108, 0, v6
	v_max_f32_e32 v109, 0, v7
	v_mul_f32_e32 v50, v244, v108
	v_mul_f32_e32 v51, v245, v109
	v_max_f32_e32 v210, 0, v8
	v_max_f32_e32 v211, 0, v9
	v_fmac_f32_e32 v50, v246, v210
	v_fmac_f32_e32 v51, v247, v211
	v_max_f32_e32 v108, 0, v10
	v_max_f32_e32 v109, 0, v11
	v_fmac_f32_e32 v50, v248, v108
	v_fmac_f32_e32 v51, v249, v109
	s_waitcnt lgkmcnt(2)
	v_mfma_f32_32x32x16_bf16 v[212:227], v[74:77], v[42:45], v[212:227]
	v_max_f32_e32 v210, 0, v12
	v_max_f32_e32 v211, 0, v13
	v_fmac_f32_e32 v50, v250, v210
	v_fmac_f32_e32 v51, v251, v211
	v_max_f32_e32 v108, 0, v14
	v_max_f32_e32 v109, 0, v15
	v_fmac_f32_e32 v50, v252, v108
	v_fmac_f32_e32 v51, v253, v109
	v_max_f32_e32 v210, 0, v16
	v_max_f32_e32 v211, 0, v17
	v_fmac_f32_e32 v50, v254, v210
	v_fmac_f32_e32 v51, v255, v211
	s_waitcnt lgkmcnt(1)
	v_mfma_f32_32x32x16_bf16 v[212:227], v[78:81], v[46:49], v[212:227]
	v_max_f32_e32 v108, 0, v18
	v_max_f32_e32 v109, 0, v19
	v_fmac_f32_e32 v50, v200, v108
	v_fmac_f32_e32 v51, v201, v109
	v_max_f32_e32 v210, 0, v20
	v_max_f32_e32 v211, 0, v21
	v_fmac_f32_e32 v50, v202, v210
	v_fmac_f32_e32 v51, v203, v211
	v_add_f32_e32 v50, v50, v51
	v_ashrrev_i32_e32 v51, 31, v50
	s_waitcnt lgkmcnt(0)
	v_mfma_f32_32x32x16_bf16 v[212:227], v[82:85], v[196:199], v[212:227]
	v_or_b32_e32 v51, 0x80000000, v51
	s_cmpk_gt_i32 s11, 296
	s_cselect_b64 vcc, -1, 0
	v_xor_b32_e32 v50, v51, v50
	v_cndmask_b32_e32 v50, v123, v50, vcc
	global_store_dword v243, v50, s[8:9] offset:2048
	s_add_u32 s8, s8, 0x1000
	s_addc_u32 s9, s9, 0
	s_add_i32 m0, s10, 32768
	v_mfma_f32_32x32x16_bf16 v[6:21], v[86:89], v[38:41], 0
	global_load_lds_dwordx4 v102, s[6:7]
	s_add_i32 m0, s10, 33792
	s_nop 0
	global_load_lds_dwordx4 v110, s[6:7]
	s_add_i32 m0, s10, 34816
	s_nop 0
	global_load_lds_dwordx4 v112, s[6:7]
	s_add_i32 m0, s10, 35840
	s_nop 0
	global_load_lds_dwordx4 v193, s[6:7]
	s_add_u32 s6, s6, 0x8000
	s_addc_u32 s7, s7, 0
	v_max_f32_e32 v108, 0, v212
	v_max_f32_e32 v109, 0, v213
	v_mul_f32_e32 v0, v22, v108
	v_mul_f32_e32 v1, v23, v109
	v_max_f32_e32 v210, 0, v214
	v_max_f32_e32 v211, 0, v215
	v_fmac_f32_e32 v0, v24, v210
	v_fmac_f32_e32 v1, v25, v211
	v_max_f32_e32 v108, 0, v216
	v_max_f32_e32 v109, 0, v217
	v_fmac_f32_e32 v0, v26, v108
	v_fmac_f32_e32 v1, v27, v109
	v_mfma_f32_32x32x16_bf16 v[6:21], v[90:93], v[42:45], v[6:21]
	v_max_f32_e32 v210, 0, v218
	v_max_f32_e32 v211, 0, v219
	v_fmac_f32_e32 v0, v28, v210
	v_fmac_f32_e32 v1, v29, v211
	v_max_f32_e32 v108, 0, v220
	v_max_f32_e32 v109, 0, v221
	v_fmac_f32_e32 v0, v30, v108
	v_fmac_f32_e32 v1, v31, v109
	v_max_f32_e32 v210, 0, v222
	v_max_f32_e32 v211, 0, v223
	v_fmac_f32_e32 v0, v32, v210
	v_fmac_f32_e32 v1, v33, v211
	v_mfma_f32_32x32x16_bf16 v[6:21], v[94:97], v[46:49], v[6:21]
	v_max_f32_e32 v108, 0, v224
	v_max_f32_e32 v109, 0, v225
	v_fmac_f32_e32 v0, v34, v108
	v_fmac_f32_e32 v1, v35, v109
	v_max_f32_e32 v210, 0, v226
	v_max_f32_e32 v211, 0, v227
	v_fmac_f32_e32 v0, v36, v210
	v_fmac_f32_e32 v1, v37, v211
	v_add_f32_e32 v0, v0, v1
	v_ashrrev_i32_e32 v1, 31, v0
	v_mfma_f32_32x32x16_bf16 v[6:21], v[98:101], v[196:199], v[6:21]
	s_waitcnt vmcnt(10)
	v_add_u32_e32 v228, 0x10000, v5
	ds_read_b128 v[38:41], v228 offset:43264
	v_add_u32_e32 v228, 0x10000, v52
	ds_read_b128 v[42:45], v228 offset:43264
	v_add_u32_e32 v228, 0x10000, v55
	ds_read_b128 v[46:49], v228 offset:43264
	v_add_u32_e32 v228, 0x10000, v56
	ds_read_b128 v[196:199], v228 offset:43264
	v_or_b32_e32 v1, 0x80000000, v1
	s_cmpk_gt_i32 s11, 304
	s_cselect_b64 vcc, -1, 0
	v_xor_b32_e32 v0, v1, v0
	v_cndmask_b32_e32 v172, v123, v0, vcc
	s_nop 3
	s_waitcnt lgkmcnt(3)
	v_mfma_f32_32x32x16_bf16 v[212:227], v[70:73], v[38:41], 0
	v_max_f32_e32 v108, 0, v6
	v_max_f32_e32 v109, 0, v7
	v_mul_f32_e32 v50, v244, v108
	v_mul_f32_e32 v51, v245, v109
	v_max_f32_e32 v210, 0, v8
	v_max_f32_e32 v211, 0, v9
	v_fmac_f32_e32 v50, v246, v210
	v_fmac_f32_e32 v51, v247, v211
	v_max_f32_e32 v108, 0, v10
	v_max_f32_e32 v109, 0, v11
	v_fmac_f32_e32 v50, v248, v108
	v_fmac_f32_e32 v51, v249, v109
	s_waitcnt lgkmcnt(2)
	v_mfma_f32_32x32x16_bf16 v[212:227], v[74:77], v[42:45], v[212:227]
	v_max_f32_e32 v210, 0, v12
	v_max_f32_e32 v211, 0, v13
	v_fmac_f32_e32 v50, v250, v210
	v_fmac_f32_e32 v51, v251, v211
	v_max_f32_e32 v108, 0, v14
	v_max_f32_e32 v109, 0, v15
	v_fmac_f32_e32 v50, v252, v108
	v_fmac_f32_e32 v51, v253, v109
	v_max_f32_e32 v210, 0, v16
	v_max_f32_e32 v211, 0, v17
	v_fmac_f32_e32 v50, v254, v210
	v_fmac_f32_e32 v51, v255, v211
	s_waitcnt lgkmcnt(1)
	v_mfma_f32_32x32x16_bf16 v[212:227], v[78:81], v[46:49], v[212:227]
	v_max_f32_e32 v108, 0, v18
	v_max_f32_e32 v109, 0, v19
	v_fmac_f32_e32 v50, v200, v108
	v_fmac_f32_e32 v51, v201, v109
	v_max_f32_e32 v210, 0, v20
	v_max_f32_e32 v211, 0, v21
	v_fmac_f32_e32 v50, v202, v210
	v_fmac_f32_e32 v51, v203, v211
	v_add_f32_e32 v50, v50, v51
	v_ashrrev_i32_e32 v51, 31, v50
	s_waitcnt lgkmcnt(0)
	v_mfma_f32_32x32x16_bf16 v[212:227], v[82:85], v[196:199], v[212:227]
	v_or_b32_e32 v51, 0x80000000, v51
	s_cmpk_gt_i32 s11, 304
	s_cselect_b64 vcc, -1, 0
	v_xor_b32_e32 v50, v51, v50
	v_cndmask_b32_e32 v50, v123, v50, vcc
	global_store_dword v243, v50, s[8:9]
	s_add_i32 m0, s10, 65536
	v_mfma_f32_32x32x16_bf16 v[6:21], v[86:89], v[38:41], 0
	global_load_lds_dwordx4 v102, s[6:7]
	s_add_i32 m0, s10, 66560
	s_nop 0
	global_load_lds_dwordx4 v110, s[6:7]
	s_add_i32 m0, s10, 67584
	s_nop 0
	global_load_lds_dwordx4 v112, s[6:7]
	s_add_i32 m0, s10, 68608
	s_nop 0
	global_load_lds_dwordx4 v193, s[6:7]
	s_add_u32 s6, s6, 0x8000
	s_addc_u32 s7, s7, 0
	v_max_f32_e32 v108, 0, v212
	v_max_f32_e32 v109, 0, v213
	v_mul_f32_e32 v0, v22, v108
	v_mul_f32_e32 v1, v23, v109
	v_max_f32_e32 v210, 0, v214
	v_max_f32_e32 v211, 0, v215
	v_fmac_f32_e32 v0, v24, v210
	v_fmac_f32_e32 v1, v25, v211
	v_max_f32_e32 v108, 0, v216
	v_max_f32_e32 v109, 0, v217
	v_fmac_f32_e32 v0, v26, v108
	v_fmac_f32_e32 v1, v27, v109
	v_mfma_f32_32x32x16_bf16 v[6:21], v[90:93], v[42:45], v[6:21]
	v_max_f32_e32 v210, 0, v218
	v_max_f32_e32 v211, 0, v219
	v_fmac_f32_e32 v0, v28, v210
	v_fmac_f32_e32 v1, v29, v211
	v_max_f32_e32 v108, 0, v220
	v_max_f32_e32 v109, 0, v221
	v_fmac_f32_e32 v0, v30, v108
	v_fmac_f32_e32 v1, v31, v109
	v_max_f32_e32 v210, 0, v222
	v_max_f32_e32 v211, 0, v223
	v_fmac_f32_e32 v0, v32, v210
	v_fmac_f32_e32 v1, v33, v211
	v_mfma_f32_32x32x16_bf16 v[6:21], v[94:97], v[46:49], v[6:21]
	v_max_f32_e32 v108, 0, v224
	v_max_f32_e32 v109, 0, v225
	v_fmac_f32_e32 v0, v34, v108
	v_fmac_f32_e32 v1, v35, v109
	v_max_f32_e32 v210, 0, v226
	v_max_f32_e32 v211, 0, v227
	v_fmac_f32_e32 v0, v36, v210
	v_fmac_f32_e32 v1, v37, v211
	v_add_f32_e32 v0, v0, v1
	v_ashrrev_i32_e32 v1, 31, v0
	v_mfma_f32_32x32x16_bf16 v[6:21], v[98:101], v[196:199], v[6:21]
	s_waitcnt vmcnt(10)
	ds_read_b128 v[38:41], v5 offset:10496
	ds_read_b128 v[42:45], v52 offset:10496
	ds_read_b128 v[46:49], v55 offset:10496
	ds_read_b128 v[196:199], v56 offset:10496
	v_or_b32_e32 v1, 0x80000000, v1
	s_cmpk_gt_i32 s11, 312
	s_cselect_b64 vcc, -1, 0
	v_xor_b32_e32 v0, v1, v0
	v_cndmask_b32_e32 v171, v123, v0, vcc
	s_nop 3
	v_max_f32_e32 v108, 0, v6
	v_max_f32_e32 v109, 0, v7
	v_mul_f32_e32 v50, v244, v108
	v_mul_f32_e32 v51, v245, v109
	v_max_f32_e32 v210, 0, v8
	v_max_f32_e32 v211, 0, v9
	v_fmac_f32_e32 v50, v246, v210
	v_fmac_f32_e32 v51, v247, v211
	v_max_f32_e32 v108, 0, v10
	v_max_f32_e32 v109, 0, v11
	v_fmac_f32_e32 v50, v248, v108
	v_fmac_f32_e32 v51, v249, v109
	v_max_f32_e32 v210, 0, v12
	v_max_f32_e32 v211, 0, v13
	v_fmac_f32_e32 v50, v250, v210
	v_fmac_f32_e32 v51, v251, v211
	v_max_f32_e32 v108, 0, v14
	v_max_f32_e32 v109, 0, v15
	v_fmac_f32_e32 v50, v252, v108
	v_fmac_f32_e32 v51, v253, v109
	v_max_f32_e32 v210, 0, v16
	v_max_f32_e32 v211, 0, v17
	v_fmac_f32_e32 v50, v254, v210
	v_fmac_f32_e32 v51, v255, v211
	v_max_f32_e32 v108, 0, v18
	v_max_f32_e32 v109, 0, v19
	v_fmac_f32_e32 v50, v200, v108
	v_fmac_f32_e32 v51, v201, v109
	v_max_f32_e32 v210, 0, v20
	v_max_f32_e32 v211, 0, v21
	v_fmac_f32_e32 v50, v202, v210
	v_fmac_f32_e32 v51, v203, v211
	v_add_f32_e32 v50, v50, v51
	v_ashrrev_i32_e32 v51, 31, v50
	v_or_b32_e32 v51, 0x80000000, v51
	s_cmpk_gt_i32 s11, 312
	s_cselect_b64 vcc, -1, 0
	v_xor_b32_e32 v50, v51, v50
	v_cndmask_b32_e32 v50, v123, v50, vcc
	global_store_dword v243, v50, s[8:9] offset:2048
	s_add_u32 s8, s8, 0x1000
	s_addc_u32 s9, s9, 0
	s_cmpk_gt_i32 s81, 40
	s_cbranch_scc0 .Lix_fill_5
	s_waitcnt lgkmcnt(3)
	s_add_i32 m0, s10, 98304
	v_mfma_f32_32x32x16_bf16 v[212:227], v[70:73], v[38:41], 0
	global_load_lds_dwordx4 v102, s[6:7]
	s_waitcnt lgkmcnt(2)
	s_add_i32 m0, s10, 99328
	v_mfma_f32_32x32x16_bf16 v[212:227], v[74:77], v[42:45], v[212:227]
	global_load_lds_dwordx4 v110, s[6:7]
	s_waitcnt lgkmcnt(1)
	s_add_i32 m0, s10, 100352
	v_mfma_f32_32x32x16_bf16 v[212:227], v[78:81], v[46:49], v[212:227]
	global_load_lds_dwordx4 v112, s[6:7]
	s_waitcnt lgkmcnt(0)
	s_add_i32 m0, s10, 101376
	v_mfma_f32_32x32x16_bf16 v[212:227], v[82:85], v[196:199], v[212:227]
	global_load_lds_dwordx4 v193, s[6:7]
	s_add_u32 s6, s6, 0x8000
	s_addc_u32 s7, s7, 0
	v_mfma_f32_32x32x16_bf16 v[6:21], v[86:89], v[38:41], 0
	s_nop 7
	s_nop 2
	v_max_f32_e32 v108, 0, v212
	v_max_f32_e32 v109, 0, v213
	v_mul_f32_e32 v0, v22, v108
	v_mul_f32_e32 v1, v23, v109
	v_max_f32_e32 v210, 0, v214
	v_max_f32_e32 v211, 0, v215
	v_fmac_f32_e32 v0, v24, v210
	v_fmac_f32_e32 v1, v25, v211
	v_max_f32_e32 v108, 0, v216
	v_max_f32_e32 v109, 0, v217
	v_fmac_f32_e32 v0, v26, v108
	v_fmac_f32_e32 v1, v27, v109
	v_mfma_f32_32x32x16_bf16 v[6:21], v[90:93], v[42:45], v[6:21]
	v_max_f32_e32 v210, 0, v218
	v_max_f32_e32 v211, 0, v219
	v_fmac_f32_e32 v0, v28, v210
	v_fmac_f32_e32 v1, v29, v211
	v_max_f32_e32 v108, 0, v220
	v_max_f32_e32 v109, 0, v221
	v_fmac_f32_e32 v0, v30, v108
	v_fmac_f32_e32 v1, v31, v109
	v_max_f32_e32 v210, 0, v222
	v_max_f32_e32 v211, 0, v223
	v_fmac_f32_e32 v0, v32, v210
	v_fmac_f32_e32 v1, v33, v211
	v_mfma_f32_32x32x16_bf16 v[6:21], v[94:97], v[46:49], v[6:21]
	v_max_f32_e32 v108, 0, v224
	v_max_f32_e32 v109, 0, v225
	v_fmac_f32_e32 v0, v34, v108
	v_fmac_f32_e32 v1, v35, v109
	v_max_f32_e32 v210, 0, v226
	v_max_f32_e32 v211, 0, v227
	v_fmac_f32_e32 v0, v36, v210
	v_fmac_f32_e32 v1, v37, v211
	v_add_f32_e32 v0, v0, v1
	v_ashrrev_i32_e32 v1, 31, v0
	v_mfma_f32_32x32x16_bf16 v[6:21], v[98:101], v[196:199], v[6:21]
	s_waitcnt vmcnt(10)
	ds_read_b128 v[38:41], v5 offset:43264
	ds_read_b128 v[42:45], v52 offset:43264
	ds_read_b128 v[46:49], v55 offset:43264
	ds_read_b128 v[196:199], v56 offset:43264
	v_or_b32_e32 v1, 0x80000000, v1
	s_cmpk_gt_i32 s11, 320
	s_cselect_b64 vcc, -1, 0
	v_xor_b32_e32 v0, v1, v0
	v_cndmask_b32_e32 v174, v123, v0, vcc
	s_nop 3
	s_waitcnt lgkmcnt(3)
	v_mfma_f32_32x32x16_bf16 v[212:227], v[70:73], v[38:41], 0
	v_max_f32_e32 v108, 0, v6
	v_max_f32_e32 v109, 0, v7
	v_mul_f32_e32 v50, v244, v108
	v_mul_f32_e32 v51, v245, v109
	v_max_f32_e32 v210, 0, v8
	v_max_f32_e32 v211, 0, v9
	v_fmac_f32_e32 v50, v246, v210
	v_fmac_f32_e32 v51, v247, v211
	v_max_f32_e32 v108, 0, v10
	v_max_f32_e32 v109, 0, v11
	v_fmac_f32_e32 v50, v248, v108
	v_fmac_f32_e32 v51, v249, v109
	s_waitcnt lgkmcnt(2)
	v_mfma_f32_32x32x16_bf16 v[212:227], v[74:77], v[42:45], v[212:227]
	v_max_f32_e32 v210, 0, v12
	v_max_f32_e32 v211, 0, v13
	v_fmac_f32_e32 v50, v250, v210
	v_fmac_f32_e32 v51, v251, v211
	v_max_f32_e32 v108, 0, v14
	v_max_f32_e32 v109, 0, v15
	v_fmac_f32_e32 v50, v252, v108
	v_fmac_f32_e32 v51, v253, v109
	v_max_f32_e32 v210, 0, v16
	v_max_f32_e32 v211, 0, v17
	v_fmac_f32_e32 v50, v254, v210
	v_fmac_f32_e32 v51, v255, v211
	s_waitcnt lgkmcnt(1)
	v_mfma_f32_32x32x16_bf16 v[212:227], v[78:81], v[46:49], v[212:227]
	v_max_f32_e32 v108, 0, v18
	v_max_f32_e32 v109, 0, v19
	v_fmac_f32_e32 v50, v200, v108
	v_fmac_f32_e32 v51, v201, v109
	v_max_f32_e32 v210, 0, v20
	v_max_f32_e32 v211, 0, v21
	v_fmac_f32_e32 v50, v202, v210
	v_fmac_f32_e32 v51, v203, v211
	v_add_f32_e32 v50, v50, v51
	v_ashrrev_i32_e32 v51, 31, v50
	s_waitcnt lgkmcnt(0)
	v_mfma_f32_32x32x16_bf16 v[212:227], v[82:85], v[196:199], v[212:227]
	v_or_b32_e32 v51, 0x80000000, v51
	s_cmpk_gt_i32 s11, 320
	s_cselect_b64 vcc, -1, 0
	v_xor_b32_e32 v50, v51, v50
	v_cndmask_b32_e32 v50, v123, v50, vcc
	global_store_dword v243, v50, s[8:9]
	s_add_i32 m0, s10, 0
	v_mfma_f32_32x32x16_bf16 v[6:21], v[86:89], v[38:41], 0
	global_load_lds_dwordx4 v102, s[6:7]
	s_add_i32 m0, s10, 1024
	s_nop 0
	global_load_lds_dwordx4 v110, s[6:7]
	s_add_i32 m0, s10, 2048
	s_nop 0
	global_load_lds_dwordx4 v112, s[6:7]
	s_add_i32 m0, s10, 3072
	s_nop 0
	global_load_lds_dwordx4 v193, s[6:7]
	s_add_u32 s6, s6, 0x8000
	s_addc_u32 s7, s7, 0
	v_max_f32_e32 v108, 0, v212
	v_max_f32_e32 v109, 0, v213
	v_mul_f32_e32 v0, v22, v108
	v_mul_f32_e32 v1, v23, v109
	v_max_f32_e32 v210, 0, v214
	v_max_f32_e32 v211, 0, v215
	v_fmac_f32_e32 v0, v24, v210
	v_fmac_f32_e32 v1, v25, v211
	v_max_f32_e32 v108, 0, v216
	v_max_f32_e32 v109, 0, v217
	v_fmac_f32_e32 v0, v26, v108
	v_fmac_f32_e32 v1, v27, v109
	v_mfma_f32_32x32x16_bf16 v[6:21], v[90:93], v[42:45], v[6:21]
	v_max_f32_e32 v210, 0, v218
	v_max_f32_e32 v211, 0, v219
	v_fmac_f32_e32 v0, v28, v210
	v_fmac_f32_e32 v1, v29, v211
	v_max_f32_e32 v108, 0, v220
	v_max_f32_e32 v109, 0, v221
	v_fmac_f32_e32 v0, v30, v108
	v_fmac_f32_e32 v1, v31, v109
	v_max_f32_e32 v210, 0, v222
	v_max_f32_e32 v211, 0, v223
	v_fmac_f32_e32 v0, v32, v210
	v_fmac_f32_e32 v1, v33, v211
	v_mfma_f32_32x32x16_bf16 v[6:21], v[94:97], v[46:49], v[6:21]
	v_max_f32_e32 v108, 0, v224
	v_max_f32_e32 v109, 0, v225
	v_fmac_f32_e32 v0, v34, v108
	v_fmac_f32_e32 v1, v35, v109
	v_max_f32_e32 v210, 0, v226
	v_max_f32_e32 v211, 0, v227
	v_fmac_f32_e32 v0, v36, v210
	v_fmac_f32_e32 v1, v37, v211
	v_add_f32_e32 v0, v0, v1
	v_ashrrev_i32_e32 v1, 31, v0
	v_mfma_f32_32x32x16_bf16 v[6:21], v[98:101], v[196:199], v[6:21]
	s_waitcnt vmcnt(10)
	v_add_u32_e32 v228, 0x10000, v5
	ds_read_b128 v[38:41], v228 offset:10496
	v_add_u32_e32 v228, 0x10000, v52
	ds_read_b128 v[42:45], v228 offset:10496
	v_add_u32_e32 v228, 0x10000, v55
	ds_read_b128 v[46:49], v228 offset:10496
	v_add_u32_e32 v228, 0x10000, v56
	ds_read_b128 v[196:199], v228 offset:10496
	v_or_b32_e32 v1, 0x80000000, v1
	s_cmpk_gt_i32 s11, 328
	s_cselect_b64 vcc, -1, 0
	v_xor_b32_e32 v0, v1, v0
	v_cndmask_b32_e32 v173, v123, v0, vcc
	s_nop 3
	s_waitcnt lgkmcnt(3)
	v_mfma_f32_32x32x16_bf16 v[212:227], v[70:73], v[38:41], 0
	v_max_f32_e32 v108, 0, v6
	v_max_f32_e32 v109, 0, v7
	v_mul_f32_e32 v50, v244, v108
	v_mul_f32_e32 v51, v245, v109
	v_max_f32_e32 v210, 0, v8
	v_max_f32_e32 v211, 0, v9
	v_fmac_f32_e32 v50, v246, v210
	v_fmac_f32_e32 v51, v247, v211
	v_max_f32_e32 v108, 0, v10
	v_max_f32_e32 v109, 0, v11
	v_fmac_f32_e32 v50, v248, v108
	v_fmac_f32_e32 v51, v249, v109
	s_waitcnt lgkmcnt(2)
	v_mfma_f32_32x32x16_bf16 v[212:227], v[74:77], v[42:45], v[212:227]
	v_max_f32_e32 v210, 0, v12
	v_max_f32_e32 v211, 0, v13
	v_fmac_f32_e32 v50, v250, v210
	v_fmac_f32_e32 v51, v251, v211
	v_max_f32_e32 v108, 0, v14
	v_max_f32_e32 v109, 0, v15
	v_fmac_f32_e32 v50, v252, v108
	v_fmac_f32_e32 v51, v253, v109
	v_max_f32_e32 v210, 0, v16
	v_max_f32_e32 v211, 0, v17
	v_fmac_f32_e32 v50, v254, v210
	v_fmac_f32_e32 v51, v255, v211
	s_waitcnt lgkmcnt(1)
	v_mfma_f32_32x32x16_bf16 v[212:227], v[78:81], v[46:49], v[212:227]
	v_max_f32_e32 v108, 0, v18
	v_max_f32_e32 v109, 0, v19
	v_fmac_f32_e32 v50, v200, v108
	v_fmac_f32_e32 v51, v201, v109
	v_max_f32_e32 v210, 0, v20
	v_max_f32_e32 v211, 0, v21
	v_fmac_f32_e32 v50, v202, v210
	v_fmac_f32_e32 v51, v203, v211
	v_add_f32_e32 v50, v50, v51
	v_ashrrev_i32_e32 v51, 31, v50
	s_waitcnt lgkmcnt(0)
	v_mfma_f32_32x32x16_bf16 v[212:227], v[82:85], v[196:199], v[212:227]
	v_or_b32_e32 v51, 0x80000000, v51
	s_cmpk_gt_i32 s11, 328
	s_cselect_b64 vcc, -1, 0
	v_xor_b32_e32 v50, v51, v50
	v_cndmask_b32_e32 v50, v123, v50, vcc
	global_store_dword v243, v50, s[8:9] offset:2048
	s_add_u32 s8, s8, 0x1000
	s_addc_u32 s9, s9, 0
	s_add_i32 m0, s10, 32768
	v_mfma_f32_32x32x16_bf16 v[6:21], v[86:89], v[38:41], 0
	global_load_lds_dwordx4 v102, s[6:7]
	s_add_i32 m0, s10, 33792
	s_nop 0
	global_load_lds_dwordx4 v110, s[6:7]
	s_add_i32 m0, s10, 34816
	s_nop 0
	global_load_lds_dwordx4 v112, s[6:7]
	s_add_i32 m0, s10, 35840
	s_nop 0
	global_load_lds_dwordx4 v193, s[6:7]
	s_add_u32 s6, s6, 0x8000
	s_addc_u32 s7, s7, 0
	v_max_f32_e32 v108, 0, v212
	v_max_f32_e32 v109, 0, v213
	v_mul_f32_e32 v0, v22, v108
	v_mul_f32_e32 v1, v23, v109
	v_max_f32_e32 v210, 0, v214
	v_max_f32_e32 v211, 0, v215
	v_fmac_f32_e32 v0, v24, v210
	v_fmac_f32_e32 v1, v25, v211
	v_max_f32_e32 v108, 0, v216
	v_max_f32_e32 v109, 0, v217
	v_fmac_f32_e32 v0, v26, v108
	v_fmac_f32_e32 v1, v27, v109
	v_mfma_f32_32x32x16_bf16 v[6:21], v[90:93], v[42:45], v[6:21]
	v_max_f32_e32 v210, 0, v218
	v_max_f32_e32 v211, 0, v219
	v_fmac_f32_e32 v0, v28, v210
	v_fmac_f32_e32 v1, v29, v211
	v_max_f32_e32 v108, 0, v220
	v_max_f32_e32 v109, 0, v221
	v_fmac_f32_e32 v0, v30, v108
	v_fmac_f32_e32 v1, v31, v109
	v_max_f32_e32 v210, 0, v222
	v_max_f32_e32 v211, 0, v223
	v_fmac_f32_e32 v0, v32, v210
	v_fmac_f32_e32 v1, v33, v211
	v_mfma_f32_32x32x16_bf16 v[6:21], v[94:97], v[46:49], v[6:21]
	v_max_f32_e32 v108, 0, v224
	v_max_f32_e32 v109, 0, v225
	v_fmac_f32_e32 v0, v34, v108
	v_fmac_f32_e32 v1, v35, v109
	v_max_f32_e32 v210, 0, v226
	v_max_f32_e32 v211, 0, v227
	v_fmac_f32_e32 v0, v36, v210
	v_fmac_f32_e32 v1, v37, v211
	v_add_f32_e32 v0, v0, v1
	v_ashrrev_i32_e32 v1, 31, v0
	v_mfma_f32_32x32x16_bf16 v[6:21], v[98:101], v[196:199], v[6:21]
	s_waitcnt vmcnt(10)
	v_add_u32_e32 v228, 0x10000, v5
	ds_read_b128 v[38:41], v228 offset:43264
	v_add_u32_e32 v228, 0x10000, v52
	ds_read_b128 v[42:45], v228 offset:43264
	v_add_u32_e32 v228, 0x10000, v55
	ds_read_b128 v[46:49], v228 offset:43264
	v_add_u32_e32 v228, 0x10000, v56
	ds_read_b128 v[196:199], v228 offset:43264
	v_or_b32_e32 v1, 0x80000000, v1
	s_cmpk_gt_i32 s11, 336
	s_cselect_b64 vcc, -1, 0
	v_xor_b32_e32 v0, v1, v0
	v_cndmask_b32_e32 v176, v123, v0, vcc
	s_nop 3
	s_waitcnt lgkmcnt(3)
	v_mfma_f32_32x32x16_bf16 v[212:227], v[70:73], v[38:41], 0
	v_max_f32_e32 v108, 0, v6
	v_max_f32_e32 v109, 0, v7
	v_mul_f32_e32 v50, v244, v108
	v_mul_f32_e32 v51, v245, v109
	v_max_f32_e32 v210, 0, v8
	v_max_f32_e32 v211, 0, v9
	v_fmac_f32_e32 v50, v246, v210
	v_fmac_f32_e32 v51, v247, v211
	v_max_f32_e32 v108, 0, v10
	v_max_f32_e32 v109, 0, v11
	v_fmac_f32_e32 v50, v248, v108
	v_fmac_f32_e32 v51, v249, v109
	s_waitcnt lgkmcnt(2)
	v_mfma_f32_32x32x16_bf16 v[212:227], v[74:77], v[42:45], v[212:227]
	v_max_f32_e32 v210, 0, v12
	v_max_f32_e32 v211, 0, v13
	v_fmac_f32_e32 v50, v250, v210
	v_fmac_f32_e32 v51, v251, v211
	v_max_f32_e32 v108, 0, v14
	v_max_f32_e32 v109, 0, v15
	v_fmac_f32_e32 v50, v252, v108
	v_fmac_f32_e32 v51, v253, v109
	v_max_f32_e32 v210, 0, v16
	v_max_f32_e32 v211, 0, v17
	v_fmac_f32_e32 v50, v254, v210
	v_fmac_f32_e32 v51, v255, v211
	s_waitcnt lgkmcnt(1)
	v_mfma_f32_32x32x16_bf16 v[212:227], v[78:81], v[46:49], v[212:227]
	v_max_f32_e32 v108, 0, v18
	v_max_f32_e32 v109, 0, v19
	v_fmac_f32_e32 v50, v200, v108
	v_fmac_f32_e32 v51, v201, v109
	v_max_f32_e32 v210, 0, v20
	v_max_f32_e32 v211, 0, v21
	v_fmac_f32_e32 v50, v202, v210
	v_fmac_f32_e32 v51, v203, v211
	v_add_f32_e32 v50, v50, v51
	v_ashrrev_i32_e32 v51, 31, v50
	s_waitcnt lgkmcnt(0)
	v_mfma_f32_32x32x16_bf16 v[212:227], v[82:85], v[196:199], v[212:227]
	v_or_b32_e32 v51, 0x80000000, v51
	s_cmpk_gt_i32 s11, 336
	s_cselect_b64 vcc, -1, 0
	v_xor_b32_e32 v50, v51, v50
	v_cndmask_b32_e32 v50, v123, v50, vcc
	global_store_dword v243, v50, s[8:9]
	s_add_i32 m0, s10, 65536
	v_mfma_f32_32x32x16_bf16 v[6:21], v[86:89], v[38:41], 0
	global_load_lds_dwordx4 v102, s[6:7]
	s_add_i32 m0, s10, 66560
	s_nop 0
	global_load_lds_dwordx4 v110, s[6:7]
	s_add_i32 m0, s10, 67584
	s_nop 0
	global_load_lds_dwordx4 v112, s[6:7]
	s_add_i32 m0, s10, 68608
	s_nop 0
	global_load_lds_dwordx4 v193, s[6:7]
	s_add_u32 s6, s6, 0x8000
	s_addc_u32 s7, s7, 0
	v_max_f32_e32 v108, 0, v212
	v_max_f32_e32 v109, 0, v213
	v_mul_f32_e32 v0, v22, v108
	v_mul_f32_e32 v1, v23, v109
	v_max_f32_e32 v210, 0, v214
	v_max_f32_e32 v211, 0, v215
	v_fmac_f32_e32 v0, v24, v210
	v_fmac_f32_e32 v1, v25, v211
	v_max_f32_e32 v108, 0, v216
	v_max_f32_e32 v109, 0, v217
	v_fmac_f32_e32 v0, v26, v108
	v_fmac_f32_e32 v1, v27, v109
	v_mfma_f32_32x32x16_bf16 v[6:21], v[90:93], v[42:45], v[6:21]
	v_max_f32_e32 v210, 0, v218
	v_max_f32_e32 v211, 0, v219
	v_fmac_f32_e32 v0, v28, v210
	v_fmac_f32_e32 v1, v29, v211
	v_max_f32_e32 v108, 0, v220
	v_max_f32_e32 v109, 0, v221
	v_fmac_f32_e32 v0, v30, v108
	v_fmac_f32_e32 v1, v31, v109
	v_max_f32_e32 v210, 0, v222
	v_max_f32_e32 v211, 0, v223
	v_fmac_f32_e32 v0, v32, v210
	v_fmac_f32_e32 v1, v33, v211
	v_mfma_f32_32x32x16_bf16 v[6:21], v[94:97], v[46:49], v[6:21]
	v_max_f32_e32 v108, 0, v224
	v_max_f32_e32 v109, 0, v225
	v_fmac_f32_e32 v0, v34, v108
	v_fmac_f32_e32 v1, v35, v109
	v_max_f32_e32 v210, 0, v226
	v_max_f32_e32 v211, 0, v227
	v_fmac_f32_e32 v0, v36, v210
	v_fmac_f32_e32 v1, v37, v211
	v_add_f32_e32 v0, v0, v1
	v_ashrrev_i32_e32 v1, 31, v0
	v_mfma_f32_32x32x16_bf16 v[6:21], v[98:101], v[196:199], v[6:21]
	s_waitcnt vmcnt(10)
	ds_read_b128 v[38:41], v5 offset:10496
	ds_read_b128 v[42:45], v52 offset:10496
	ds_read_b128 v[46:49], v55 offset:10496
	ds_read_b128 v[196:199], v56 offset:10496
	v_or_b32_e32 v1, 0x80000000, v1
	s_cmpk_gt_i32 s11, 344
	s_cselect_b64 vcc, -1, 0
	v_xor_b32_e32 v0, v1, v0
	v_cndmask_b32_e32 v175, v123, v0, vcc
	s_nop 3
	s_waitcnt lgkmcnt(3)
	v_mfma_f32_32x32x16_bf16 v[212:227], v[70:73], v[38:41], 0
	v_max_f32_e32 v108, 0, v6
	v_max_f32_e32 v109, 0, v7
	v_mul_f32_e32 v50, v244, v108
	v_mul_f32_e32 v51, v245, v109
	v_max_f32_e32 v210, 0, v8
	v_max_f32_e32 v211, 0, v9
	v_fmac_f32_e32 v50, v246, v210
	v_fmac_f32_e32 v51, v247, v211
	v_max_f32_e32 v108, 0, v10
	v_max_f32_e32 v109, 0, v11
	v_fmac_f32_e32 v50, v248, v108
	v_fmac_f32_e32 v51, v249, v109
	s_waitcnt lgkmcnt(2)
	v_mfma_f32_32x32x16_bf16 v[212:227], v[74:77], v[42:45], v[212:227]
	v_max_f32_e32 v210, 0, v12
	v_max_f32_e32 v211, 0, v13
	v_fmac_f32_e32 v50, v250, v210
	v_fmac_f32_e32 v51, v251, v211
	v_max_f32_e32 v108, 0, v14
	v_max_f32_e32 v109, 0, v15
	v_fmac_f32_e32 v50, v252, v108
	v_fmac_f32_e32 v51, v253, v109
	v_max_f32_e32 v210, 0, v16
	v_max_f32_e32 v211, 0, v17
	v_fmac_f32_e32 v50, v254, v210
	v_fmac_f32_e32 v51, v255, v211
	s_waitcnt lgkmcnt(1)
	v_mfma_f32_32x32x16_bf16 v[212:227], v[78:81], v[46:49], v[212:227]
	v_max_f32_e32 v108, 0, v18
	v_max_f32_e32 v109, 0, v19
	v_fmac_f32_e32 v50, v200, v108
	v_fmac_f32_e32 v51, v201, v109
	v_max_f32_e32 v210, 0, v20
	v_max_f32_e32 v211, 0, v21
	v_fmac_f32_e32 v50, v202, v210
	v_fmac_f32_e32 v51, v203, v211
	v_add_f32_e32 v50, v50, v51
	v_ashrrev_i32_e32 v51, 31, v50
	s_waitcnt lgkmcnt(0)
	v_mfma_f32_32x32x16_bf16 v[212:227], v[82:85], v[196:199], v[212:227]
	v_or_b32_e32 v51, 0x80000000, v51
	s_cmpk_gt_i32 s11, 344
	s_cselect_b64 vcc, -1, 0
	v_xor_b32_e32 v50, v51, v50
	v_cndmask_b32_e32 v50, v123, v50, vcc
	global_store_dword v243, v50, s[8:9] offset:2048
	s_add_u32 s8, s8, 0x1000
	s_addc_u32 s9, s9, 0
	s_add_i32 m0, s10, 98304
	v_mfma_f32_32x32x16_bf16 v[6:21], v[86:89], v[38:41], 0
	global_load_lds_dwordx4 v102, s[6:7]
	s_add_i32 m0, s10, 99328
	s_nop 0
	global_load_lds_dwordx4 v110, s[6:7]
	s_add_i32 m0, s10, 100352
	s_nop 0
	global_load_lds_dwordx4 v112, s[6:7]
	s_add_i32 m0, s10, 101376
	s_nop 0
	global_load_lds_dwordx4 v193, s[6:7]
	s_add_u32 s6, s6, 0x8000
	s_addc_u32 s7, s7, 0
	v_max_f32_e32 v108, 0, v212
	v_max_f32_e32 v109, 0, v213
	v_mul_f32_e32 v0, v22, v108
	v_mul_f32_e32 v1, v23, v109
	v_max_f32_e32 v210, 0, v214
	v_max_f32_e32 v211, 0, v215
	v_fmac_f32_e32 v0, v24, v210
	v_fmac_f32_e32 v1, v25, v211
	v_max_f32_e32 v108, 0, v216
	v_max_f32_e32 v109, 0, v217
	v_fmac_f32_e32 v0, v26, v108
	v_fmac_f32_e32 v1, v27, v109
	v_mfma_f32_32x32x16_bf16 v[6:21], v[90:93], v[42:45], v[6:21]
	v_max_f32_e32 v210, 0, v218
	v_max_f32_e32 v211, 0, v219
	v_fmac_f32_e32 v0, v28, v210
	v_fmac_f32_e32 v1, v29, v211
	v_max_f32_e32 v108, 0, v220
	v_max_f32_e32 v109, 0, v221
	v_fmac_f32_e32 v0, v30, v108
	v_fmac_f32_e32 v1, v31, v109
	v_max_f32_e32 v210, 0, v222
	v_max_f32_e32 v211, 0, v223
	v_fmac_f32_e32 v0, v32, v210
	v_fmac_f32_e32 v1, v33, v211
	v_mfma_f32_32x32x16_bf16 v[6:21], v[94:97], v[46:49], v[6:21]
	v_max_f32_e32 v108, 0, v224
	v_max_f32_e32 v109, 0, v225
	v_fmac_f32_e32 v0, v34, v108
	v_fmac_f32_e32 v1, v35, v109
	v_max_f32_e32 v210, 0, v226
	v_max_f32_e32 v211, 0, v227
	v_fmac_f32_e32 v0, v36, v210
	v_fmac_f32_e32 v1, v37, v211
	v_add_f32_e32 v0, v0, v1
	v_ashrrev_i32_e32 v1, 31, v0
	v_mfma_f32_32x32x16_bf16 v[6:21], v[98:101], v[196:199], v[6:21]
	s_waitcnt vmcnt(10)
	ds_read_b128 v[38:41], v5 offset:43264
	ds_read_b128 v[42:45], v52 offset:43264
	ds_read_b128 v[46:49], v55 offset:43264
	ds_read_b128 v[196:199], v56 offset:43264
	v_or_b32_e32 v1, 0x80000000, v1
	s_cmpk_gt_i32 s11, 352
	s_cselect_b64 vcc, -1, 0
	v_xor_b32_e32 v0, v1, v0
	v_cndmask_b32_e32 v178, v123, v0, vcc
	s_nop 3
	s_waitcnt lgkmcnt(3)
	v_mfma_f32_32x32x16_bf16 v[212:227], v[70:73], v[38:41], 0
	v_max_f32_e32 v108, 0, v6
	v_max_f32_e32 v109, 0, v7
	v_mul_f32_e32 v50, v244, v108
	v_mul_f32_e32 v51, v245, v109
	v_max_f32_e32 v210, 0, v8
	v_max_f32_e32 v211, 0, v9
	v_fmac_f32_e32 v50, v246, v210
	v_fmac_f32_e32 v51, v247, v211
	v_max_f32_e32 v108, 0, v10
	v_max_f32_e32 v109, 0, v11
	v_fmac_f32_e32 v50, v248, v108
	v_fmac_f32_e32 v51, v249, v109
	s_waitcnt lgkmcnt(2)
	v_mfma_f32_32x32x16_bf16 v[212:227], v[74:77], v[42:45], v[212:227]
	v_max_f32_e32 v210, 0, v12
	v_max_f32_e32 v211, 0, v13
	v_fmac_f32_e32 v50, v250, v210
	v_fmac_f32_e32 v51, v251, v211
	v_max_f32_e32 v108, 0, v14
	v_max_f32_e32 v109, 0, v15
	v_fmac_f32_e32 v50, v252, v108
	v_fmac_f32_e32 v51, v253, v109
	v_max_f32_e32 v210, 0, v16
	v_max_f32_e32 v211, 0, v17
	v_fmac_f32_e32 v50, v254, v210
	v_fmac_f32_e32 v51, v255, v211
	s_waitcnt lgkmcnt(1)
	v_mfma_f32_32x32x16_bf16 v[212:227], v[78:81], v[46:49], v[212:227]
	v_max_f32_e32 v108, 0, v18
	v_max_f32_e32 v109, 0, v19
	v_fmac_f32_e32 v50, v200, v108
	v_fmac_f32_e32 v51, v201, v109
	v_max_f32_e32 v210, 0, v20
	v_max_f32_e32 v211, 0, v21
	v_fmac_f32_e32 v50, v202, v210
	v_fmac_f32_e32 v51, v203, v211
	v_add_f32_e32 v50, v50, v51
	v_ashrrev_i32_e32 v51, 31, v50
	s_waitcnt lgkmcnt(0)
	v_mfma_f32_32x32x16_bf16 v[212:227], v[82:85], v[196:199], v[212:227]
	v_or_b32_e32 v51, 0x80000000, v51
	s_cmpk_gt_i32 s11, 352
	s_cselect_b64 vcc, -1, 0
	v_xor_b32_e32 v50, v51, v50
	v_cndmask_b32_e32 v50, v123, v50, vcc
	global_store_dword v243, v50, s[8:9]
	s_add_i32 m0, s10, 0
	v_mfma_f32_32x32x16_bf16 v[6:21], v[86:89], v[38:41], 0
	global_load_lds_dwordx4 v102, s[6:7]
	s_add_i32 m0, s10, 1024
	s_nop 0
	global_load_lds_dwordx4 v110, s[6:7]
	s_add_i32 m0, s10, 2048
	s_nop 0
	global_load_lds_dwordx4 v112, s[6:7]
	s_add_i32 m0, s10, 3072
	s_nop 0
	global_load_lds_dwordx4 v193, s[6:7]
	s_add_u32 s6, s6, 0x8000
	s_addc_u32 s7, s7, 0
	v_max_f32_e32 v108, 0, v212
	v_max_f32_e32 v109, 0, v213
	v_mul_f32_e32 v0, v22, v108
	v_mul_f32_e32 v1, v23, v109
	v_max_f32_e32 v210, 0, v214
	v_max_f32_e32 v211, 0, v215
	v_fmac_f32_e32 v0, v24, v210
	v_fmac_f32_e32 v1, v25, v211
	v_max_f32_e32 v108, 0, v216
	v_max_f32_e32 v109, 0, v217
	v_fmac_f32_e32 v0, v26, v108
	v_fmac_f32_e32 v1, v27, v109
	v_mfma_f32_32x32x16_bf16 v[6:21], v[90:93], v[42:45], v[6:21]
	v_max_f32_e32 v210, 0, v218
	v_max_f32_e32 v211, 0, v219
	v_fmac_f32_e32 v0, v28, v210
	v_fmac_f32_e32 v1, v29, v211
	v_max_f32_e32 v108, 0, v220
	v_max_f32_e32 v109, 0, v221
	v_fmac_f32_e32 v0, v30, v108
	v_fmac_f32_e32 v1, v31, v109
	v_max_f32_e32 v210, 0, v222
	v_max_f32_e32 v211, 0, v223
	v_fmac_f32_e32 v0, v32, v210
	v_fmac_f32_e32 v1, v33, v211
	v_mfma_f32_32x32x16_bf16 v[6:21], v[94:97], v[46:49], v[6:21]
	v_max_f32_e32 v108, 0, v224
	v_max_f32_e32 v109, 0, v225
	v_fmac_f32_e32 v0, v34, v108
	v_fmac_f32_e32 v1, v35, v109
	v_max_f32_e32 v210, 0, v226
	v_max_f32_e32 v211, 0, v227
	v_fmac_f32_e32 v0, v36, v210
	v_fmac_f32_e32 v1, v37, v211
	v_add_f32_e32 v0, v0, v1
	v_ashrrev_i32_e32 v1, 31, v0
	v_mfma_f32_32x32x16_bf16 v[6:21], v[98:101], v[196:199], v[6:21]
	s_waitcnt vmcnt(10)
	v_add_u32_e32 v228, 0x10000, v5
	ds_read_b128 v[38:41], v228 offset:10496
	v_add_u32_e32 v228, 0x10000, v52
	ds_read_b128 v[42:45], v228 offset:10496
	v_add_u32_e32 v228, 0x10000, v55
	ds_read_b128 v[46:49], v228 offset:10496
	v_add_u32_e32 v228, 0x10000, v56
	ds_read_b128 v[196:199], v228 offset:10496
	v_or_b32_e32 v1, 0x80000000, v1
	s_cmpk_gt_i32 s11, 360
	s_cselect_b64 vcc, -1, 0
	v_xor_b32_e32 v0, v1, v0
	v_cndmask_b32_e32 v177, v123, v0, vcc
	s_nop 3
	s_waitcnt lgkmcnt(3)
	v_mfma_f32_32x32x16_bf16 v[212:227], v[70:73], v[38:41], 0
	v_max_f32_e32 v108, 0, v6
	v_max_f32_e32 v109, 0, v7
	v_mul_f32_e32 v50, v244, v108
	v_mul_f32_e32 v51, v245, v109
	v_max_f32_e32 v210, 0, v8
	v_max_f32_e32 v211, 0, v9
	v_fmac_f32_e32 v50, v246, v210
	v_fmac_f32_e32 v51, v247, v211
	v_max_f32_e32 v108, 0, v10
	v_max_f32_e32 v109, 0, v11
	v_fmac_f32_e32 v50, v248, v108
	v_fmac_f32_e32 v51, v249, v109
	s_waitcnt lgkmcnt(2)
	v_mfma_f32_32x32x16_bf16 v[212:227], v[74:77], v[42:45], v[212:227]
	v_max_f32_e32 v210, 0, v12
	v_max_f32_e32 v211, 0, v13
	v_fmac_f32_e32 v50, v250, v210
	v_fmac_f32_e32 v51, v251, v211
	v_max_f32_e32 v108, 0, v14
	v_max_f32_e32 v109, 0, v15
	v_fmac_f32_e32 v50, v252, v108
	v_fmac_f32_e32 v51, v253, v109
	v_max_f32_e32 v210, 0, v16
	v_max_f32_e32 v211, 0, v17
	v_fmac_f32_e32 v50, v254, v210
	v_fmac_f32_e32 v51, v255, v211
	s_waitcnt lgkmcnt(1)
	v_mfma_f32_32x32x16_bf16 v[212:227], v[78:81], v[46:49], v[212:227]
	v_max_f32_e32 v108, 0, v18
	v_max_f32_e32 v109, 0, v19
	v_fmac_f32_e32 v50, v200, v108
	v_fmac_f32_e32 v51, v201, v109
	v_max_f32_e32 v210, 0, v20
	v_max_f32_e32 v211, 0, v21
	v_fmac_f32_e32 v50, v202, v210
	v_fmac_f32_e32 v51, v203, v211
	v_add_f32_e32 v50, v50, v51
	v_ashrrev_i32_e32 v51, 31, v50
	s_waitcnt lgkmcnt(0)
	v_mfma_f32_32x32x16_bf16 v[212:227], v[82:85], v[196:199], v[212:227]
	v_or_b32_e32 v51, 0x80000000, v51
	s_cmpk_gt_i32 s11, 360
	s_cselect_b64 vcc, -1, 0
	v_xor_b32_e32 v50, v51, v50
	v_cndmask_b32_e32 v50, v123, v50, vcc
	global_store_dword v243, v50, s[8:9] offset:2048
	s_add_u32 s8, s8, 0x1000
	s_addc_u32 s9, s9, 0
	s_add_i32 m0, s10, 32768
	v_mfma_f32_32x32x16_bf16 v[6:21], v[86:89], v[38:41], 0
	global_load_lds_dwordx4 v102, s[6:7]
	s_add_i32 m0, s10, 33792
	s_nop 0
	global_load_lds_dwordx4 v110, s[6:7]
	s_add_i32 m0, s10, 34816
	s_nop 0
	global_load_lds_dwordx4 v112, s[6:7]
	s_add_i32 m0, s10, 35840
	s_nop 0
	global_load_lds_dwordx4 v193, s[6:7]
	s_add_u32 s6, s6, 0x8000
	s_addc_u32 s7, s7, 0
	v_max_f32_e32 v108, 0, v212
	v_max_f32_e32 v109, 0, v213
	v_mul_f32_e32 v0, v22, v108
	v_mul_f32_e32 v1, v23, v109
	v_max_f32_e32 v210, 0, v214
	v_max_f32_e32 v211, 0, v215
	v_fmac_f32_e32 v0, v24, v210
	v_fmac_f32_e32 v1, v25, v211
	v_max_f32_e32 v108, 0, v216
	v_max_f32_e32 v109, 0, v217
	v_fmac_f32_e32 v0, v26, v108
	v_fmac_f32_e32 v1, v27, v109
	v_mfma_f32_32x32x16_bf16 v[6:21], v[90:93], v[42:45], v[6:21]
	v_max_f32_e32 v210, 0, v218
	v_max_f32_e32 v211, 0, v219
	v_fmac_f32_e32 v0, v28, v210
	v_fmac_f32_e32 v1, v29, v211
	v_max_f32_e32 v108, 0, v220
	v_max_f32_e32 v109, 0, v221
	v_fmac_f32_e32 v0, v30, v108
	v_fmac_f32_e32 v1, v31, v109
	v_max_f32_e32 v210, 0, v222
	v_max_f32_e32 v211, 0, v223
	v_fmac_f32_e32 v0, v32, v210
	v_fmac_f32_e32 v1, v33, v211
	v_mfma_f32_32x32x16_bf16 v[6:21], v[94:97], v[46:49], v[6:21]
	v_max_f32_e32 v108, 0, v224
	v_max_f32_e32 v109, 0, v225
	v_fmac_f32_e32 v0, v34, v108
	v_fmac_f32_e32 v1, v35, v109
	v_max_f32_e32 v210, 0, v226
	v_max_f32_e32 v211, 0, v227
	v_fmac_f32_e32 v0, v36, v210
	v_fmac_f32_e32 v1, v37, v211
	v_add_f32_e32 v0, v0, v1
	v_ashrrev_i32_e32 v1, 31, v0
	v_mfma_f32_32x32x16_bf16 v[6:21], v[98:101], v[196:199], v[6:21]
	s_waitcnt vmcnt(10)
	v_add_u32_e32 v228, 0x10000, v5
	ds_read_b128 v[38:41], v228 offset:43264
	v_add_u32_e32 v228, 0x10000, v52
	ds_read_b128 v[42:45], v228 offset:43264
	v_add_u32_e32 v228, 0x10000, v55
	ds_read_b128 v[46:49], v228 offset:43264
	v_add_u32_e32 v228, 0x10000, v56
	ds_read_b128 v[196:199], v228 offset:43264
	v_or_b32_e32 v1, 0x80000000, v1
	s_cmpk_gt_i32 s11, 368
	s_cselect_b64 vcc, -1, 0
	v_xor_b32_e32 v0, v1, v0
	v_cndmask_b32_e32 v179, v123, v0, vcc
	s_nop 3
	s_waitcnt lgkmcnt(3)
	v_mfma_f32_32x32x16_bf16 v[212:227], v[70:73], v[38:41], 0
	v_max_f32_e32 v108, 0, v6
	v_max_f32_e32 v109, 0, v7
	v_mul_f32_e32 v50, v244, v108
	v_mul_f32_e32 v51, v245, v109
	v_max_f32_e32 v210, 0, v8
	v_max_f32_e32 v211, 0, v9
	v_fmac_f32_e32 v50, v246, v210
	v_fmac_f32_e32 v51, v247, v211
	v_max_f32_e32 v108, 0, v10
	v_max_f32_e32 v109, 0, v11
	v_fmac_f32_e32 v50, v248, v108
	v_fmac_f32_e32 v51, v249, v109
	s_waitcnt lgkmcnt(2)
	v_mfma_f32_32x32x16_bf16 v[212:227], v[74:77], v[42:45], v[212:227]
	v_max_f32_e32 v210, 0, v12
	v_max_f32_e32 v211, 0, v13
	v_fmac_f32_e32 v50, v250, v210
	v_fmac_f32_e32 v51, v251, v211
	v_max_f32_e32 v108, 0, v14
	v_max_f32_e32 v109, 0, v15
	v_fmac_f32_e32 v50, v252, v108
	v_fmac_f32_e32 v51, v253, v109
	v_max_f32_e32 v210, 0, v16
	v_max_f32_e32 v211, 0, v17
	v_fmac_f32_e32 v50, v254, v210
	v_fmac_f32_e32 v51, v255, v211
	s_waitcnt lgkmcnt(1)
	v_mfma_f32_32x32x16_bf16 v[212:227], v[78:81], v[46:49], v[212:227]
	v_max_f32_e32 v108, 0, v18
	v_max_f32_e32 v109, 0, v19
	v_fmac_f32_e32 v50, v200, v108
	v_fmac_f32_e32 v51, v201, v109
	v_max_f32_e32 v210, 0, v20
	v_max_f32_e32 v211, 0, v21
	v_fmac_f32_e32 v50, v202, v210
	v_fmac_f32_e32 v51, v203, v211
	v_add_f32_e32 v50, v50, v51
	v_ashrrev_i32_e32 v51, 31, v50
	s_waitcnt lgkmcnt(0)
	v_mfma_f32_32x32x16_bf16 v[212:227], v[82:85], v[196:199], v[212:227]
	v_or_b32_e32 v51, 0x80000000, v51
	s_cmpk_gt_i32 s11, 368
	s_cselect_b64 vcc, -1, 0
	v_xor_b32_e32 v50, v51, v50
	v_cndmask_b32_e32 v50, v123, v50, vcc
	global_store_dword v243, v50, s[8:9]
	s_add_i32 m0, s10, 65536
	v_mfma_f32_32x32x16_bf16 v[6:21], v[86:89], v[38:41], 0
	global_load_lds_dwordx4 v102, s[6:7]
	s_add_i32 m0, s10, 66560
	s_nop 0
	global_load_lds_dwordx4 v110, s[6:7]
	s_add_i32 m0, s10, 67584
	s_nop 0
	global_load_lds_dwordx4 v112, s[6:7]
	s_add_i32 m0, s10, 68608
	s_nop 0
	global_load_lds_dwordx4 v193, s[6:7]
	s_add_u32 s6, s6, 0x8000
	s_addc_u32 s7, s7, 0
	v_max_f32_e32 v108, 0, v212
	v_max_f32_e32 v109, 0, v213
	v_mul_f32_e32 v0, v22, v108
	v_mul_f32_e32 v1, v23, v109
	v_max_f32_e32 v210, 0, v214
	v_max_f32_e32 v211, 0, v215
	v_fmac_f32_e32 v0, v24, v210
	v_fmac_f32_e32 v1, v25, v211
	v_max_f32_e32 v108, 0, v216
	v_max_f32_e32 v109, 0, v217
	v_fmac_f32_e32 v0, v26, v108
	v_fmac_f32_e32 v1, v27, v109
	v_mfma_f32_32x32x16_bf16 v[6:21], v[90:93], v[42:45], v[6:21]
	v_max_f32_e32 v210, 0, v218
	v_max_f32_e32 v211, 0, v219
	v_fmac_f32_e32 v0, v28, v210
	v_fmac_f32_e32 v1, v29, v211
	v_max_f32_e32 v108, 0, v220
	v_max_f32_e32 v109, 0, v221
	v_fmac_f32_e32 v0, v30, v108
	v_fmac_f32_e32 v1, v31, v109
	v_max_f32_e32 v210, 0, v222
	v_max_f32_e32 v211, 0, v223
	v_fmac_f32_e32 v0, v32, v210
	v_fmac_f32_e32 v1, v33, v211
	v_mfma_f32_32x32x16_bf16 v[6:21], v[94:97], v[46:49], v[6:21]
	v_max_f32_e32 v108, 0, v224
	v_max_f32_e32 v109, 0, v225
	v_fmac_f32_e32 v0, v34, v108
	v_fmac_f32_e32 v1, v35, v109
	v_max_f32_e32 v210, 0, v226
	v_max_f32_e32 v211, 0, v227
	v_fmac_f32_e32 v0, v36, v210
	v_fmac_f32_e32 v1, v37, v211
	v_add_f32_e32 v0, v0, v1
	v_ashrrev_i32_e32 v1, 31, v0
	v_mfma_f32_32x32x16_bf16 v[6:21], v[98:101], v[196:199], v[6:21]
	s_waitcnt vmcnt(10)
	ds_read_b128 v[38:41], v5 offset:10496
	ds_read_b128 v[42:45], v52 offset:10496
	ds_read_b128 v[46:49], v55 offset:10496
	ds_read_b128 v[196:199], v56 offset:10496
	v_or_b32_e32 v1, 0x80000000, v1
	s_cmpk_gt_i32 s11, 376
	s_cselect_b64 vcc, -1, 0
	v_xor_b32_e32 v0, v1, v0
	v_cndmask_b32_e32 v168, v123, v0, vcc
	s_nop 3
	v_max_f32_e32 v108, 0, v6
	v_max_f32_e32 v109, 0, v7
	v_mul_f32_e32 v50, v244, v108
	v_mul_f32_e32 v51, v245, v109
	v_max_f32_e32 v210, 0, v8
	v_max_f32_e32 v211, 0, v9
	v_fmac_f32_e32 v50, v246, v210
	v_fmac_f32_e32 v51, v247, v211
	v_max_f32_e32 v108, 0, v10
	v_max_f32_e32 v109, 0, v11
	v_fmac_f32_e32 v50, v248, v108
	v_fmac_f32_e32 v51, v249, v109
	v_max_f32_e32 v210, 0, v12
	v_max_f32_e32 v211, 0, v13
	v_fmac_f32_e32 v50, v250, v210
	v_fmac_f32_e32 v51, v251, v211
	v_max_f32_e32 v108, 0, v14
	v_max_f32_e32 v109, 0, v15
	v_fmac_f32_e32 v50, v252, v108
	v_fmac_f32_e32 v51, v253, v109
	v_max_f32_e32 v210, 0, v16
	v_max_f32_e32 v211, 0, v17
	v_fmac_f32_e32 v50, v254, v210
	v_fmac_f32_e32 v51, v255, v211
	v_max_f32_e32 v108, 0, v18
	v_max_f32_e32 v109, 0, v19
	v_fmac_f32_e32 v50, v200, v108
	v_fmac_f32_e32 v51, v201, v109
	v_max_f32_e32 v210, 0, v20
	v_max_f32_e32 v211, 0, v21
	v_fmac_f32_e32 v50, v202, v210
	v_fmac_f32_e32 v51, v203, v211
	v_add_f32_e32 v50, v50, v51
	v_ashrrev_i32_e32 v51, 31, v50
	v_or_b32_e32 v51, 0x80000000, v51
	s_cmpk_gt_i32 s11, 376
	s_cselect_b64 vcc, -1, 0
	v_xor_b32_e32 v50, v51, v50
	v_cndmask_b32_e32 v50, v123, v50, vcc
	global_store_dword v243, v50, s[8:9] offset:2048
	s_add_u32 s8, s8, 0x1000
	s_addc_u32 s9, s9, 0
	s_cmpk_gt_i32 s81, 48
	s_cbranch_scc0 .Lix_fill_6
	s_waitcnt lgkmcnt(3)
	s_add_i32 m0, s10, 98304
	v_mfma_f32_32x32x16_bf16 v[212:227], v[70:73], v[38:41], 0
	global_load_lds_dwordx4 v102, s[6:7]
	s_waitcnt lgkmcnt(2)
	s_add_i32 m0, s10, 99328
	v_mfma_f32_32x32x16_bf16 v[212:227], v[74:77], v[42:45], v[212:227]
	global_load_lds_dwordx4 v110, s[6:7]
	s_waitcnt lgkmcnt(1)
	s_add_i32 m0, s10, 100352
	v_mfma_f32_32x32x16_bf16 v[212:227], v[78:81], v[46:49], v[212:227]
	global_load_lds_dwordx4 v112, s[6:7]
	s_waitcnt lgkmcnt(0)
	s_add_i32 m0, s10, 101376
	v_mfma_f32_32x32x16_bf16 v[212:227], v[82:85], v[196:199], v[212:227]
	global_load_lds_dwordx4 v193, s[6:7]
	s_add_u32 s6, s6, 0x8000
	s_addc_u32 s7, s7, 0
	v_mfma_f32_32x32x16_bf16 v[6:21], v[86:89], v[38:41], 0
	s_nop 7
	s_nop 2
	v_max_f32_e32 v108, 0, v212
	v_max_f32_e32 v109, 0, v213
	v_mul_f32_e32 v0, v22, v108
	v_mul_f32_e32 v1, v23, v109
	v_max_f32_e32 v210, 0, v214
	v_max_f32_e32 v211, 0, v215
	v_fmac_f32_e32 v0, v24, v210
	v_fmac_f32_e32 v1, v25, v211
	v_max_f32_e32 v108, 0, v216
	v_max_f32_e32 v109, 0, v217
	v_fmac_f32_e32 v0, v26, v108
	v_fmac_f32_e32 v1, v27, v109
	v_mfma_f32_32x32x16_bf16 v[6:21], v[90:93], v[42:45], v[6:21]
	v_max_f32_e32 v210, 0, v218
	v_max_f32_e32 v211, 0, v219
	v_fmac_f32_e32 v0, v28, v210
	v_fmac_f32_e32 v1, v29, v211
	v_max_f32_e32 v108, 0, v220
	v_max_f32_e32 v109, 0, v221
	v_fmac_f32_e32 v0, v30, v108
	v_fmac_f32_e32 v1, v31, v109
	v_max_f32_e32 v210, 0, v222
	v_max_f32_e32 v211, 0, v223
	v_fmac_f32_e32 v0, v32, v210
	v_fmac_f32_e32 v1, v33, v211
	v_mfma_f32_32x32x16_bf16 v[6:21], v[94:97], v[46:49], v[6:21]
	v_max_f32_e32 v108, 0, v224
	v_max_f32_e32 v109, 0, v225
	v_fmac_f32_e32 v0, v34, v108
	v_fmac_f32_e32 v1, v35, v109
	v_max_f32_e32 v210, 0, v226
	v_max_f32_e32 v211, 0, v227
	v_fmac_f32_e32 v0, v36, v210
	v_fmac_f32_e32 v1, v37, v211
	v_add_f32_e32 v0, v0, v1
	v_ashrrev_i32_e32 v1, 31, v0
	v_mfma_f32_32x32x16_bf16 v[6:21], v[98:101], v[196:199], v[6:21]
	s_waitcnt vmcnt(10)
	ds_read_b128 v[38:41], v5 offset:43264
	ds_read_b128 v[42:45], v52 offset:43264
	ds_read_b128 v[46:49], v55 offset:43264
	ds_read_b128 v[196:199], v56 offset:43264
	v_or_b32_e32 v1, 0x80000000, v1
	s_cmpk_gt_i32 s11, 384
	s_cselect_b64 vcc, -1, 0
	v_xor_b32_e32 v0, v1, v0
	v_cndmask_b32_e32 v182, v123, v0, vcc
	s_nop 3
	s_waitcnt lgkmcnt(3)
	v_mfma_f32_32x32x16_bf16 v[212:227], v[70:73], v[38:41], 0
	v_max_f32_e32 v108, 0, v6
	v_max_f32_e32 v109, 0, v7
	v_mul_f32_e32 v50, v244, v108
	v_mul_f32_e32 v51, v245, v109
	v_max_f32_e32 v210, 0, v8
	v_max_f32_e32 v211, 0, v9
	v_fmac_f32_e32 v50, v246, v210
	v_fmac_f32_e32 v51, v247, v211
	v_max_f32_e32 v108, 0, v10
	v_max_f32_e32 v109, 0, v11
	v_fmac_f32_e32 v50, v248, v108
	v_fmac_f32_e32 v51, v249, v109
	s_waitcnt lgkmcnt(2)
	v_mfma_f32_32x32x16_bf16 v[212:227], v[74:77], v[42:45], v[212:227]
	v_max_f32_e32 v210, 0, v12
	v_max_f32_e32 v211, 0, v13
	v_fmac_f32_e32 v50, v250, v210
	v_fmac_f32_e32 v51, v251, v211
	v_max_f32_e32 v108, 0, v14
	v_max_f32_e32 v109, 0, v15
	v_fmac_f32_e32 v50, v252, v108
	v_fmac_f32_e32 v51, v253, v109
	v_max_f32_e32 v210, 0, v16
	v_max_f32_e32 v211, 0, v17
	v_fmac_f32_e32 v50, v254, v210
	v_fmac_f32_e32 v51, v255, v211
	s_waitcnt lgkmcnt(1)
	v_mfma_f32_32x32x16_bf16 v[212:227], v[78:81], v[46:49], v[212:227]
	v_max_f32_e32 v108, 0, v18
	v_max_f32_e32 v109, 0, v19
	v_fmac_f32_e32 v50, v200, v108
	v_fmac_f32_e32 v51, v201, v109
	v_max_f32_e32 v210, 0, v20
	v_max_f32_e32 v211, 0, v21
	v_fmac_f32_e32 v50, v202, v210
	v_fmac_f32_e32 v51, v203, v211
	v_add_f32_e32 v50, v50, v51
	v_ashrrev_i32_e32 v51, 31, v50
	s_waitcnt lgkmcnt(0)
	v_mfma_f32_32x32x16_bf16 v[212:227], v[82:85], v[196:199], v[212:227]
	v_or_b32_e32 v51, 0x80000000, v51
	s_cmpk_gt_i32 s11, 384
	s_cselect_b64 vcc, -1, 0
	v_xor_b32_e32 v50, v51, v50
	v_cndmask_b32_e32 v50, v123, v50, vcc
	global_store_dword v243, v50, s[8:9]
	s_add_i32 m0, s10, 0
	v_mfma_f32_32x32x16_bf16 v[6:21], v[86:89], v[38:41], 0
	global_load_lds_dwordx4 v102, s[6:7]
	s_add_i32 m0, s10, 1024
	s_nop 0
	global_load_lds_dwordx4 v110, s[6:7]
	s_add_i32 m0, s10, 2048
	s_nop 0
	global_load_lds_dwordx4 v112, s[6:7]
	s_add_i32 m0, s10, 3072
	s_nop 0
	global_load_lds_dwordx4 v193, s[6:7]
	s_add_u32 s6, s6, 0x8000
	s_addc_u32 s7, s7, 0
	v_max_f32_e32 v108, 0, v212
	v_max_f32_e32 v109, 0, v213
	v_mul_f32_e32 v0, v22, v108
	v_mul_f32_e32 v1, v23, v109
	v_max_f32_e32 v210, 0, v214
	v_max_f32_e32 v211, 0, v215
	v_fmac_f32_e32 v0, v24, v210
	v_fmac_f32_e32 v1, v25, v211
	v_max_f32_e32 v108, 0, v216
	v_max_f32_e32 v109, 0, v217
	v_fmac_f32_e32 v0, v26, v108
	v_fmac_f32_e32 v1, v27, v109
	v_mfma_f32_32x32x16_bf16 v[6:21], v[90:93], v[42:45], v[6:21]
	v_max_f32_e32 v210, 0, v218
	v_max_f32_e32 v211, 0, v219
	v_fmac_f32_e32 v0, v28, v210
	v_fmac_f32_e32 v1, v29, v211
	v_max_f32_e32 v108, 0, v220
	v_max_f32_e32 v109, 0, v221
	v_fmac_f32_e32 v0, v30, v108
	v_fmac_f32_e32 v1, v31, v109
	v_max_f32_e32 v210, 0, v222
	v_max_f32_e32 v211, 0, v223
	v_fmac_f32_e32 v0, v32, v210
	v_fmac_f32_e32 v1, v33, v211
	v_mfma_f32_32x32x16_bf16 v[6:21], v[94:97], v[46:49], v[6:21]
	v_max_f32_e32 v108, 0, v224
	v_max_f32_e32 v109, 0, v225
	v_fmac_f32_e32 v0, v34, v108
	v_fmac_f32_e32 v1, v35, v109
	v_max_f32_e32 v210, 0, v226
	v_max_f32_e32 v211, 0, v227
	v_fmac_f32_e32 v0, v36, v210
	v_fmac_f32_e32 v1, v37, v211
	v_add_f32_e32 v0, v0, v1
	v_ashrrev_i32_e32 v1, 31, v0
	v_mfma_f32_32x32x16_bf16 v[6:21], v[98:101], v[196:199], v[6:21]
	s_waitcnt vmcnt(10)
	v_add_u32_e32 v228, 0x10000, v5
	ds_read_b128 v[38:41], v228 offset:10496
	v_add_u32_e32 v228, 0x10000, v52
	ds_read_b128 v[42:45], v228 offset:10496
	v_add_u32_e32 v228, 0x10000, v55
	ds_read_b128 v[46:49], v228 offset:10496
	v_add_u32_e32 v228, 0x10000, v56
	ds_read_b128 v[196:199], v228 offset:10496
	v_or_b32_e32 v1, 0x80000000, v1
	s_cmpk_gt_i32 s11, 392
	s_cselect_b64 vcc, -1, 0
	v_xor_b32_e32 v0, v1, v0
	v_cndmask_b32_e32 v181, v123, v0, vcc
	s_nop 3
	s_waitcnt lgkmcnt(3)
	v_mfma_f32_32x32x16_bf16 v[212:227], v[70:73], v[38:41], 0
	v_max_f32_e32 v108, 0, v6
	v_max_f32_e32 v109, 0, v7
	v_mul_f32_e32 v50, v244, v108
	v_mul_f32_e32 v51, v245, v109
	v_max_f32_e32 v210, 0, v8
	v_max_f32_e32 v211, 0, v9
	v_fmac_f32_e32 v50, v246, v210
	v_fmac_f32_e32 v51, v247, v211
	v_max_f32_e32 v108, 0, v10
	v_max_f32_e32 v109, 0, v11
	v_fmac_f32_e32 v50, v248, v108
	v_fmac_f32_e32 v51, v249, v109
	s_waitcnt lgkmcnt(2)
	v_mfma_f32_32x32x16_bf16 v[212:227], v[74:77], v[42:45], v[212:227]
	v_max_f32_e32 v210, 0, v12
	v_max_f32_e32 v211, 0, v13
	v_fmac_f32_e32 v50, v250, v210
	v_fmac_f32_e32 v51, v251, v211
	v_max_f32_e32 v108, 0, v14
	v_max_f32_e32 v109, 0, v15
	v_fmac_f32_e32 v50, v252, v108
	v_fmac_f32_e32 v51, v253, v109
	v_max_f32_e32 v210, 0, v16
	v_max_f32_e32 v211, 0, v17
	v_fmac_f32_e32 v50, v254, v210
	v_fmac_f32_e32 v51, v255, v211
	s_waitcnt lgkmcnt(1)
	v_mfma_f32_32x32x16_bf16 v[212:227], v[78:81], v[46:49], v[212:227]
	v_max_f32_e32 v108, 0, v18
	v_max_f32_e32 v109, 0, v19
	v_fmac_f32_e32 v50, v200, v108
	v_fmac_f32_e32 v51, v201, v109
	v_max_f32_e32 v210, 0, v20
	v_max_f32_e32 v211, 0, v21
	v_fmac_f32_e32 v50, v202, v210
	v_fmac_f32_e32 v51, v203, v211
	v_add_f32_e32 v50, v50, v51
	v_ashrrev_i32_e32 v51, 31, v50
	s_waitcnt lgkmcnt(0)
	v_mfma_f32_32x32x16_bf16 v[212:227], v[82:85], v[196:199], v[212:227]
	v_or_b32_e32 v51, 0x80000000, v51
	s_cmpk_gt_i32 s11, 392
	s_cselect_b64 vcc, -1, 0
	v_xor_b32_e32 v50, v51, v50
	v_cndmask_b32_e32 v50, v123, v50, vcc
	global_store_dword v243, v50, s[8:9] offset:2048
	s_add_u32 s8, s8, 0x1000
	s_addc_u32 s9, s9, 0
	s_add_i32 m0, s10, 32768
	v_mfma_f32_32x32x16_bf16 v[6:21], v[86:89], v[38:41], 0
	global_load_lds_dwordx4 v102, s[6:7]
	s_add_i32 m0, s10, 33792
	s_nop 0
	global_load_lds_dwordx4 v110, s[6:7]
	s_add_i32 m0, s10, 34816
	s_nop 0
	global_load_lds_dwordx4 v112, s[6:7]
	s_add_i32 m0, s10, 35840
	s_nop 0
	global_load_lds_dwordx4 v193, s[6:7]
	s_add_u32 s6, s6, 0x8000
	s_addc_u32 s7, s7, 0
	v_max_f32_e32 v108, 0, v212
	v_max_f32_e32 v109, 0, v213
	v_mul_f32_e32 v0, v22, v108
	v_mul_f32_e32 v1, v23, v109
	v_max_f32_e32 v210, 0, v214
	v_max_f32_e32 v211, 0, v215
	v_fmac_f32_e32 v0, v24, v210
	v_fmac_f32_e32 v1, v25, v211
	v_max_f32_e32 v108, 0, v216
	v_max_f32_e32 v109, 0, v217
	v_fmac_f32_e32 v0, v26, v108
	v_fmac_f32_e32 v1, v27, v109
	v_mfma_f32_32x32x16_bf16 v[6:21], v[90:93], v[42:45], v[6:21]
	v_max_f32_e32 v210, 0, v218
	v_max_f32_e32 v211, 0, v219
	v_fmac_f32_e32 v0, v28, v210
	v_fmac_f32_e32 v1, v29, v211
	v_max_f32_e32 v108, 0, v220
	v_max_f32_e32 v109, 0, v221
	v_fmac_f32_e32 v0, v30, v108
	v_fmac_f32_e32 v1, v31, v109
	v_max_f32_e32 v210, 0, v222
	v_max_f32_e32 v211, 0, v223
	v_fmac_f32_e32 v0, v32, v210
	v_fmac_f32_e32 v1, v33, v211
	v_mfma_f32_32x32x16_bf16 v[6:21], v[94:97], v[46:49], v[6:21]
	v_max_f32_e32 v108, 0, v224
	v_max_f32_e32 v109, 0, v225
	v_fmac_f32_e32 v0, v34, v108
	v_fmac_f32_e32 v1, v35, v109
	v_max_f32_e32 v210, 0, v226
	v_max_f32_e32 v211, 0, v227
	v_fmac_f32_e32 v0, v36, v210
	v_fmac_f32_e32 v1, v37, v211
	v_add_f32_e32 v0, v0, v1
	v_ashrrev_i32_e32 v1, 31, v0
	v_mfma_f32_32x32x16_bf16 v[6:21], v[98:101], v[196:199], v[6:21]
	s_waitcnt vmcnt(10)
	v_add_u32_e32 v228, 0x10000, v5
	ds_read_b128 v[38:41], v228 offset:43264
	v_add_u32_e32 v228, 0x10000, v52
	ds_read_b128 v[42:45], v228 offset:43264
	v_add_u32_e32 v228, 0x10000, v55
	ds_read_b128 v[46:49], v228 offset:43264
	v_add_u32_e32 v228, 0x10000, v56
	ds_read_b128 v[196:199], v228 offset:43264
	v_or_b32_e32 v1, 0x80000000, v1
	s_cmpk_gt_i32 s11, 400
	s_cselect_b64 vcc, -1, 0
	v_xor_b32_e32 v0, v1, v0
	v_cndmask_b32_e32 v184, v123, v0, vcc
	s_nop 3
	s_waitcnt lgkmcnt(3)
	v_mfma_f32_32x32x16_bf16 v[212:227], v[70:73], v[38:41], 0
	v_max_f32_e32 v108, 0, v6
	v_max_f32_e32 v109, 0, v7
	v_mul_f32_e32 v50, v244, v108
	v_mul_f32_e32 v51, v245, v109
	v_max_f32_e32 v210, 0, v8
	v_max_f32_e32 v211, 0, v9
	v_fmac_f32_e32 v50, v246, v210
	v_fmac_f32_e32 v51, v247, v211
	v_max_f32_e32 v108, 0, v10
	v_max_f32_e32 v109, 0, v11
	v_fmac_f32_e32 v50, v248, v108
	v_fmac_f32_e32 v51, v249, v109
	s_waitcnt lgkmcnt(2)
	v_mfma_f32_32x32x16_bf16 v[212:227], v[74:77], v[42:45], v[212:227]
	v_max_f32_e32 v210, 0, v12
	v_max_f32_e32 v211, 0, v13
	v_fmac_f32_e32 v50, v250, v210
	v_fmac_f32_e32 v51, v251, v211
	v_max_f32_e32 v108, 0, v14
	v_max_f32_e32 v109, 0, v15
	v_fmac_f32_e32 v50, v252, v108
	v_fmac_f32_e32 v51, v253, v109
	v_max_f32_e32 v210, 0, v16
	v_max_f32_e32 v211, 0, v17
	v_fmac_f32_e32 v50, v254, v210
	v_fmac_f32_e32 v51, v255, v211
	s_waitcnt lgkmcnt(1)
	v_mfma_f32_32x32x16_bf16 v[212:227], v[78:81], v[46:49], v[212:227]
	v_max_f32_e32 v108, 0, v18
	v_max_f32_e32 v109, 0, v19
	v_fmac_f32_e32 v50, v200, v108
	v_fmac_f32_e32 v51, v201, v109
	v_max_f32_e32 v210, 0, v20
	v_max_f32_e32 v211, 0, v21
	v_fmac_f32_e32 v50, v202, v210
	v_fmac_f32_e32 v51, v203, v211
	v_add_f32_e32 v50, v50, v51
	v_ashrrev_i32_e32 v51, 31, v50
	s_waitcnt lgkmcnt(0)
	v_mfma_f32_32x32x16_bf16 v[212:227], v[82:85], v[196:199], v[212:227]
	v_or_b32_e32 v51, 0x80000000, v51
	s_cmpk_gt_i32 s11, 400
	s_cselect_b64 vcc, -1, 0
	v_xor_b32_e32 v50, v51, v50
	v_cndmask_b32_e32 v50, v123, v50, vcc
	global_store_dword v243, v50, s[8:9]
	s_add_i32 m0, s10, 65536
	v_mfma_f32_32x32x16_bf16 v[6:21], v[86:89], v[38:41], 0
	global_load_lds_dwordx4 v102, s[6:7]
	s_add_i32 m0, s10, 66560
	s_nop 0
	global_load_lds_dwordx4 v110, s[6:7]
	s_add_i32 m0, s10, 67584
	s_nop 0
	global_load_lds_dwordx4 v112, s[6:7]
	s_add_i32 m0, s10, 68608
	s_nop 0
	global_load_lds_dwordx4 v193, s[6:7]
	s_add_u32 s6, s6, 0x8000
	s_addc_u32 s7, s7, 0
	v_max_f32_e32 v108, 0, v212
	v_max_f32_e32 v109, 0, v213
	v_mul_f32_e32 v0, v22, v108
	v_mul_f32_e32 v1, v23, v109
	v_max_f32_e32 v210, 0, v214
	v_max_f32_e32 v211, 0, v215
	v_fmac_f32_e32 v0, v24, v210
	v_fmac_f32_e32 v1, v25, v211
	v_max_f32_e32 v108, 0, v216
	v_max_f32_e32 v109, 0, v217
	v_fmac_f32_e32 v0, v26, v108
	v_fmac_f32_e32 v1, v27, v109
	v_mfma_f32_32x32x16_bf16 v[6:21], v[90:93], v[42:45], v[6:21]
	v_max_f32_e32 v210, 0, v218
	v_max_f32_e32 v211, 0, v219
	v_fmac_f32_e32 v0, v28, v210
	v_fmac_f32_e32 v1, v29, v211
	v_max_f32_e32 v108, 0, v220
	v_max_f32_e32 v109, 0, v221
	v_fmac_f32_e32 v0, v30, v108
	v_fmac_f32_e32 v1, v31, v109
	v_max_f32_e32 v210, 0, v222
	v_max_f32_e32 v211, 0, v223
	v_fmac_f32_e32 v0, v32, v210
	v_fmac_f32_e32 v1, v33, v211
	v_mfma_f32_32x32x16_bf16 v[6:21], v[94:97], v[46:49], v[6:21]
	v_max_f32_e32 v108, 0, v224
	v_max_f32_e32 v109, 0, v225
	v_fmac_f32_e32 v0, v34, v108
	v_fmac_f32_e32 v1, v35, v109
	v_max_f32_e32 v210, 0, v226
	v_max_f32_e32 v211, 0, v227
	v_fmac_f32_e32 v0, v36, v210
	v_fmac_f32_e32 v1, v37, v211
	v_add_f32_e32 v0, v0, v1
	v_ashrrev_i32_e32 v1, 31, v0
	v_mfma_f32_32x32x16_bf16 v[6:21], v[98:101], v[196:199], v[6:21]
	s_waitcnt vmcnt(10)
	ds_read_b128 v[38:41], v5 offset:10496
	ds_read_b128 v[42:45], v52 offset:10496
	ds_read_b128 v[46:49], v55 offset:10496
	ds_read_b128 v[196:199], v56 offset:10496
	v_or_b32_e32 v1, 0x80000000, v1
	s_cmpk_gt_i32 s11, 408
	s_cselect_b64 vcc, -1, 0
	v_xor_b32_e32 v0, v1, v0
	v_cndmask_b32_e32 v183, v123, v0, vcc
	s_nop 3
	s_waitcnt lgkmcnt(3)
	v_mfma_f32_32x32x16_bf16 v[212:227], v[70:73], v[38:41], 0
	v_max_f32_e32 v108, 0, v6
	v_max_f32_e32 v109, 0, v7
	v_mul_f32_e32 v50, v244, v108
	v_mul_f32_e32 v51, v245, v109
	v_max_f32_e32 v210, 0, v8
	v_max_f32_e32 v211, 0, v9
	v_fmac_f32_e32 v50, v246, v210
	v_fmac_f32_e32 v51, v247, v211
	v_max_f32_e32 v108, 0, v10
	v_max_f32_e32 v109, 0, v11
	v_fmac_f32_e32 v50, v248, v108
	v_fmac_f32_e32 v51, v249, v109
	s_waitcnt lgkmcnt(2)
	v_mfma_f32_32x32x16_bf16 v[212:227], v[74:77], v[42:45], v[212:227]
	v_max_f32_e32 v210, 0, v12
	v_max_f32_e32 v211, 0, v13
	v_fmac_f32_e32 v50, v250, v210
	v_fmac_f32_e32 v51, v251, v211
	v_max_f32_e32 v108, 0, v14
	v_max_f32_e32 v109, 0, v15
	v_fmac_f32_e32 v50, v252, v108
	v_fmac_f32_e32 v51, v253, v109
	v_max_f32_e32 v210, 0, v16
	v_max_f32_e32 v211, 0, v17
	v_fmac_f32_e32 v50, v254, v210
	v_fmac_f32_e32 v51, v255, v211
	s_waitcnt lgkmcnt(1)
	v_mfma_f32_32x32x16_bf16 v[212:227], v[78:81], v[46:49], v[212:227]
	v_max_f32_e32 v108, 0, v18
	v_max_f32_e32 v109, 0, v19
	v_fmac_f32_e32 v50, v200, v108
	v_fmac_f32_e32 v51, v201, v109
	v_max_f32_e32 v210, 0, v20
	v_max_f32_e32 v211, 0, v21
	v_fmac_f32_e32 v50, v202, v210
	v_fmac_f32_e32 v51, v203, v211
	v_add_f32_e32 v50, v50, v51
	v_ashrrev_i32_e32 v51, 31, v50
	s_waitcnt lgkmcnt(0)
	v_mfma_f32_32x32x16_bf16 v[212:227], v[82:85], v[196:199], v[212:227]
	v_or_b32_e32 v51, 0x80000000, v51
	s_cmpk_gt_i32 s11, 408
	s_cselect_b64 vcc, -1, 0
	v_xor_b32_e32 v50, v51, v50
	v_cndmask_b32_e32 v50, v123, v50, vcc
	global_store_dword v243, v50, s[8:9] offset:2048
	s_add_u32 s8, s8, 0x1000
	s_addc_u32 s9, s9, 0
	s_add_i32 m0, s10, 98304
	v_mfma_f32_32x32x16_bf16 v[6:21], v[86:89], v[38:41], 0
	global_load_lds_dwordx4 v102, s[6:7]
	s_add_i32 m0, s10, 99328
	s_nop 0
	global_load_lds_dwordx4 v110, s[6:7]
	s_add_i32 m0, s10, 100352
	s_nop 0
	global_load_lds_dwordx4 v112, s[6:7]
	s_add_i32 m0, s10, 101376
	s_nop 0
	global_load_lds_dwordx4 v193, s[6:7]
	s_add_u32 s6, s6, 0x8000
	s_addc_u32 s7, s7, 0
	v_max_f32_e32 v108, 0, v212
	v_max_f32_e32 v109, 0, v213
	v_mul_f32_e32 v0, v22, v108
	v_mul_f32_e32 v1, v23, v109
	v_max_f32_e32 v210, 0, v214
	v_max_f32_e32 v211, 0, v215
	v_fmac_f32_e32 v0, v24, v210
	v_fmac_f32_e32 v1, v25, v211
	v_max_f32_e32 v108, 0, v216
	v_max_f32_e32 v109, 0, v217
	v_fmac_f32_e32 v0, v26, v108
	v_fmac_f32_e32 v1, v27, v109
	v_mfma_f32_32x32x16_bf16 v[6:21], v[90:93], v[42:45], v[6:21]
	v_max_f32_e32 v210, 0, v218
	v_max_f32_e32 v211, 0, v219
	v_fmac_f32_e32 v0, v28, v210
	v_fmac_f32_e32 v1, v29, v211
	v_max_f32_e32 v108, 0, v220
	v_max_f32_e32 v109, 0, v221
	v_fmac_f32_e32 v0, v30, v108
	v_fmac_f32_e32 v1, v31, v109
	v_max_f32_e32 v210, 0, v222
	v_max_f32_e32 v211, 0, v223
	v_fmac_f32_e32 v0, v32, v210
	v_fmac_f32_e32 v1, v33, v211
	v_mfma_f32_32x32x16_bf16 v[6:21], v[94:97], v[46:49], v[6:21]
	v_max_f32_e32 v108, 0, v224
	v_max_f32_e32 v109, 0, v225
	v_fmac_f32_e32 v0, v34, v108
	v_fmac_f32_e32 v1, v35, v109
	v_max_f32_e32 v210, 0, v226
	v_max_f32_e32 v211, 0, v227
	v_fmac_f32_e32 v0, v36, v210
	v_fmac_f32_e32 v1, v37, v211
	v_add_f32_e32 v0, v0, v1
	v_ashrrev_i32_e32 v1, 31, v0
	v_mfma_f32_32x32x16_bf16 v[6:21], v[98:101], v[196:199], v[6:21]
	s_waitcnt vmcnt(10)
	ds_read_b128 v[38:41], v5 offset:43264
	ds_read_b128 v[42:45], v52 offset:43264
	ds_read_b128 v[46:49], v55 offset:43264
	ds_read_b128 v[196:199], v56 offset:43264
	v_or_b32_e32 v1, 0x80000000, v1
	s_cmpk_gt_i32 s11, 416
	s_cselect_b64 vcc, -1, 0
	v_xor_b32_e32 v0, v1, v0
	v_cndmask_b32_e32 v187, v123, v0, vcc
	s_nop 3
	s_waitcnt lgkmcnt(3)
	v_mfma_f32_32x32x16_bf16 v[212:227], v[70:73], v[38:41], 0
	v_max_f32_e32 v108, 0, v6
	v_max_f32_e32 v109, 0, v7
	v_mul_f32_e32 v50, v244, v108
	v_mul_f32_e32 v51, v245, v109
	v_max_f32_e32 v210, 0, v8
	v_max_f32_e32 v211, 0, v9
	v_fmac_f32_e32 v50, v246, v210
	v_fmac_f32_e32 v51, v247, v211
	v_max_f32_e32 v108, 0, v10
	v_max_f32_e32 v109, 0, v11
	v_fmac_f32_e32 v50, v248, v108
	v_fmac_f32_e32 v51, v249, v109
	s_waitcnt lgkmcnt(2)
	v_mfma_f32_32x32x16_bf16 v[212:227], v[74:77], v[42:45], v[212:227]
	v_max_f32_e32 v210, 0, v12
	v_max_f32_e32 v211, 0, v13
	v_fmac_f32_e32 v50, v250, v210
	v_fmac_f32_e32 v51, v251, v211
	v_max_f32_e32 v108, 0, v14
	v_max_f32_e32 v109, 0, v15
	v_fmac_f32_e32 v50, v252, v108
	v_fmac_f32_e32 v51, v253, v109
	v_max_f32_e32 v210, 0, v16
	v_max_f32_e32 v211, 0, v17
	v_fmac_f32_e32 v50, v254, v210
	v_fmac_f32_e32 v51, v255, v211
	s_waitcnt lgkmcnt(1)
	v_mfma_f32_32x32x16_bf16 v[212:227], v[78:81], v[46:49], v[212:227]
	v_max_f32_e32 v108, 0, v18
	v_max_f32_e32 v109, 0, v19
	v_fmac_f32_e32 v50, v200, v108
	v_fmac_f32_e32 v51, v201, v109
	v_max_f32_e32 v210, 0, v20
	v_max_f32_e32 v211, 0, v21
	v_fmac_f32_e32 v50, v202, v210
	v_fmac_f32_e32 v51, v203, v211
	v_add_f32_e32 v50, v50, v51
	v_ashrrev_i32_e32 v51, 31, v50
	s_waitcnt lgkmcnt(0)
	v_mfma_f32_32x32x16_bf16 v[212:227], v[82:85], v[196:199], v[212:227]
	v_or_b32_e32 v51, 0x80000000, v51
	s_cmpk_gt_i32 s11, 416
	s_cselect_b64 vcc, -1, 0
	v_xor_b32_e32 v50, v51, v50
	v_cndmask_b32_e32 v50, v123, v50, vcc
	global_store_dword v243, v50, s[8:9]
	s_add_i32 m0, s10, 0
	v_mfma_f32_32x32x16_bf16 v[6:21], v[86:89], v[38:41], 0
	global_load_lds_dwordx4 v102, s[6:7]
	s_add_i32 m0, s10, 1024
	s_nop 0
	global_load_lds_dwordx4 v110, s[6:7]
	s_add_i32 m0, s10, 2048
	s_nop 0
	global_load_lds_dwordx4 v112, s[6:7]
	s_add_i32 m0, s10, 3072
	s_nop 0
	global_load_lds_dwordx4 v193, s[6:7]
	s_add_u32 s6, s6, 0x8000
	s_addc_u32 s7, s7, 0
	v_max_f32_e32 v108, 0, v212
	v_max_f32_e32 v109, 0, v213
	v_mul_f32_e32 v0, v22, v108
	v_mul_f32_e32 v1, v23, v109
	v_max_f32_e32 v210, 0, v214
	v_max_f32_e32 v211, 0, v215
	v_fmac_f32_e32 v0, v24, v210
	v_fmac_f32_e32 v1, v25, v211
	v_max_f32_e32 v108, 0, v216
	v_max_f32_e32 v109, 0, v217
	v_fmac_f32_e32 v0, v26, v108
	v_fmac_f32_e32 v1, v27, v109
	v_mfma_f32_32x32x16_bf16 v[6:21], v[90:93], v[42:45], v[6:21]
	v_max_f32_e32 v210, 0, v218
	v_max_f32_e32 v211, 0, v219
	v_fmac_f32_e32 v0, v28, v210
	v_fmac_f32_e32 v1, v29, v211
	v_max_f32_e32 v108, 0, v220
	v_max_f32_e32 v109, 0, v221
	v_fmac_f32_e32 v0, v30, v108
	v_fmac_f32_e32 v1, v31, v109
	v_max_f32_e32 v210, 0, v222
	v_max_f32_e32 v211, 0, v223
	v_fmac_f32_e32 v0, v32, v210
	v_fmac_f32_e32 v1, v33, v211
	v_mfma_f32_32x32x16_bf16 v[6:21], v[94:97], v[46:49], v[6:21]
	v_max_f32_e32 v108, 0, v224
	v_max_f32_e32 v109, 0, v225
	v_fmac_f32_e32 v0, v34, v108
	v_fmac_f32_e32 v1, v35, v109
	v_max_f32_e32 v210, 0, v226
	v_max_f32_e32 v211, 0, v227
	v_fmac_f32_e32 v0, v36, v210
	v_fmac_f32_e32 v1, v37, v211
	v_add_f32_e32 v0, v0, v1
	v_ashrrev_i32_e32 v1, 31, v0
	v_mfma_f32_32x32x16_bf16 v[6:21], v[98:101], v[196:199], v[6:21]
	s_waitcnt vmcnt(10)
	v_add_u32_e32 v228, 0x10000, v5
	ds_read_b128 v[38:41], v228 offset:10496
	v_add_u32_e32 v228, 0x10000, v52
	ds_read_b128 v[42:45], v228 offset:10496
	v_add_u32_e32 v228, 0x10000, v55
	ds_read_b128 v[46:49], v228 offset:10496
	v_add_u32_e32 v228, 0x10000, v56
	ds_read_b128 v[196:199], v228 offset:10496
	v_or_b32_e32 v1, 0x80000000, v1
	s_cmpk_gt_i32 s11, 424
	s_cselect_b64 vcc, -1, 0
	v_xor_b32_e32 v0, v1, v0
	v_cndmask_b32_e32 v186, v123, v0, vcc
	s_nop 3
	s_waitcnt lgkmcnt(3)
	v_mfma_f32_32x32x16_bf16 v[212:227], v[70:73], v[38:41], 0
	v_max_f32_e32 v108, 0, v6
	v_max_f32_e32 v109, 0, v7
	v_mul_f32_e32 v50, v244, v108
	v_mul_f32_e32 v51, v245, v109
	v_max_f32_e32 v210, 0, v8
	v_max_f32_e32 v211, 0, v9
	v_fmac_f32_e32 v50, v246, v210
	v_fmac_f32_e32 v51, v247, v211
	v_max_f32_e32 v108, 0, v10
	v_max_f32_e32 v109, 0, v11
	v_fmac_f32_e32 v50, v248, v108
	v_fmac_f32_e32 v51, v249, v109
	s_waitcnt lgkmcnt(2)
	v_mfma_f32_32x32x16_bf16 v[212:227], v[74:77], v[42:45], v[212:227]
	v_max_f32_e32 v210, 0, v12
	v_max_f32_e32 v211, 0, v13
	v_fmac_f32_e32 v50, v250, v210
	v_fmac_f32_e32 v51, v251, v211
	v_max_f32_e32 v108, 0, v14
	v_max_f32_e32 v109, 0, v15
	v_fmac_f32_e32 v50, v252, v108
	v_fmac_f32_e32 v51, v253, v109
	v_max_f32_e32 v210, 0, v16
	v_max_f32_e32 v211, 0, v17
	v_fmac_f32_e32 v50, v254, v210
	v_fmac_f32_e32 v51, v255, v211
	s_waitcnt lgkmcnt(1)
	v_mfma_f32_32x32x16_bf16 v[212:227], v[78:81], v[46:49], v[212:227]
	v_max_f32_e32 v108, 0, v18
	v_max_f32_e32 v109, 0, v19
	v_fmac_f32_e32 v50, v200, v108
	v_fmac_f32_e32 v51, v201, v109
	v_max_f32_e32 v210, 0, v20
	v_max_f32_e32 v211, 0, v21
	v_fmac_f32_e32 v50, v202, v210
	v_fmac_f32_e32 v51, v203, v211
	v_add_f32_e32 v50, v50, v51
	v_ashrrev_i32_e32 v51, 31, v50
	s_waitcnt lgkmcnt(0)
	v_mfma_f32_32x32x16_bf16 v[212:227], v[82:85], v[196:199], v[212:227]
	v_or_b32_e32 v51, 0x80000000, v51
	s_cmpk_gt_i32 s11, 424
	s_cselect_b64 vcc, -1, 0
	v_xor_b32_e32 v50, v51, v50
	v_cndmask_b32_e32 v50, v123, v50, vcc
	global_store_dword v243, v50, s[8:9] offset:2048
	s_add_u32 s8, s8, 0x1000
	s_addc_u32 s9, s9, 0
	s_add_i32 m0, s10, 32768
	v_mfma_f32_32x32x16_bf16 v[6:21], v[86:89], v[38:41], 0
	global_load_lds_dwordx4 v102, s[6:7]
	s_add_i32 m0, s10, 33792
	s_nop 0
	global_load_lds_dwordx4 v110, s[6:7]
	s_add_i32 m0, s10, 34816
	s_nop 0
	global_load_lds_dwordx4 v112, s[6:7]
	s_add_i32 m0, s10, 35840
	s_nop 0
	global_load_lds_dwordx4 v193, s[6:7]
	s_add_u32 s6, s6, 0x8000
	s_addc_u32 s7, s7, 0
	v_max_f32_e32 v108, 0, v212
	v_max_f32_e32 v109, 0, v213
	v_mul_f32_e32 v0, v22, v108
	v_mul_f32_e32 v1, v23, v109
	v_max_f32_e32 v210, 0, v214
	v_max_f32_e32 v211, 0, v215
	v_fmac_f32_e32 v0, v24, v210
	v_fmac_f32_e32 v1, v25, v211
	v_max_f32_e32 v108, 0, v216
	v_max_f32_e32 v109, 0, v217
	v_fmac_f32_e32 v0, v26, v108
	v_fmac_f32_e32 v1, v27, v109
	v_mfma_f32_32x32x16_bf16 v[6:21], v[90:93], v[42:45], v[6:21]
	v_max_f32_e32 v210, 0, v218
	v_max_f32_e32 v211, 0, v219
	v_fmac_f32_e32 v0, v28, v210
	v_fmac_f32_e32 v1, v29, v211
	v_max_f32_e32 v108, 0, v220
	v_max_f32_e32 v109, 0, v221
	v_fmac_f32_e32 v0, v30, v108
	v_fmac_f32_e32 v1, v31, v109
	v_max_f32_e32 v210, 0, v222
	v_max_f32_e32 v211, 0, v223
	v_fmac_f32_e32 v0, v32, v210
	v_fmac_f32_e32 v1, v33, v211
	v_mfma_f32_32x32x16_bf16 v[6:21], v[94:97], v[46:49], v[6:21]
	v_max_f32_e32 v108, 0, v224
	v_max_f32_e32 v109, 0, v225
	v_fmac_f32_e32 v0, v34, v108
	v_fmac_f32_e32 v1, v35, v109
	v_max_f32_e32 v210, 0, v226
	v_max_f32_e32 v211, 0, v227
	v_fmac_f32_e32 v0, v36, v210
	v_fmac_f32_e32 v1, v37, v211
	v_add_f32_e32 v0, v0, v1
	v_ashrrev_i32_e32 v1, 31, v0
	v_mfma_f32_32x32x16_bf16 v[6:21], v[98:101], v[196:199], v[6:21]
	s_waitcnt vmcnt(10)
	v_add_u32_e32 v228, 0x10000, v5
	ds_read_b128 v[38:41], v228 offset:43264
	v_add_u32_e32 v228, 0x10000, v52
	ds_read_b128 v[42:45], v228 offset:43264
	v_add_u32_e32 v228, 0x10000, v55
	ds_read_b128 v[46:49], v228 offset:43264
	v_add_u32_e32 v228, 0x10000, v56
	ds_read_b128 v[196:199], v228 offset:43264
	v_or_b32_e32 v1, 0x80000000, v1
	s_cmpk_gt_i32 s11, 432
	s_cselect_b64 vcc, -1, 0
	v_xor_b32_e32 v0, v1, v0
	v_cndmask_b32_e32 v189, v123, v0, vcc
	s_nop 3
	s_waitcnt lgkmcnt(3)
	v_mfma_f32_32x32x16_bf16 v[212:227], v[70:73], v[38:41], 0
	v_max_f32_e32 v108, 0, v6
	v_max_f32_e32 v109, 0, v7
	v_mul_f32_e32 v50, v244, v108
	v_mul_f32_e32 v51, v245, v109
	v_max_f32_e32 v210, 0, v8
	v_max_f32_e32 v211, 0, v9
	v_fmac_f32_e32 v50, v246, v210
	v_fmac_f32_e32 v51, v247, v211
	v_max_f32_e32 v108, 0, v10
	v_max_f32_e32 v109, 0, v11
	v_fmac_f32_e32 v50, v248, v108
	v_fmac_f32_e32 v51, v249, v109
	s_waitcnt lgkmcnt(2)
	v_mfma_f32_32x32x16_bf16 v[212:227], v[74:77], v[42:45], v[212:227]
	v_max_f32_e32 v210, 0, v12
	v_max_f32_e32 v211, 0, v13
	v_fmac_f32_e32 v50, v250, v210
	v_fmac_f32_e32 v51, v251, v211
	v_max_f32_e32 v108, 0, v14
	v_max_f32_e32 v109, 0, v15
	v_fmac_f32_e32 v50, v252, v108
	v_fmac_f32_e32 v51, v253, v109
	v_max_f32_e32 v210, 0, v16
	v_max_f32_e32 v211, 0, v17
	v_fmac_f32_e32 v50, v254, v210
	v_fmac_f32_e32 v51, v255, v211
	s_waitcnt lgkmcnt(1)
	v_mfma_f32_32x32x16_bf16 v[212:227], v[78:81], v[46:49], v[212:227]
	v_max_f32_e32 v108, 0, v18
	v_max_f32_e32 v109, 0, v19
	v_fmac_f32_e32 v50, v200, v108
	v_fmac_f32_e32 v51, v201, v109
	v_max_f32_e32 v210, 0, v20
	v_max_f32_e32 v211, 0, v21
	v_fmac_f32_e32 v50, v202, v210
	v_fmac_f32_e32 v51, v203, v211
	v_add_f32_e32 v50, v50, v51
	v_ashrrev_i32_e32 v51, 31, v50
	s_waitcnt lgkmcnt(0)
	v_mfma_f32_32x32x16_bf16 v[212:227], v[82:85], v[196:199], v[212:227]
	v_or_b32_e32 v51, 0x80000000, v51
	s_cmpk_gt_i32 s11, 432
	s_cselect_b64 vcc, -1, 0
	v_xor_b32_e32 v50, v51, v50
	v_cndmask_b32_e32 v50, v123, v50, vcc
	global_store_dword v243, v50, s[8:9]
	s_add_i32 m0, s10, 65536
	v_mfma_f32_32x32x16_bf16 v[6:21], v[86:89], v[38:41], 0
	global_load_lds_dwordx4 v102, s[6:7]
	s_add_i32 m0, s10, 66560
	s_nop 0
	global_load_lds_dwordx4 v110, s[6:7]
	s_add_i32 m0, s10, 67584
	s_nop 0
	global_load_lds_dwordx4 v112, s[6:7]
	s_add_i32 m0, s10, 68608
	s_nop 0
	global_load_lds_dwordx4 v193, s[6:7]
	s_add_u32 s6, s6, 0x8000
	s_addc_u32 s7, s7, 0
	v_max_f32_e32 v108, 0, v212
	v_max_f32_e32 v109, 0, v213
	v_mul_f32_e32 v0, v22, v108
	v_mul_f32_e32 v1, v23, v109
	v_max_f32_e32 v210, 0, v214
	v_max_f32_e32 v211, 0, v215
	v_fmac_f32_e32 v0, v24, v210
	v_fmac_f32_e32 v1, v25, v211
	v_max_f32_e32 v108, 0, v216
	v_max_f32_e32 v109, 0, v217
	v_fmac_f32_e32 v0, v26, v108
	v_fmac_f32_e32 v1, v27, v109
	v_mfma_f32_32x32x16_bf16 v[6:21], v[90:93], v[42:45], v[6:21]
	v_max_f32_e32 v210, 0, v218
	v_max_f32_e32 v211, 0, v219
	v_fmac_f32_e32 v0, v28, v210
	v_fmac_f32_e32 v1, v29, v211
	v_max_f32_e32 v108, 0, v220
	v_max_f32_e32 v109, 0, v221
	v_fmac_f32_e32 v0, v30, v108
	v_fmac_f32_e32 v1, v31, v109
	v_max_f32_e32 v210, 0, v222
	v_max_f32_e32 v211, 0, v223
	v_fmac_f32_e32 v0, v32, v210
	v_fmac_f32_e32 v1, v33, v211
	v_mfma_f32_32x32x16_bf16 v[6:21], v[94:97], v[46:49], v[6:21]
	v_max_f32_e32 v108, 0, v224
	v_max_f32_e32 v109, 0, v225
	v_fmac_f32_e32 v0, v34, v108
	v_fmac_f32_e32 v1, v35, v109
	v_max_f32_e32 v210, 0, v226
	v_max_f32_e32 v211, 0, v227
	v_fmac_f32_e32 v0, v36, v210
	v_fmac_f32_e32 v1, v37, v211
	v_add_f32_e32 v0, v0, v1
	v_ashrrev_i32_e32 v1, 31, v0
	v_mfma_f32_32x32x16_bf16 v[6:21], v[98:101], v[196:199], v[6:21]
	s_waitcnt vmcnt(10)
	ds_read_b128 v[38:41], v5 offset:10496
	ds_read_b128 v[42:45], v52 offset:10496
	ds_read_b128 v[46:49], v55 offset:10496
	ds_read_b128 v[196:199], v56 offset:10496
	v_or_b32_e32 v1, 0x80000000, v1
	s_cmpk_gt_i32 s11, 440
	s_cselect_b64 vcc, -1, 0
	v_xor_b32_e32 v0, v1, v0
	v_cndmask_b32_e32 v188, v123, v0, vcc
	s_nop 3
	v_max_f32_e32 v108, 0, v6
	v_max_f32_e32 v109, 0, v7
	v_mul_f32_e32 v50, v244, v108
	v_mul_f32_e32 v51, v245, v109
	v_max_f32_e32 v210, 0, v8
	v_max_f32_e32 v211, 0, v9
	v_fmac_f32_e32 v50, v246, v210
	v_fmac_f32_e32 v51, v247, v211
	v_max_f32_e32 v108, 0, v10
	v_max_f32_e32 v109, 0, v11
	v_fmac_f32_e32 v50, v248, v108
	v_fmac_f32_e32 v51, v249, v109
	v_max_f32_e32 v210, 0, v12
	v_max_f32_e32 v211, 0, v13
	v_fmac_f32_e32 v50, v250, v210
	v_fmac_f32_e32 v51, v251, v211
	v_max_f32_e32 v108, 0, v14
	v_max_f32_e32 v109, 0, v15
	v_fmac_f32_e32 v50, v252, v108
	v_fmac_f32_e32 v51, v253, v109
	v_max_f32_e32 v210, 0, v16
	v_max_f32_e32 v211, 0, v17
	v_fmac_f32_e32 v50, v254, v210
	v_fmac_f32_e32 v51, v255, v211
	v_max_f32_e32 v108, 0, v18
	v_max_f32_e32 v109, 0, v19
	v_fmac_f32_e32 v50, v200, v108
	v_fmac_f32_e32 v51, v201, v109
	v_max_f32_e32 v210, 0, v20
	v_max_f32_e32 v211, 0, v21
	v_fmac_f32_e32 v50, v202, v210
	v_fmac_f32_e32 v51, v203, v211
	v_add_f32_e32 v50, v50, v51
	v_ashrrev_i32_e32 v51, 31, v50
	v_or_b32_e32 v51, 0x80000000, v51
	s_cmpk_gt_i32 s11, 440
	s_cselect_b64 vcc, -1, 0
	v_xor_b32_e32 v50, v51, v50
	v_cndmask_b32_e32 v50, v123, v50, vcc
	global_store_dword v243, v50, s[8:9] offset:2048
	s_add_u32 s8, s8, 0x1000
	s_addc_u32 s9, s9, 0
	s_cmpk_gt_i32 s81, 56
	s_cbranch_scc0 .Lix_fill_7
	s_waitcnt lgkmcnt(3)
	s_add_i32 m0, s10, 98304
	v_mfma_f32_32x32x16_bf16 v[212:227], v[70:73], v[38:41], 0
	global_load_lds_dwordx4 v102, s[6:7]
	s_waitcnt lgkmcnt(2)
	s_add_i32 m0, s10, 99328
	v_mfma_f32_32x32x16_bf16 v[212:227], v[74:77], v[42:45], v[212:227]
	global_load_lds_dwordx4 v110, s[6:7]
	s_waitcnt lgkmcnt(1)
	s_add_i32 m0, s10, 100352
	v_mfma_f32_32x32x16_bf16 v[212:227], v[78:81], v[46:49], v[212:227]
	global_load_lds_dwordx4 v112, s[6:7]
	s_waitcnt lgkmcnt(0)
	s_add_i32 m0, s10, 101376
	v_mfma_f32_32x32x16_bf16 v[212:227], v[82:85], v[196:199], v[212:227]
	global_load_lds_dwordx4 v193, s[6:7]
	s_add_u32 s6, s6, 0x8000
	s_addc_u32 s7, s7, 0
	v_mfma_f32_32x32x16_bf16 v[6:21], v[86:89], v[38:41], 0
	s_nop 7
	s_nop 2
	v_max_f32_e32 v108, 0, v212
	v_max_f32_e32 v109, 0, v213
	v_mul_f32_e32 v0, v22, v108
	v_mul_f32_e32 v1, v23, v109
	v_max_f32_e32 v210, 0, v214
	v_max_f32_e32 v211, 0, v215
	v_fmac_f32_e32 v0, v24, v210
	v_fmac_f32_e32 v1, v25, v211
	v_max_f32_e32 v108, 0, v216
	v_max_f32_e32 v109, 0, v217
	v_fmac_f32_e32 v0, v26, v108
	v_fmac_f32_e32 v1, v27, v109
	v_mfma_f32_32x32x16_bf16 v[6:21], v[90:93], v[42:45], v[6:21]
	v_max_f32_e32 v210, 0, v218
	v_max_f32_e32 v211, 0, v219
	v_fmac_f32_e32 v0, v28, v210
	v_fmac_f32_e32 v1, v29, v211
	v_max_f32_e32 v108, 0, v220
	v_max_f32_e32 v109, 0, v221
	v_fmac_f32_e32 v0, v30, v108
	v_fmac_f32_e32 v1, v31, v109
	v_max_f32_e32 v210, 0, v222
	v_max_f32_e32 v211, 0, v223
	v_fmac_f32_e32 v0, v32, v210
	v_fmac_f32_e32 v1, v33, v211
	v_mfma_f32_32x32x16_bf16 v[6:21], v[94:97], v[46:49], v[6:21]
	v_max_f32_e32 v108, 0, v224
	v_max_f32_e32 v109, 0, v225
	v_fmac_f32_e32 v0, v34, v108
	v_fmac_f32_e32 v1, v35, v109
	v_max_f32_e32 v210, 0, v226
	v_max_f32_e32 v211, 0, v227
	v_fmac_f32_e32 v0, v36, v210
	v_fmac_f32_e32 v1, v37, v211
	v_add_f32_e32 v0, v0, v1
	v_ashrrev_i32_e32 v1, 31, v0
	v_mfma_f32_32x32x16_bf16 v[6:21], v[98:101], v[196:199], v[6:21]
	s_waitcnt vmcnt(10)
	ds_read_b128 v[38:41], v5 offset:43264
	ds_read_b128 v[42:45], v52 offset:43264
	ds_read_b128 v[46:49], v55 offset:43264
	ds_read_b128 v[196:199], v56 offset:43264
	v_or_b32_e32 v1, 0x80000000, v1
	s_cmpk_gt_i32 s11, 448
	s_cselect_b64 vcc, -1, 0
	v_xor_b32_e32 v0, v1, v0
	v_cndmask_b32_e32 v190, v123, v0, vcc
	s_nop 3
	s_waitcnt lgkmcnt(3)
	v_mfma_f32_32x32x16_bf16 v[212:227], v[70:73], v[38:41], 0
	v_max_f32_e32 v108, 0, v6
	v_max_f32_e32 v109, 0, v7
	v_mul_f32_e32 v50, v244, v108
	v_mul_f32_e32 v51, v245, v109
	v_max_f32_e32 v210, 0, v8
	v_max_f32_e32 v211, 0, v9
	v_fmac_f32_e32 v50, v246, v210
	v_fmac_f32_e32 v51, v247, v211
	v_max_f32_e32 v108, 0, v10
	v_max_f32_e32 v109, 0, v11
	v_fmac_f32_e32 v50, v248, v108
	v_fmac_f32_e32 v51, v249, v109
	s_waitcnt lgkmcnt(2)
	v_mfma_f32_32x32x16_bf16 v[212:227], v[74:77], v[42:45], v[212:227]
	v_max_f32_e32 v210, 0, v12
	v_max_f32_e32 v211, 0, v13
	v_fmac_f32_e32 v50, v250, v210
	v_fmac_f32_e32 v51, v251, v211
	v_max_f32_e32 v108, 0, v14
	v_max_f32_e32 v109, 0, v15
	v_fmac_f32_e32 v50, v252, v108
	v_fmac_f32_e32 v51, v253, v109
	v_max_f32_e32 v210, 0, v16
	v_max_f32_e32 v211, 0, v17
	v_fmac_f32_e32 v50, v254, v210
	v_fmac_f32_e32 v51, v255, v211
	s_waitcnt lgkmcnt(1)
	v_mfma_f32_32x32x16_bf16 v[212:227], v[78:81], v[46:49], v[212:227]
	v_max_f32_e32 v108, 0, v18
	v_max_f32_e32 v109, 0, v19
	v_fmac_f32_e32 v50, v200, v108
	v_fmac_f32_e32 v51, v201, v109
	v_max_f32_e32 v210, 0, v20
	v_max_f32_e32 v211, 0, v21
	v_fmac_f32_e32 v50, v202, v210
	v_fmac_f32_e32 v51, v203, v211
	v_add_f32_e32 v50, v50, v51
	v_ashrrev_i32_e32 v51, 31, v50
	s_waitcnt lgkmcnt(0)
	v_mfma_f32_32x32x16_bf16 v[212:227], v[82:85], v[196:199], v[212:227]
	v_or_b32_e32 v51, 0x80000000, v51
	s_cmpk_gt_i32 s11, 448
	s_cselect_b64 vcc, -1, 0
	v_xor_b32_e32 v50, v51, v50
	v_cndmask_b32_e32 v50, v123, v50, vcc
	global_store_dword v243, v50, s[8:9]
	s_add_i32 m0, s10, 0
	v_mfma_f32_32x32x16_bf16 v[6:21], v[86:89], v[38:41], 0
	global_load_lds_dwordx4 v102, s[6:7]
	s_add_i32 m0, s10, 1024
	s_nop 0
	global_load_lds_dwordx4 v110, s[6:7]
	s_add_i32 m0, s10, 2048
	s_nop 0
	global_load_lds_dwordx4 v112, s[6:7]
	s_add_i32 m0, s10, 3072
	s_nop 0
	global_load_lds_dwordx4 v193, s[6:7]
	s_add_u32 s6, s6, 0x8000
	s_addc_u32 s7, s7, 0
	v_max_f32_e32 v108, 0, v212
	v_max_f32_e32 v109, 0, v213
	v_mul_f32_e32 v0, v22, v108
	v_mul_f32_e32 v1, v23, v109
	v_max_f32_e32 v210, 0, v214
	v_max_f32_e32 v211, 0, v215
	v_fmac_f32_e32 v0, v24, v210
	v_fmac_f32_e32 v1, v25, v211
	v_max_f32_e32 v108, 0, v216
	v_max_f32_e32 v109, 0, v217
	v_fmac_f32_e32 v0, v26, v108
	v_fmac_f32_e32 v1, v27, v109
	v_mfma_f32_32x32x16_bf16 v[6:21], v[90:93], v[42:45], v[6:21]
	v_max_f32_e32 v210, 0, v218
	v_max_f32_e32 v211, 0, v219
	v_fmac_f32_e32 v0, v28, v210
	v_fmac_f32_e32 v1, v29, v211
	v_max_f32_e32 v108, 0, v220
	v_max_f32_e32 v109, 0, v221
	v_fmac_f32_e32 v0, v30, v108
	v_fmac_f32_e32 v1, v31, v109
	v_max_f32_e32 v210, 0, v222
	v_max_f32_e32 v211, 0, v223
	v_fmac_f32_e32 v0, v32, v210
	v_fmac_f32_e32 v1, v33, v211
	v_mfma_f32_32x32x16_bf16 v[6:21], v[94:97], v[46:49], v[6:21]
	v_max_f32_e32 v108, 0, v224
	v_max_f32_e32 v109, 0, v225
	v_fmac_f32_e32 v0, v34, v108
	v_fmac_f32_e32 v1, v35, v109
	v_max_f32_e32 v210, 0, v226
	v_max_f32_e32 v211, 0, v227
	v_fmac_f32_e32 v0, v36, v210
	v_fmac_f32_e32 v1, v37, v211
	v_add_f32_e32 v0, v0, v1
	v_ashrrev_i32_e32 v1, 31, v0
	v_mfma_f32_32x32x16_bf16 v[6:21], v[98:101], v[196:199], v[6:21]
	s_waitcnt vmcnt(10)
	v_add_u32_e32 v228, 0x10000, v5
	ds_read_b128 v[38:41], v228 offset:10496
	v_add_u32_e32 v228, 0x10000, v52
	ds_read_b128 v[42:45], v228 offset:10496
	v_add_u32_e32 v228, 0x10000, v55
	ds_read_b128 v[46:49], v228 offset:10496
	v_add_u32_e32 v228, 0x10000, v56
	ds_read_b128 v[196:199], v228 offset:10496
	v_or_b32_e32 v1, 0x80000000, v1
	s_cmpk_gt_i32 s11, 456
	s_cselect_b64 vcc, -1, 0
	v_xor_b32_e32 v0, v1, v0
	v_cndmask_b32_e32 v53, v123, v0, vcc
	s_nop 3
	s_waitcnt lgkmcnt(3)
	v_mfma_f32_32x32x16_bf16 v[212:227], v[70:73], v[38:41], 0
	v_max_f32_e32 v108, 0, v6
	v_max_f32_e32 v109, 0, v7
	v_mul_f32_e32 v50, v244, v108
	v_mul_f32_e32 v51, v245, v109
	v_max_f32_e32 v210, 0, v8
	v_max_f32_e32 v211, 0, v9
	v_fmac_f32_e32 v50, v246, v210
	v_fmac_f32_e32 v51, v247, v211
	v_max_f32_e32 v108, 0, v10
	v_max_f32_e32 v109, 0, v11
	v_fmac_f32_e32 v50, v248, v108
	v_fmac_f32_e32 v51, v249, v109
	s_waitcnt lgkmcnt(2)
	v_mfma_f32_32x32x16_bf16 v[212:227], v[74:77], v[42:45], v[212:227]
	v_max_f32_e32 v210, 0, v12
	v_max_f32_e32 v211, 0, v13
	v_fmac_f32_e32 v50, v250, v210
	v_fmac_f32_e32 v51, v251, v211
	v_max_f32_e32 v108, 0, v14
	v_max_f32_e32 v109, 0, v15
	v_fmac_f32_e32 v50, v252, v108
	v_fmac_f32_e32 v51, v253, v109
	v_max_f32_e32 v210, 0, v16
	v_max_f32_e32 v211, 0, v17
	v_fmac_f32_e32 v50, v254, v210
	v_fmac_f32_e32 v51, v255, v211
	s_waitcnt lgkmcnt(1)
	v_mfma_f32_32x32x16_bf16 v[212:227], v[78:81], v[46:49], v[212:227]
	v_max_f32_e32 v108, 0, v18
	v_max_f32_e32 v109, 0, v19
	v_fmac_f32_e32 v50, v200, v108
	v_fmac_f32_e32 v51, v201, v109
	v_max_f32_e32 v210, 0, v20
	v_max_f32_e32 v211, 0, v21
	v_fmac_f32_e32 v50, v202, v210
	v_fmac_f32_e32 v51, v203, v211
	v_add_f32_e32 v50, v50, v51
	v_ashrrev_i32_e32 v51, 31, v50
	s_waitcnt lgkmcnt(0)
	v_mfma_f32_32x32x16_bf16 v[212:227], v[82:85], v[196:199], v[212:227]
	v_or_b32_e32 v51, 0x80000000, v51
	s_cmpk_gt_i32 s11, 456
	s_cselect_b64 vcc, -1, 0
	v_xor_b32_e32 v50, v51, v50
	v_cndmask_b32_e32 v50, v123, v50, vcc
	global_store_dword v243, v50, s[8:9] offset:2048
	s_add_u32 s8, s8, 0x1000
	s_addc_u32 s9, s9, 0
	s_add_i32 m0, s10, 32768
	v_mfma_f32_32x32x16_bf16 v[6:21], v[86:89], v[38:41], 0
	global_load_lds_dwordx4 v102, s[6:7]
	s_add_i32 m0, s10, 33792
	s_nop 0
	global_load_lds_dwordx4 v110, s[6:7]
	s_add_i32 m0, s10, 34816
	s_nop 0
	global_load_lds_dwordx4 v112, s[6:7]
	s_add_i32 m0, s10, 35840
	s_nop 0
	global_load_lds_dwordx4 v193, s[6:7]
	s_add_u32 s6, s6, 0x8000
	s_addc_u32 s7, s7, 0
	v_max_f32_e32 v108, 0, v212
	v_max_f32_e32 v109, 0, v213
	v_mul_f32_e32 v0, v22, v108
	v_mul_f32_e32 v1, v23, v109
	v_max_f32_e32 v210, 0, v214
	v_max_f32_e32 v211, 0, v215
	v_fmac_f32_e32 v0, v24, v210
	v_fmac_f32_e32 v1, v25, v211
	v_max_f32_e32 v108, 0, v216
	v_max_f32_e32 v109, 0, v217
	v_fmac_f32_e32 v0, v26, v108
	v_fmac_f32_e32 v1, v27, v109
	v_mfma_f32_32x32x16_bf16 v[6:21], v[90:93], v[42:45], v[6:21]
	v_max_f32_e32 v210, 0, v218
	v_max_f32_e32 v211, 0, v219
	v_fmac_f32_e32 v0, v28, v210
	v_fmac_f32_e32 v1, v29, v211
	v_max_f32_e32 v108, 0, v220
	v_max_f32_e32 v109, 0, v221
	v_fmac_f32_e32 v0, v30, v108
	v_fmac_f32_e32 v1, v31, v109
	v_max_f32_e32 v210, 0, v222
	v_max_f32_e32 v211, 0, v223
	v_fmac_f32_e32 v0, v32, v210
	v_fmac_f32_e32 v1, v33, v211
	v_mfma_f32_32x32x16_bf16 v[6:21], v[94:97], v[46:49], v[6:21]
	v_max_f32_e32 v108, 0, v224
	v_max_f32_e32 v109, 0, v225
	v_fmac_f32_e32 v0, v34, v108
	v_fmac_f32_e32 v1, v35, v109
	v_max_f32_e32 v210, 0, v226
	v_max_f32_e32 v211, 0, v227
	v_fmac_f32_e32 v0, v36, v210
	v_fmac_f32_e32 v1, v37, v211
	v_add_f32_e32 v0, v0, v1
	v_ashrrev_i32_e32 v1, 31, v0
	v_mfma_f32_32x32x16_bf16 v[6:21], v[98:101], v[196:199], v[6:21]
	s_waitcnt vmcnt(10)
	v_add_u32_e32 v228, 0x10000, v5
	ds_read_b128 v[38:41], v228 offset:43264
	v_add_u32_e32 v228, 0x10000, v52
	ds_read_b128 v[42:45], v228 offset:43264
	v_add_u32_e32 v228, 0x10000, v55
	ds_read_b128 v[46:49], v228 offset:43264
	v_add_u32_e32 v228, 0x10000, v56
	ds_read_b128 v[196:199], v228 offset:43264
	v_or_b32_e32 v1, 0x80000000, v1
	s_cmpk_gt_i32 s11, 464
	s_cselect_b64 vcc, -1, 0
	v_xor_b32_e32 v0, v1, v0
	v_cndmask_b32_e32 v192, v123, v0, vcc
	s_nop 3
	s_waitcnt lgkmcnt(3)
	v_mfma_f32_32x32x16_bf16 v[212:227], v[70:73], v[38:41], 0
	v_max_f32_e32 v108, 0, v6
	v_max_f32_e32 v109, 0, v7
	v_mul_f32_e32 v50, v244, v108
	v_mul_f32_e32 v51, v245, v109
	v_max_f32_e32 v210, 0, v8
	v_max_f32_e32 v211, 0, v9
	v_fmac_f32_e32 v50, v246, v210
	v_fmac_f32_e32 v51, v247, v211
	v_max_f32_e32 v108, 0, v10
	v_max_f32_e32 v109, 0, v11
	v_fmac_f32_e32 v50, v248, v108
	v_fmac_f32_e32 v51, v249, v109
	s_waitcnt lgkmcnt(2)
	v_mfma_f32_32x32x16_bf16 v[212:227], v[74:77], v[42:45], v[212:227]
	v_max_f32_e32 v210, 0, v12
	v_max_f32_e32 v211, 0, v13
	v_fmac_f32_e32 v50, v250, v210
	v_fmac_f32_e32 v51, v251, v211
	v_max_f32_e32 v108, 0, v14
	v_max_f32_e32 v109, 0, v15
	v_fmac_f32_e32 v50, v252, v108
	v_fmac_f32_e32 v51, v253, v109
	v_max_f32_e32 v210, 0, v16
	v_max_f32_e32 v211, 0, v17
	v_fmac_f32_e32 v50, v254, v210
	v_fmac_f32_e32 v51, v255, v211
	s_waitcnt lgkmcnt(1)
	v_mfma_f32_32x32x16_bf16 v[212:227], v[78:81], v[46:49], v[212:227]
	v_max_f32_e32 v108, 0, v18
	v_max_f32_e32 v109, 0, v19
	v_fmac_f32_e32 v50, v200, v108
	v_fmac_f32_e32 v51, v201, v109
	v_max_f32_e32 v210, 0, v20
	v_max_f32_e32 v211, 0, v21
	v_fmac_f32_e32 v50, v202, v210
	v_fmac_f32_e32 v51, v203, v211
	v_add_f32_e32 v50, v50, v51
	v_ashrrev_i32_e32 v51, 31, v50
	s_waitcnt lgkmcnt(0)
	v_mfma_f32_32x32x16_bf16 v[212:227], v[82:85], v[196:199], v[212:227]
	v_or_b32_e32 v51, 0x80000000, v51
	s_cmpk_gt_i32 s11, 464
	s_cselect_b64 vcc, -1, 0
	v_xor_b32_e32 v50, v51, v50
	v_cndmask_b32_e32 v50, v123, v50, vcc
	global_store_dword v243, v50, s[8:9]
	s_add_i32 m0, s10, 65536
	v_mfma_f32_32x32x16_bf16 v[6:21], v[86:89], v[38:41], 0
	global_load_lds_dwordx4 v102, s[6:7]
	s_add_i32 m0, s10, 66560
	s_nop 0
	global_load_lds_dwordx4 v110, s[6:7]
	s_add_i32 m0, s10, 67584
	s_nop 0
	global_load_lds_dwordx4 v112, s[6:7]
	s_add_i32 m0, s10, 68608
	s_nop 0
	global_load_lds_dwordx4 v193, s[6:7]
	s_add_u32 s6, s6, 0x8000
	s_addc_u32 s7, s7, 0
	v_max_f32_e32 v108, 0, v212
	v_max_f32_e32 v109, 0, v213
	v_mul_f32_e32 v0, v22, v108
	v_mul_f32_e32 v1, v23, v109
	v_max_f32_e32 v210, 0, v214
	v_max_f32_e32 v211, 0, v215
	v_fmac_f32_e32 v0, v24, v210
	v_fmac_f32_e32 v1, v25, v211
	v_max_f32_e32 v108, 0, v216
	v_max_f32_e32 v109, 0, v217
	v_fmac_f32_e32 v0, v26, v108
	v_fmac_f32_e32 v1, v27, v109
	v_mfma_f32_32x32x16_bf16 v[6:21], v[90:93], v[42:45], v[6:21]
	v_max_f32_e32 v210, 0, v218
	v_max_f32_e32 v211, 0, v219
	v_fmac_f32_e32 v0, v28, v210
	v_fmac_f32_e32 v1, v29, v211
	v_max_f32_e32 v108, 0, v220
	v_max_f32_e32 v109, 0, v221
	v_fmac_f32_e32 v0, v30, v108
	v_fmac_f32_e32 v1, v31, v109
	v_max_f32_e32 v210, 0, v222
	v_max_f32_e32 v211, 0, v223
	v_fmac_f32_e32 v0, v32, v210
	v_fmac_f32_e32 v1, v33, v211
	v_mfma_f32_32x32x16_bf16 v[6:21], v[94:97], v[46:49], v[6:21]
	v_max_f32_e32 v108, 0, v224
	v_max_f32_e32 v109, 0, v225
	v_fmac_f32_e32 v0, v34, v108
	v_fmac_f32_e32 v1, v35, v109
	v_max_f32_e32 v210, 0, v226
	v_max_f32_e32 v211, 0, v227
	v_fmac_f32_e32 v0, v36, v210
	v_fmac_f32_e32 v1, v37, v211
	v_add_f32_e32 v0, v0, v1
	v_ashrrev_i32_e32 v1, 31, v0
	v_mfma_f32_32x32x16_bf16 v[6:21], v[98:101], v[196:199], v[6:21]
	s_waitcnt vmcnt(10)
	ds_read_b128 v[38:41], v5 offset:10496
	ds_read_b128 v[42:45], v52 offset:10496
	ds_read_b128 v[46:49], v55 offset:10496
	ds_read_b128 v[196:199], v56 offset:10496
	v_or_b32_e32 v1, 0x80000000, v1
	s_cmpk_gt_i32 s11, 472
	s_cselect_b64 vcc, -1, 0
	v_xor_b32_e32 v0, v1, v0
	v_cndmask_b32_e32 v191, v123, v0, vcc
	s_nop 3
	s_waitcnt lgkmcnt(3)
	v_mfma_f32_32x32x16_bf16 v[212:227], v[70:73], v[38:41], 0
	v_max_f32_e32 v108, 0, v6
	v_max_f32_e32 v109, 0, v7
	v_mul_f32_e32 v50, v244, v108
	v_mul_f32_e32 v51, v245, v109
	v_max_f32_e32 v210, 0, v8
	v_max_f32_e32 v211, 0, v9
	v_fmac_f32_e32 v50, v246, v210
	v_fmac_f32_e32 v51, v247, v211
	v_max_f32_e32 v108, 0, v10
	v_max_f32_e32 v109, 0, v11
	v_fmac_f32_e32 v50, v248, v108
	v_fmac_f32_e32 v51, v249, v109
	s_waitcnt lgkmcnt(2)
	v_mfma_f32_32x32x16_bf16 v[212:227], v[74:77], v[42:45], v[212:227]
	v_max_f32_e32 v210, 0, v12
	v_max_f32_e32 v211, 0, v13
	v_fmac_f32_e32 v50, v250, v210
	v_fmac_f32_e32 v51, v251, v211
	v_max_f32_e32 v108, 0, v14
	v_max_f32_e32 v109, 0, v15
	v_fmac_f32_e32 v50, v252, v108
	v_fmac_f32_e32 v51, v253, v109
	v_max_f32_e32 v210, 0, v16
	v_max_f32_e32 v211, 0, v17
	v_fmac_f32_e32 v50, v254, v210
	v_fmac_f32_e32 v51, v255, v211
	s_waitcnt lgkmcnt(1)
	v_mfma_f32_32x32x16_bf16 v[212:227], v[78:81], v[46:49], v[212:227]
	v_max_f32_e32 v108, 0, v18
	v_max_f32_e32 v109, 0, v19
	v_fmac_f32_e32 v50, v200, v108
	v_fmac_f32_e32 v51, v201, v109
	v_max_f32_e32 v210, 0, v20
	v_max_f32_e32 v211, 0, v21
	v_fmac_f32_e32 v50, v202, v210
	v_fmac_f32_e32 v51, v203, v211
	v_add_f32_e32 v50, v50, v51
	v_ashrrev_i32_e32 v51, 31, v50
	s_waitcnt lgkmcnt(0)
	v_mfma_f32_32x32x16_bf16 v[212:227], v[82:85], v[196:199], v[212:227]
	v_or_b32_e32 v51, 0x80000000, v51
	s_cmpk_gt_i32 s11, 472
	s_cselect_b64 vcc, -1, 0
	v_xor_b32_e32 v50, v51, v50
	v_cndmask_b32_e32 v50, v123, v50, vcc
	global_store_dword v243, v50, s[8:9] offset:2048
	s_add_u32 s8, s8, 0x1000
	s_addc_u32 s9, s9, 0
	s_add_i32 m0, s10, 98304
	v_mfma_f32_32x32x16_bf16 v[6:21], v[86:89], v[38:41], 0
	global_load_lds_dwordx4 v102, s[6:7]
	s_add_i32 m0, s10, 99328
	s_nop 0
	global_load_lds_dwordx4 v110, s[6:7]
	s_add_i32 m0, s10, 100352
	s_nop 0
	global_load_lds_dwordx4 v112, s[6:7]
	s_add_i32 m0, s10, 101376
	s_nop 0
	global_load_lds_dwordx4 v193, s[6:7]
	s_add_u32 s6, s6, 0x8000
	s_addc_u32 s7, s7, 0
	v_max_f32_e32 v108, 0, v212
	v_max_f32_e32 v109, 0, v213
	v_mul_f32_e32 v0, v22, v108
	v_mul_f32_e32 v1, v23, v109
	v_max_f32_e32 v210, 0, v214
	v_max_f32_e32 v211, 0, v215
	v_fmac_f32_e32 v0, v24, v210
	v_fmac_f32_e32 v1, v25, v211
	v_max_f32_e32 v108, 0, v216
	v_max_f32_e32 v109, 0, v217
	v_fmac_f32_e32 v0, v26, v108
	v_fmac_f32_e32 v1, v27, v109
	v_mfma_f32_32x32x16_bf16 v[6:21], v[90:93], v[42:45], v[6:21]
	v_max_f32_e32 v210, 0, v218
	v_max_f32_e32 v211, 0, v219
	v_fmac_f32_e32 v0, v28, v210
	v_fmac_f32_e32 v1, v29, v211
	v_max_f32_e32 v108, 0, v220
	v_max_f32_e32 v109, 0, v221
	v_fmac_f32_e32 v0, v30, v108
	v_fmac_f32_e32 v1, v31, v109
	v_max_f32_e32 v210, 0, v222
	v_max_f32_e32 v211, 0, v223
	v_fmac_f32_e32 v0, v32, v210
	v_fmac_f32_e32 v1, v33, v211
	v_mfma_f32_32x32x16_bf16 v[6:21], v[94:97], v[46:49], v[6:21]
	v_max_f32_e32 v108, 0, v224
	v_max_f32_e32 v109, 0, v225
	v_fmac_f32_e32 v0, v34, v108
	v_fmac_f32_e32 v1, v35, v109
	v_max_f32_e32 v210, 0, v226
	v_max_f32_e32 v211, 0, v227
	v_fmac_f32_e32 v0, v36, v210
	v_fmac_f32_e32 v1, v37, v211
	v_add_f32_e32 v0, v0, v1
	v_ashrrev_i32_e32 v1, 31, v0
	v_mfma_f32_32x32x16_bf16 v[6:21], v[98:101], v[196:199], v[6:21]
	s_waitcnt vmcnt(10)
	ds_read_b128 v[38:41], v5 offset:43264
	ds_read_b128 v[42:45], v52 offset:43264
	ds_read_b128 v[46:49], v55 offset:43264
	ds_read_b128 v[196:199], v56 offset:43264
	v_or_b32_e32 v1, 0x80000000, v1
	s_cmpk_gt_i32 s11, 480
	s_cselect_b64 vcc, -1, 0
	v_xor_b32_e32 v0, v1, v0
	v_cndmask_b32_e32 v3, v123, v0, vcc
	s_nop 3
	s_waitcnt lgkmcnt(3)
	v_mfma_f32_32x32x16_bf16 v[212:227], v[70:73], v[38:41], 0
	v_max_f32_e32 v108, 0, v6
	v_max_f32_e32 v109, 0, v7
	v_mul_f32_e32 v50, v244, v108
	v_mul_f32_e32 v51, v245, v109
	v_max_f32_e32 v210, 0, v8
	v_max_f32_e32 v211, 0, v9
	v_fmac_f32_e32 v50, v246, v210
	v_fmac_f32_e32 v51, v247, v211
	v_max_f32_e32 v108, 0, v10
	v_max_f32_e32 v109, 0, v11
	v_fmac_f32_e32 v50, v248, v108
	v_fmac_f32_e32 v51, v249, v109
	s_waitcnt lgkmcnt(2)
	v_mfma_f32_32x32x16_bf16 v[212:227], v[74:77], v[42:45], v[212:227]
	v_max_f32_e32 v210, 0, v12
	v_max_f32_e32 v211, 0, v13
	v_fmac_f32_e32 v50, v250, v210
	v_fmac_f32_e32 v51, v251, v211
	v_max_f32_e32 v108, 0, v14
	v_max_f32_e32 v109, 0, v15
	v_fmac_f32_e32 v50, v252, v108
	v_fmac_f32_e32 v51, v253, v109
	v_max_f32_e32 v210, 0, v16
	v_max_f32_e32 v211, 0, v17
	v_fmac_f32_e32 v50, v254, v210
	v_fmac_f32_e32 v51, v255, v211
	s_waitcnt lgkmcnt(1)
	v_mfma_f32_32x32x16_bf16 v[212:227], v[78:81], v[46:49], v[212:227]
	v_max_f32_e32 v108, 0, v18
	v_max_f32_e32 v109, 0, v19
	v_fmac_f32_e32 v50, v200, v108
	v_fmac_f32_e32 v51, v201, v109
	v_max_f32_e32 v210, 0, v20
	v_max_f32_e32 v211, 0, v21
	v_fmac_f32_e32 v50, v202, v210
	v_fmac_f32_e32 v51, v203, v211
	v_add_f32_e32 v50, v50, v51
	v_ashrrev_i32_e32 v51, 31, v50
	s_waitcnt lgkmcnt(0)
	v_mfma_f32_32x32x16_bf16 v[212:227], v[82:85], v[196:199], v[212:227]
	v_or_b32_e32 v51, 0x80000000, v51
	s_cmpk_gt_i32 s11, 480
	s_cselect_b64 vcc, -1, 0
	v_xor_b32_e32 v50, v51, v50
	v_cndmask_b32_e32 v50, v123, v50, vcc
	global_store_dword v243, v50, s[8:9]
	s_add_i32 m0, s10, 0
	v_mfma_f32_32x32x16_bf16 v[6:21], v[86:89], v[38:41], 0
	global_load_lds_dwordx4 v102, s[6:7]
	s_add_i32 m0, s10, 1024
	s_nop 0
	global_load_lds_dwordx4 v110, s[6:7]
	s_add_i32 m0, s10, 2048
	s_nop 0
	global_load_lds_dwordx4 v112, s[6:7]
	s_add_i32 m0, s10, 3072
	s_nop 0
	global_load_lds_dwordx4 v193, s[6:7]
	s_add_u32 s6, s6, 0x8000
	s_addc_u32 s7, s7, 0
	v_max_f32_e32 v108, 0, v212
	v_max_f32_e32 v109, 0, v213
	v_mul_f32_e32 v0, v22, v108
	v_mul_f32_e32 v1, v23, v109
	v_max_f32_e32 v210, 0, v214
	v_max_f32_e32 v211, 0, v215
	v_fmac_f32_e32 v0, v24, v210
	v_fmac_f32_e32 v1, v25, v211
	v_max_f32_e32 v108, 0, v216
	v_max_f32_e32 v109, 0, v217
	v_fmac_f32_e32 v0, v26, v108
	v_fmac_f32_e32 v1, v27, v109
	v_mfma_f32_32x32x16_bf16 v[6:21], v[90:93], v[42:45], v[6:21]
	v_max_f32_e32 v210, 0, v218
	v_max_f32_e32 v211, 0, v219
	v_fmac_f32_e32 v0, v28, v210
	v_fmac_f32_e32 v1, v29, v211
	v_max_f32_e32 v108, 0, v220
	v_max_f32_e32 v109, 0, v221
	v_fmac_f32_e32 v0, v30, v108
	v_fmac_f32_e32 v1, v31, v109
	v_max_f32_e32 v210, 0, v222
	v_max_f32_e32 v211, 0, v223
	v_fmac_f32_e32 v0, v32, v210
	v_fmac_f32_e32 v1, v33, v211
	v_mfma_f32_32x32x16_bf16 v[6:21], v[94:97], v[46:49], v[6:21]
	v_max_f32_e32 v108, 0, v224
	v_max_f32_e32 v109, 0, v225
	v_fmac_f32_e32 v0, v34, v108
	v_fmac_f32_e32 v1, v35, v109
	v_max_f32_e32 v210, 0, v226
	v_max_f32_e32 v211, 0, v227
	v_fmac_f32_e32 v0, v36, v210
	v_fmac_f32_e32 v1, v37, v211
	v_add_f32_e32 v0, v0, v1
	v_ashrrev_i32_e32 v1, 31, v0
	v_mfma_f32_32x32x16_bf16 v[6:21], v[98:101], v[196:199], v[6:21]
	s_waitcnt vmcnt(10)
	v_add_u32_e32 v228, 0x10000, v5
	ds_read_b128 v[38:41], v228 offset:10496
	v_add_u32_e32 v228, 0x10000, v52
	ds_read_b128 v[42:45], v228 offset:10496
	v_add_u32_e32 v228, 0x10000, v55
	ds_read_b128 v[46:49], v228 offset:10496
	v_add_u32_e32 v228, 0x10000, v56
	ds_read_b128 v[196:199], v228 offset:10496
	v_or_b32_e32 v1, 0x80000000, v1
	s_cmpk_gt_i32 s11, 488
	s_cselect_b64 vcc, -1, 0
	v_xor_b32_e32 v0, v1, v0
	v_cndmask_b32_e32 v2, v123, v0, vcc
	s_nop 3
	s_waitcnt lgkmcnt(3)
	v_mfma_f32_32x32x16_bf16 v[212:227], v[70:73], v[38:41], 0
	v_max_f32_e32 v108, 0, v6
	v_max_f32_e32 v109, 0, v7
	v_mul_f32_e32 v50, v244, v108
	v_mul_f32_e32 v51, v245, v109
	v_max_f32_e32 v210, 0, v8
	v_max_f32_e32 v211, 0, v9
	v_fmac_f32_e32 v50, v246, v210
	v_fmac_f32_e32 v51, v247, v211
	v_max_f32_e32 v108, 0, v10
	v_max_f32_e32 v109, 0, v11
	v_fmac_f32_e32 v50, v248, v108
	v_fmac_f32_e32 v51, v249, v109
	s_waitcnt lgkmcnt(2)
	v_mfma_f32_32x32x16_bf16 v[212:227], v[74:77], v[42:45], v[212:227]
	v_max_f32_e32 v210, 0, v12
	v_max_f32_e32 v211, 0, v13
	v_fmac_f32_e32 v50, v250, v210
	v_fmac_f32_e32 v51, v251, v211
	v_max_f32_e32 v108, 0, v14
	v_max_f32_e32 v109, 0, v15
	v_fmac_f32_e32 v50, v252, v108
	v_fmac_f32_e32 v51, v253, v109
	v_max_f32_e32 v210, 0, v16
	v_max_f32_e32 v211, 0, v17
	v_fmac_f32_e32 v50, v254, v210
	v_fmac_f32_e32 v51, v255, v211
	s_waitcnt lgkmcnt(1)
	v_mfma_f32_32x32x16_bf16 v[212:227], v[78:81], v[46:49], v[212:227]
	v_max_f32_e32 v108, 0, v18
	v_max_f32_e32 v109, 0, v19
	v_fmac_f32_e32 v50, v200, v108
	v_fmac_f32_e32 v51, v201, v109
	v_max_f32_e32 v210, 0, v20
	v_max_f32_e32 v211, 0, v21
	v_fmac_f32_e32 v50, v202, v210
	v_fmac_f32_e32 v51, v203, v211
	v_add_f32_e32 v50, v50, v51
	v_ashrrev_i32_e32 v51, 31, v50
	s_waitcnt lgkmcnt(0)
	v_mfma_f32_32x32x16_bf16 v[212:227], v[82:85], v[196:199], v[212:227]
	v_or_b32_e32 v51, 0x80000000, v51
	s_cmpk_gt_i32 s11, 488
	s_cselect_b64 vcc, -1, 0
	v_xor_b32_e32 v50, v51, v50
	v_cndmask_b32_e32 v50, v123, v50, vcc
	global_store_dword v243, v50, s[8:9] offset:2048
	s_add_u32 s8, s8, 0x1000
	s_addc_u32 s9, s9, 0
	s_add_i32 m0, s10, 32768
	v_mfma_f32_32x32x16_bf16 v[6:21], v[86:89], v[38:41], 0
	global_load_lds_dwordx4 v102, s[6:7]
	s_add_i32 m0, s10, 33792
	s_nop 0
	global_load_lds_dwordx4 v110, s[6:7]
	s_add_i32 m0, s10, 34816
	s_nop 0
	global_load_lds_dwordx4 v112, s[6:7]
	s_add_i32 m0, s10, 35840
	s_nop 0
	global_load_lds_dwordx4 v193, s[6:7]
	s_add_u32 s6, s6, 0x8000
	s_addc_u32 s7, s7, 0
	v_max_f32_e32 v108, 0, v212
	v_max_f32_e32 v109, 0, v213
	v_mul_f32_e32 v0, v22, v108
	v_mul_f32_e32 v1, v23, v109
	v_max_f32_e32 v210, 0, v214
	v_max_f32_e32 v211, 0, v215
	v_fmac_f32_e32 v0, v24, v210
	v_fmac_f32_e32 v1, v25, v211
	v_max_f32_e32 v108, 0, v216
	v_max_f32_e32 v109, 0, v217
	v_fmac_f32_e32 v0, v26, v108
	v_fmac_f32_e32 v1, v27, v109
	v_mfma_f32_32x32x16_bf16 v[6:21], v[90:93], v[42:45], v[6:21]
	v_max_f32_e32 v210, 0, v218
	v_max_f32_e32 v211, 0, v219
	v_fmac_f32_e32 v0, v28, v210
	v_fmac_f32_e32 v1, v29, v211
	v_max_f32_e32 v108, 0, v220
	v_max_f32_e32 v109, 0, v221
	v_fmac_f32_e32 v0, v30, v108
	v_fmac_f32_e32 v1, v31, v109
	v_max_f32_e32 v210, 0, v222
	v_max_f32_e32 v211, 0, v223
	v_fmac_f32_e32 v0, v32, v210
	v_fmac_f32_e32 v1, v33, v211
	v_mfma_f32_32x32x16_bf16 v[6:21], v[94:97], v[46:49], v[6:21]
	v_max_f32_e32 v108, 0, v224
	v_max_f32_e32 v109, 0, v225
	v_fmac_f32_e32 v0, v34, v108
	v_fmac_f32_e32 v1, v35, v109
	v_max_f32_e32 v210, 0, v226
	v_max_f32_e32 v211, 0, v227
	v_fmac_f32_e32 v0, v36, v210
	v_fmac_f32_e32 v1, v37, v211
	v_add_f32_e32 v0, v0, v1
	v_ashrrev_i32_e32 v1, 31, v0
	v_mfma_f32_32x32x16_bf16 v[6:21], v[98:101], v[196:199], v[6:21]
	s_waitcnt vmcnt(10)
	v_add_u32_e32 v228, 0x10000, v5
	ds_read_b128 v[38:41], v228 offset:43264
	v_add_u32_e32 v228, 0x10000, v52
	ds_read_b128 v[42:45], v228 offset:43264
	v_add_u32_e32 v228, 0x10000, v55
	ds_read_b128 v[46:49], v228 offset:43264
	v_add_u32_e32 v228, 0x10000, v56
	ds_read_b128 v[196:199], v228 offset:43264
	v_or_b32_e32 v1, 0x80000000, v1
	s_cmpk_gt_i32 s11, 496
	s_cselect_b64 vcc, -1, 0
	v_xor_b32_e32 v0, v1, v0
	v_cndmask_b32_e32 v4, v123, v0, vcc
	s_nop 3
	s_waitcnt lgkmcnt(3)
	v_mfma_f32_32x32x16_bf16 v[212:227], v[70:73], v[38:41], 0
	v_max_f32_e32 v108, 0, v6
	v_max_f32_e32 v109, 0, v7
	v_mul_f32_e32 v50, v244, v108
	v_mul_f32_e32 v51, v245, v109
	v_max_f32_e32 v210, 0, v8
	v_max_f32_e32 v211, 0, v9
	v_fmac_f32_e32 v50, v246, v210
	v_fmac_f32_e32 v51, v247, v211
	v_max_f32_e32 v108, 0, v10
	v_max_f32_e32 v109, 0, v11
	v_fmac_f32_e32 v50, v248, v108
	v_fmac_f32_e32 v51, v249, v109
	s_waitcnt lgkmcnt(2)
	v_mfma_f32_32x32x16_bf16 v[212:227], v[74:77], v[42:45], v[212:227]
	v_max_f32_e32 v210, 0, v12
	v_max_f32_e32 v211, 0, v13
	v_fmac_f32_e32 v50, v250, v210
	v_fmac_f32_e32 v51, v251, v211
	v_max_f32_e32 v108, 0, v14
	v_max_f32_e32 v109, 0, v15
	v_fmac_f32_e32 v50, v252, v108
	v_fmac_f32_e32 v51, v253, v109
	v_max_f32_e32 v210, 0, v16
	v_max_f32_e32 v211, 0, v17
	v_fmac_f32_e32 v50, v254, v210
	v_fmac_f32_e32 v51, v255, v211
	s_waitcnt lgkmcnt(1)
	v_mfma_f32_32x32x16_bf16 v[212:227], v[78:81], v[46:49], v[212:227]
	v_max_f32_e32 v108, 0, v18
	v_max_f32_e32 v109, 0, v19
	v_fmac_f32_e32 v50, v200, v108
	v_fmac_f32_e32 v51, v201, v109
	v_max_f32_e32 v210, 0, v20
	v_max_f32_e32 v211, 0, v21
	v_fmac_f32_e32 v50, v202, v210
	v_fmac_f32_e32 v51, v203, v211
	v_add_f32_e32 v50, v50, v51
	v_ashrrev_i32_e32 v51, 31, v50
	s_waitcnt lgkmcnt(0)
	v_mfma_f32_32x32x16_bf16 v[212:227], v[82:85], v[196:199], v[212:227]
	v_or_b32_e32 v51, 0x80000000, v51
	s_cmpk_gt_i32 s11, 496
	s_cselect_b64 vcc, -1, 0
	v_xor_b32_e32 v50, v51, v50
	v_cndmask_b32_e32 v50, v123, v50, vcc
	global_store_dword v243, v50, s[8:9]
	s_add_i32 m0, s10, 65536
	v_mfma_f32_32x32x16_bf16 v[6:21], v[86:89], v[38:41], 0
	global_load_lds_dwordx4 v102, s[6:7]
	s_add_i32 m0, s10, 66560
	s_nop 0
	global_load_lds_dwordx4 v110, s[6:7]
	s_add_i32 m0, s10, 67584
	s_nop 0
	global_load_lds_dwordx4 v112, s[6:7]
	s_add_i32 m0, s10, 68608
	s_nop 0
	global_load_lds_dwordx4 v193, s[6:7]
	s_add_u32 s6, s6, 0x8000
	s_addc_u32 s7, s7, 0
	v_max_f32_e32 v108, 0, v212
	v_max_f32_e32 v109, 0, v213
	v_mul_f32_e32 v0, v22, v108
	v_mul_f32_e32 v1, v23, v109
	v_max_f32_e32 v210, 0, v214
	v_max_f32_e32 v211, 0, v215
	v_fmac_f32_e32 v0, v24, v210
	v_fmac_f32_e32 v1, v25, v211
	v_max_f32_e32 v108, 0, v216
	v_max_f32_e32 v109, 0, v217
	v_fmac_f32_e32 v0, v26, v108
	v_fmac_f32_e32 v1, v27, v109
	v_mfma_f32_32x32x16_bf16 v[6:21], v[90:93], v[42:45], v[6:21]
	v_max_f32_e32 v210, 0, v218
	v_max_f32_e32 v211, 0, v219
	v_fmac_f32_e32 v0, v28, v210
	v_fmac_f32_e32 v1, v29, v211
	v_max_f32_e32 v108, 0, v220
	v_max_f32_e32 v109, 0, v221
	v_fmac_f32_e32 v0, v30, v108
	v_fmac_f32_e32 v1, v31, v109
	v_max_f32_e32 v210, 0, v222
	v_max_f32_e32 v211, 0, v223
	v_fmac_f32_e32 v0, v32, v210
	v_fmac_f32_e32 v1, v33, v211
	v_mfma_f32_32x32x16_bf16 v[6:21], v[94:97], v[46:49], v[6:21]
	v_max_f32_e32 v108, 0, v224
	v_max_f32_e32 v109, 0, v225
	v_fmac_f32_e32 v0, v34, v108
	v_fmac_f32_e32 v1, v35, v109
	v_max_f32_e32 v210, 0, v226
	v_max_f32_e32 v211, 0, v227
	v_fmac_f32_e32 v0, v36, v210
	v_fmac_f32_e32 v1, v37, v211
	v_add_f32_e32 v0, v0, v1
	v_ashrrev_i32_e32 v1, 31, v0
	v_mfma_f32_32x32x16_bf16 v[6:21], v[98:101], v[196:199], v[6:21]
	s_waitcnt vmcnt(10)
	ds_read_b128 v[38:41], v5 offset:10496
	ds_read_b128 v[42:45], v52 offset:10496
	ds_read_b128 v[46:49], v55 offset:10496
	ds_read_b128 v[196:199], v56 offset:10496
	v_or_b32_e32 v1, 0x80000000, v1
	s_cmpk_gt_i32 s11, 504
	s_cselect_b64 vcc, -1, 0
	v_xor_b32_e32 v0, v1, v0
	v_cndmask_b32_e32 v185, v123, v0, vcc
	s_nop 3
	v_max_f32_e32 v108, 0, v6
	v_max_f32_e32 v109, 0, v7
	v_mul_f32_e32 v50, v244, v108
	v_mul_f32_e32 v51, v245, v109
	v_max_f32_e32 v210, 0, v8
	v_max_f32_e32 v211, 0, v9
	v_fmac_f32_e32 v50, v246, v210
	v_fmac_f32_e32 v51, v247, v211
	v_max_f32_e32 v108, 0, v10
	v_max_f32_e32 v109, 0, v11
	v_fmac_f32_e32 v50, v248, v108
	v_fmac_f32_e32 v51, v249, v109
	v_max_f32_e32 v210, 0, v12
	v_max_f32_e32 v211, 0, v13
	v_fmac_f32_e32 v50, v250, v210
	v_fmac_f32_e32 v51, v251, v211
	v_max_f32_e32 v108, 0, v14
	v_max_f32_e32 v109, 0, v15
	v_fmac_f32_e32 v50, v252, v108
	v_fmac_f32_e32 v51, v253, v109
	v_max_f32_e32 v210, 0, v16
	v_max_f32_e32 v211, 0, v17
	v_fmac_f32_e32 v50, v254, v210
	v_fmac_f32_e32 v51, v255, v211
	v_max_f32_e32 v108, 0, v18
	v_max_f32_e32 v109, 0, v19
	v_fmac_f32_e32 v50, v200, v108
	v_fmac_f32_e32 v51, v201, v109
	v_max_f32_e32 v210, 0, v20
	v_max_f32_e32 v211, 0, v21
	v_fmac_f32_e32 v50, v202, v210
	v_fmac_f32_e32 v51, v203, v211
	v_add_f32_e32 v50, v50, v51
	v_ashrrev_i32_e32 v51, 31, v50
	v_or_b32_e32 v51, 0x80000000, v51
	s_cmpk_gt_i32 s11, 504
	s_cselect_b64 vcc, -1, 0
	v_xor_b32_e32 v50, v51, v50
	v_cndmask_b32_e32 v50, v123, v50, vcc
	global_store_dword v243, v50, s[8:9] offset:2048
	s_add_u32 s8, s8, 0x1000
	s_addc_u32 s9, s9, 0
	s_branch .Lix_done
